# merge-tile gated epilogues: gate/y vectors of 4 rounds fetched together (were 1 round per full vmcnt drain)
# speedup vs baseline: 1.0381x; 1.0231x over previous
; #define STG_A(P, ptr) do { const bf16_t* _g = (ptr); \
;     __builtin_amdgcn_global_load_lds((const unsigned*)(_g + oa0), (__attribute__((address_space(3))) unsigned*)((P) + tb0), 16, 0, 0); \
;     __builtin_amdgcn_global_load_lds((const unsigned*)(_g + (size_t)64 * lda + oa0), (__attribute__((address_space(3))) unsigned*)((P) + tb1), 16, 0, 0); } while (0)
; #define STG_B(P, ptr) do { const bf16_t* _g = (ptr); \
;     __builtin_amdgcn_global_load_lds((const unsigned*)(_g + ob0), (__attribute__((address_space(3))) unsigned*)((P) + tb0), 16, 0, 0); \
;     __builtin_amdgcn_global_load_lds((const unsigned*)(_g + (size_t)64 * ldb + ob0), (__attribute__((address_space(3))) unsigned*)((P) + tb1), 16, 0, 0); } while (0)
; #define LDA(dst, b, h) _Pragma("unroll") for (int m = 0; m < 4; ++m) _Pragma("unroll") for (int k = 0; k < 2; ++k) \
;     dst[m][k] = *reinterpret_cast<const bf16x8*>(SA(b, h) + lds_byte(wr * 64 + m * 16 + fr, k * 32 + fq * 8))
; #define LDB(dst, b, h) _Pragma("unroll") for (int n = 0; n < 2; ++n) _Pragma("unroll") for (int k = 0; k < 2; ++k) \
;     dst[n][k] = *reinterpret_cast<const bf16x8*>(SB(b, h) + lds_byte(wc * 32 + n * 16 + fr, k * 32 + fq * 8))
; #define MMA(ai, bj, At_, Bt_) do { __builtin_amdgcn_s_setprio(1); \
;     _Pragma("unroll") for (int m = 0; m < 4; ++m) _Pragma("unroll") for (int n = 0; n < 2; ++n) _Pragma("unroll") for (int k = 0; k < 2; ++k) \
;       acc[ai][bj][m][n] = __builtin_amdgcn_mfma_f32_16x16x32_bf16(Bt_[n][k], At_[m][k], acc[ai][bj][m][n], 0, 0, 0); \
;     __builtin_amdgcn_s_setprio(0); } while (0)
; #define WAIT_L(n) asm volatile("s_waitcnt lgkmcnt(" #n ")" ::: "memory")
; #define BAR __builtin_amdgcn_s_barrier()
; #define SCHED __builtin_amdgcn_sched_barrier(0)
; template <int lda, int ldb, int K, class Gen, class Epi>
; DI void gemm_stream(Gen gen, Epi epi) {
;     ...
;       LDB(B0, 0, 0); SCHED; LDA(At, 0, 0); STG_A(SA(1, 1), a1 + (size_t)128 * lda);
;       WAIT_L(8); BAR; WAIT_L(0); MMA(0, 0, At, B0); BAR; SCHED;
;       LDB(B1, 0, 1); STG_B(SB(0, 0), b2);
;       BAR; WAIT_L(0); MMA(0, 1, At, B1); BAR;
;       LDA(At, 0, 1); STG_A(SA(0, 0), a2);
;       BAR; WAIT_L(0); MMA(1, 0, At, B0); BAR; SCHED;
;       STG_B(SB(0, 1), b2 + (size_t)128 * ldb);
.LBB0_1267:
	s_add_i32 s52, s52, 2
	ds_read_b128 v[130:133], v160
	ds_read_b128 v[140:143], v160 offset:1024
	ds_read_b128 v[168:171], v160 offset:2048
	ds_read_b128 v[172:175], v160 offset:3072
	s_add_u32 s26, s4, 0x100
	s_addc_u32 s27, s5, 0
	s_cmp_gt_u32 s52, 5
	s_cselect_b64 s[0:1], -1, 0
	s_and_b64 vcc, s[0:1], exec
	s_cselect_b32 s0, s33, s27
	s_cselect_b32 s1, s46, s26
	v_mov_b32_e32 v188, s1
	v_mov_b32_e32 v189, s0
	v_add_u32_e32 v0, 0xc000, v146
	v_lshl_add_u64 v[224:225], s[4:5], 0, v[138:139]
	v_readfirstlane_b32 s0, v0
	v_add_u32_e32 v0, 0xe000, v146
	v_lshl_add_u64 v[226:227], v[224:225], 0, s[10:11]
	s_mov_b32 m0, s0
	v_readfirstlane_b32 s0, v0
	ds_read_b128 v[176:179], v161
	ds_read_b128 v[180:183], v161 offset:1024
	ds_read_b128 v[184:187], v162
	ds_read_b128 v[204:207], v162 offset:1024
	ds_read_b128 v[208:211], v163
	ds_read_b128 v[212:215], v163 offset:1024
	ds_read_b128 v[216:219], v164
	ds_read_b128 v[220:223], v164 offset:1024
	global_load_lds_dwordx4 v[226:227], off
	v_lshl_add_u64 v[224:225], v[224:225], 0, s[28:29]
	s_mov_b32 m0, s0
	s_nop 0
	global_load_lds_dwordx4 v[224:225], off
	s_waitcnt lgkmcnt(8)
	s_barrier
	s_waitcnt lgkmcnt(0)
	s_setprio 1
	s_waitcnt lgkmcnt(0)
	v_mfma_f32_16x16x32_bf16 v[126:129], v[130:133], v[176:179], v[126:129]
	v_mfma_f32_16x16x32_bf16 v[122:125], v[168:171], v[176:179], v[122:125]
	v_mfma_f32_16x16x32_bf16 v[110:113], v[130:133], v[184:187], v[110:113]
	v_mfma_f32_16x16x32_bf16 v[106:109], v[168:171], v[184:187], v[106:109]
	v_mfma_f32_16x16x32_bf16 v[94:97], v[130:133], v[208:211], v[94:97]
	v_mfma_f32_16x16x32_bf16 v[90:93], v[168:171], v[208:211], v[90:93]
	v_mfma_f32_16x16x32_bf16 v[78:81], v[130:133], v[216:219], v[78:81]
	v_mfma_f32_16x16x32_bf16 v[74:77], v[168:171], v[216:219], v[74:77]
	v_mfma_f32_16x16x32_bf16 v[126:129], v[140:143], v[180:183], v[126:129]
	v_mfma_f32_16x16x32_bf16 v[122:125], v[172:175], v[180:183], v[122:125]
	v_mfma_f32_16x16x32_bf16 v[110:113], v[140:143], v[204:207], v[110:113]
	v_mfma_f32_16x16x32_bf16 v[106:109], v[172:175], v[204:207], v[106:109]
	v_mfma_f32_16x16x32_bf16 v[94:97], v[140:143], v[212:215], v[94:97]
	v_mfma_f32_16x16x32_bf16 v[90:93], v[172:175], v[212:215], v[90:93]
	v_mfma_f32_16x16x32_bf16 v[78:81], v[140:143], v[220:223], v[78:81]
	v_mfma_f32_16x16x32_bf16 v[74:77], v[172:175], v[220:223], v[74:77]
	s_setprio 0
	s_barrier
	s_cselect_b32 s0, s18, s51
	s_cselect_b32 s1, s19, s47
	v_mov_b32_e32 v244, s1
	v_mov_b32_e32 v245, s0
	v_readfirstlane_b32 s0, v145
	v_add_u32_e32 v0, 0x2000, v145
	v_lshl_add_u64 v[244:245], v[136:137], 1, v[244:245]
	s_mov_b32 m0, s0
	v_readfirstlane_b32 s0, v0
	ds_read_b128 v[224:227], v165
	ds_read_b128 v[228:231], v165 offset:1024
	ds_read_b128 v[232:235], v165 offset:2048
	ds_read_b128 v[240:243], v165 offset:3072
	global_load_lds_dwordx4 v[244:245], off
	v_lshl_add_u64 v[246:247], v[244:245], 0, s[14:15]
	s_mov_b32 m0, s0
	s_nop 0
	global_load_lds_dwordx4 v[246:247], off
	s_barrier
	s_waitcnt lgkmcnt(0)
	s_setprio 1
	s_waitcnt lgkmcnt(0)
	v_mfma_f32_16x16x32_bf16 v[118:121], v[224:227], v[176:179], v[118:121]
	v_mfma_f32_16x16x32_bf16 v[114:117], v[232:235], v[176:179], v[114:117]
	v_mfma_f32_16x16x32_bf16 v[102:105], v[224:227], v[184:187], v[102:105]
	v_mfma_f32_16x16x32_bf16 v[98:101], v[232:235], v[184:187], v[98:101]
	v_mfma_f32_16x16x32_bf16 v[86:89], v[224:227], v[208:211], v[86:89]
	v_mfma_f32_16x16x32_bf16 v[82:85], v[232:235], v[208:211], v[82:85]
	v_mfma_f32_16x16x32_bf16 v[70:73], v[224:227], v[216:219], v[70:73]
	v_mfma_f32_16x16x32_bf16 v[66:69], v[232:235], v[216:219], v[66:69]
	v_mfma_f32_16x16x32_bf16 v[118:121], v[228:231], v[180:183], v[118:121]
	v_mfma_f32_16x16x32_bf16 v[114:117], v[240:243], v[180:183], v[114:117]
	v_mfma_f32_16x16x32_bf16 v[102:105], v[228:231], v[204:207], v[102:105]
	v_mfma_f32_16x16x32_bf16 v[98:101], v[240:243], v[204:207], v[98:101]
	v_mfma_f32_16x16x32_bf16 v[86:89], v[228:231], v[212:215], v[86:89]
	v_mfma_f32_16x16x32_bf16 v[82:85], v[240:243], v[212:215], v[82:85]
	v_mfma_f32_16x16x32_bf16 v[70:73], v[228:231], v[220:223], v[70:73]
	v_mfma_f32_16x16x32_bf16 v[66:69], v[240:243], v[220:223], v[66:69]
	s_setprio 0
	v_readfirstlane_b32 s0, v146
	v_lshl_add_u64 v[188:189], v[134:135], 1, v[188:189]
	s_mov_b32 m0, s0
	v_readfirstlane_b32 s0, v147
	s_barrier
	ds_read_b128 v[176:179], v161 offset:16384
	ds_read_b128 v[180:183], v161 offset:17408
	ds_read_b128 v[184:187], v162 offset:16384
	ds_read_b128 v[204:207], v162 offset:17408
	ds_read_b128 v[208:211], v163 offset:16384
	ds_read_b128 v[212:215], v163 offset:17408
	ds_read_b128 v[216:219], v164 offset:16384
	ds_read_b128 v[220:223], v164 offset:17408
	global_load_lds_dwordx4 v[188:189], off
	v_lshl_add_u64 v[246:247], v[188:189], 0, s[14:15]
	s_mov_b32 m0, s0
	s_nop 0
	global_load_lds_dwordx4 v[246:247], off
	s_barrier
	s_waitcnt lgkmcnt(0)
	s_setprio 1
	s_waitcnt lgkmcnt(0)
	v_mfma_f32_16x16x32_bf16 v[62:65], v[130:133], v[176:179], v[62:65]
	v_mfma_f32_16x16x32_bf16 v[58:61], v[168:171], v[176:179], v[58:61]
	v_mfma_f32_16x16x32_bf16 v[46:49], v[130:133], v[184:187], v[46:49]
	v_mfma_f32_16x16x32_bf16 v[42:45], v[168:171], v[184:187], v[42:45]
	v_mfma_f32_16x16x32_bf16 v[30:33], v[130:133], v[208:211], v[30:33]
	v_mfma_f32_16x16x32_bf16 v[26:29], v[168:171], v[208:211], v[26:29]
	v_mfma_f32_16x16x32_bf16 v[14:17], v[130:133], v[216:219], v[14:17]
	v_mfma_f32_16x16x32_bf16 v[10:13], v[168:171], v[216:219], v[10:13]
	v_mfma_f32_16x16x32_bf16 v[62:65], v[140:143], v[180:183], v[62:65]
	v_mfma_f32_16x16x32_bf16 v[58:61], v[172:175], v[180:183], v[58:61]
	v_mfma_f32_16x16x32_bf16 v[46:49], v[140:143], v[204:207], v[46:49]
	v_mfma_f32_16x16x32_bf16 v[42:45], v[172:175], v[204:207], v[42:45]
	v_mfma_f32_16x16x32_bf16 v[30:33], v[140:143], v[212:215], v[30:33]
	v_mfma_f32_16x16x32_bf16 v[26:29], v[172:175], v[212:215], v[26:29]
	v_mfma_f32_16x16x32_bf16 v[14:17], v[140:143], v[220:223], v[14:17]
	v_mfma_f32_16x16x32_bf16 v[10:13], v[172:175], v[220:223], v[10:13]
	s_setprio 0
	s_barrier
; #define STG_A(P, ptr) do { const bf16_t* _g = (ptr); \
;     __builtin_amdgcn_global_load_lds((const unsigned*)(_g + oa0), (__attribute__((address_space(3))) unsigned*)((P) + tb0), 16, 0, 0); \
;     __builtin_amdgcn_global_load_lds((const unsigned*)(_g + (size_t)64 * lda + oa0), (__attribute__((address_space(3))) unsigned*)((P) + tb1), 16, 0, 0); } while (0)
; #define STG_B(P, ptr) do { const bf16_t* _g = (ptr); \
;     __builtin_amdgcn_global_load_lds((const unsigned*)(_g + ob0), (__attribute__((address_space(3))) unsigned*)((P) + tb0), 16, 0, 0); \
;     __builtin_amdgcn_global_load_lds((const unsigned*)(_g + (size_t)64 * ldb + ob0), (__attribute__((address_space(3))) unsigned*)((P) + tb1), 16, 0, 0); } while (0)
; #define LDA(dst, b, h) _Pragma("unroll") for (int m = 0; m < 4; ++m) _Pragma("unroll") for (int k = 0; k < 2; ++k) \
;     dst[m][k] = *reinterpret_cast<const bf16x8*>(SA(b, h) + lds_byte(wr * 64 + m * 16 + fr, k * 32 + fq * 8))
; #define LDB(dst, b, h) _Pragma("unroll") for (int n = 0; n < 2; ++n) _Pragma("unroll") for (int k = 0; k < 2; ++k) \
;     dst[n][k] = *reinterpret_cast<const bf16x8*>(SB(b, h) + lds_byte(wc * 32 + n * 16 + fr, k * 32 + fq * 8))
; #define MMA(ai, bj, At_, Bt_) do { __builtin_amdgcn_s_setprio(1); \
;     _Pragma("unroll") for (int m = 0; m < 4; ++m) _Pragma("unroll") for (int n = 0; n < 2; ++n) _Pragma("unroll") for (int k = 0; k < 2; ++k) \
;       acc[ai][bj][m][n] = __builtin_amdgcn_mfma_f32_16x16x32_bf16(Bt_[n][k], At_[m][k], acc[ai][bj][m][n], 0, 0, 0); \
;     __builtin_amdgcn_s_setprio(0); } while (0)
; #define WAIT_V(n) asm volatile("s_waitcnt vmcnt(" #n ")" ::: "memory")
; #define WAIT_L(n) asm volatile("s_waitcnt lgkmcnt(" #n ")" ::: "memory")
; #define BAR __builtin_amdgcn_s_barrier()
; #define SCHED __builtin_amdgcn_sched_barrier(0)
; template <int lda, int ldb, int K, class Gen, class Epi>
; DI void gemm_stream(Gen gen, Epi epi) {
;     ...
;       STG_B(SB(0, 1), b2 + (size_t)128 * ldb);
;       WAIT_V(6); BAR; MMA(1, 1, At, B1); BAR;
;       LDB(B0, 1, 0); SCHED; LDA(At, 1, 0); STG_A(SA(0, 1), a2 + (size_t)128 * lda);
;       WAIT_L(8); BAR; WAIT_L(0); MMA(0, 0, At, B0); BAR; SCHED;
;       LDB(B1, 1, 1); STG_B(SB(1, 0), b2 + 64);
;       BAR; WAIT_L(0); MMA(0, 1, At, B1); BAR;
;       LDA(At, 1, 1); STG_A(SA(1, 0), a2 + 64);
	v_readfirstlane_b32 s0, v150
	v_add_u32_e32 v0, 0x2000, v150
	v_lshl_add_u64 v[130:131], v[244:245], 0, s[24:25]
	s_mov_b32 m0, s0
	v_readfirstlane_b32 s0, v0
	global_load_lds_dwordx4 v[130:131], off
	v_lshl_add_u64 v[130:131], v[244:245], 0, s[16:17]
	s_mov_b32 m0, s0
	s_nop 0
	global_load_lds_dwordx4 v[130:131], off
	s_waitcnt vmcnt(6)
	s_barrier
	s_setprio 1
	v_mfma_f32_16x16x32_bf16 v[54:57], v[224:227], v[176:179], v[54:57]
	v_mfma_f32_16x16x32_bf16 v[50:53], v[232:235], v[176:179], v[50:53]
	v_mfma_f32_16x16x32_bf16 v[38:41], v[224:227], v[184:187], v[38:41]
	v_mfma_f32_16x16x32_bf16 v[34:37], v[232:235], v[184:187], v[34:37]
	v_mfma_f32_16x16x32_bf16 v[22:25], v[224:227], v[208:211], v[22:25]
	v_mfma_f32_16x16x32_bf16 v[18:21], v[232:235], v[208:211], v[18:21]
	v_mfma_f32_16x16x32_bf16 v[6:9], v[224:227], v[216:219], v[6:9]
	v_mfma_f32_16x16x32_bf16 v[2:5], v[232:235], v[216:219], v[2:5]
	v_mfma_f32_16x16x32_bf16 v[54:57], v[228:231], v[180:183], v[54:57]
	v_mfma_f32_16x16x32_bf16 v[50:53], v[240:243], v[180:183], v[50:53]
	v_mfma_f32_16x16x32_bf16 v[38:41], v[228:231], v[204:207], v[38:41]
	v_mfma_f32_16x16x32_bf16 v[34:37], v[240:243], v[204:207], v[34:37]
	v_mfma_f32_16x16x32_bf16 v[22:25], v[228:231], v[212:215], v[22:25]
	v_mfma_f32_16x16x32_bf16 v[18:21], v[240:243], v[212:215], v[18:21]
	v_mfma_f32_16x16x32_bf16 v[6:9], v[228:231], v[220:223], v[6:9]
	v_mfma_f32_16x16x32_bf16 v[2:5], v[240:243], v[220:223], v[2:5]
	s_setprio 0
	s_barrier
	ds_read_b128 v[130:133], v166
	ds_read_b128 v[140:143], v166 offset:1024
	ds_read_b128 v[168:171], v166 offset:2048
	ds_read_b128 v[172:175], v166 offset:3072
	v_readfirstlane_b32 s0, v152
	v_lshl_add_u64 v[224:225], v[188:189], 0, s[24:25]
	s_mov_b32 m0, s0
	v_readfirstlane_b32 s0, v153
	ds_read_b128 v[176:179], v161 offset:32768
	ds_read_b128 v[180:183], v161 offset:33792
	ds_read_b128 v[184:187], v162 offset:32768
	ds_read_b128 v[204:207], v162 offset:33792
	ds_read_b128 v[208:211], v163 offset:32768
	ds_read_b128 v[212:215], v163 offset:33792
	ds_read_b128 v[216:219], v164 offset:32768
	ds_read_b128 v[220:223], v164 offset:33792
	global_load_lds_dwordx4 v[224:225], off
	v_lshl_add_u64 v[224:225], v[188:189], 0, s[16:17]
	s_mov_b32 m0, s0
	s_nop 0
	global_load_lds_dwordx4 v[224:225], off
	s_waitcnt lgkmcnt(8)
	s_barrier
	s_waitcnt lgkmcnt(0)
	s_setprio 1
	s_waitcnt lgkmcnt(0)
	v_mfma_f32_16x16x32_bf16 v[126:129], v[130:133], v[176:179], v[126:129]
	v_mfma_f32_16x16x32_bf16 v[122:125], v[168:171], v[176:179], v[122:125]
	v_mfma_f32_16x16x32_bf16 v[110:113], v[130:133], v[184:187], v[110:113]
	v_mfma_f32_16x16x32_bf16 v[106:109], v[168:171], v[184:187], v[106:109]
	v_mfma_f32_16x16x32_bf16 v[94:97], v[130:133], v[208:211], v[94:97]
	v_mfma_f32_16x16x32_bf16 v[90:93], v[168:171], v[208:211], v[90:93]
	v_mfma_f32_16x16x32_bf16 v[78:81], v[130:133], v[216:219], v[78:81]
	v_mfma_f32_16x16x32_bf16 v[74:77], v[168:171], v[216:219], v[74:77]
	v_mfma_f32_16x16x32_bf16 v[126:129], v[140:143], v[180:183], v[126:129]
	v_mfma_f32_16x16x32_bf16 v[122:125], v[172:175], v[180:183], v[122:125]
	v_mfma_f32_16x16x32_bf16 v[110:113], v[140:143], v[204:207], v[110:113]
	v_mfma_f32_16x16x32_bf16 v[106:109], v[172:175], v[204:207], v[106:109]
	v_mfma_f32_16x16x32_bf16 v[94:97], v[140:143], v[212:215], v[94:97]
	v_mfma_f32_16x16x32_bf16 v[90:93], v[172:175], v[212:215], v[90:93]
	v_mfma_f32_16x16x32_bf16 v[78:81], v[140:143], v[220:223], v[78:81]
	v_mfma_f32_16x16x32_bf16 v[74:77], v[172:175], v[220:223], v[74:77]
	s_setprio 0
	s_barrier
	v_readfirstlane_b32 s0, v154
	v_lshl_add_u64 v[246:247], v[244:245], 0, s[34:35]
	s_mov_b32 m0, s0
	v_readfirstlane_b32 s0, v155
	ds_read_b128 v[224:227], v167
	ds_read_b128 v[228:231], v167 offset:1024
	ds_read_b128 v[232:235], v167 offset:2048
	ds_read_b128 v[240:243], v167 offset:3072
	global_load_lds_dwordx4 v[246:247], off
	v_lshl_add_u64 v[246:247], v[244:245], 0, s[6:7]
	s_mov_b32 m0, s0
	s_nop 0
	global_load_lds_dwordx4 v[246:247], off
	s_barrier
	s_waitcnt lgkmcnt(0)
	s_setprio 1
	s_waitcnt lgkmcnt(0)
	v_mfma_f32_16x16x32_bf16 v[118:121], v[224:227], v[176:179], v[118:121]
	v_mfma_f32_16x16x32_bf16 v[114:117], v[232:235], v[176:179], v[114:117]
	v_mfma_f32_16x16x32_bf16 v[102:105], v[224:227], v[184:187], v[102:105]
	v_mfma_f32_16x16x32_bf16 v[98:101], v[232:235], v[184:187], v[98:101]
	v_mfma_f32_16x16x32_bf16 v[86:89], v[224:227], v[208:211], v[86:89]
	v_mfma_f32_16x16x32_bf16 v[82:85], v[232:235], v[208:211], v[82:85]
	v_mfma_f32_16x16x32_bf16 v[70:73], v[224:227], v[216:219], v[70:73]
	v_mfma_f32_16x16x32_bf16 v[66:69], v[232:235], v[216:219], v[66:69]
	v_mfma_f32_16x16x32_bf16 v[118:121], v[228:231], v[180:183], v[118:121]
	v_mfma_f32_16x16x32_bf16 v[114:117], v[240:243], v[180:183], v[114:117]
	v_mfma_f32_16x16x32_bf16 v[102:105], v[228:231], v[204:207], v[102:105]
	v_mfma_f32_16x16x32_bf16 v[98:101], v[240:243], v[204:207], v[98:101]
	v_mfma_f32_16x16x32_bf16 v[86:89], v[228:231], v[212:215], v[86:89]
	v_mfma_f32_16x16x32_bf16 v[82:85], v[240:243], v[212:215], v[82:85]
	v_mfma_f32_16x16x32_bf16 v[70:73], v[228:231], v[220:223], v[70:73]
	v_mfma_f32_16x16x32_bf16 v[66:69], v[240:243], v[220:223], v[66:69]
	s_setprio 0
	v_readfirstlane_b32 s0, v156
	v_lshl_add_u64 v[246:247], v[188:189], 0, s[34:35]
	s_mov_b32 m0, s0
	v_readfirstlane_b32 s0, v157
	s_barrier
	ds_read_b128 v[176:179], v161 offset:49152
	ds_read_b128 v[180:183], v161 offset:50176
	ds_read_b128 v[184:187], v162 offset:49152
	ds_read_b128 v[204:207], v162 offset:50176
	ds_read_b128 v[208:211], v163 offset:49152
	ds_read_b128 v[212:215], v163 offset:50176
	ds_read_b128 v[216:219], v164 offset:49152
	ds_read_b128 v[220:223], v164 offset:50176
	global_load_lds_dwordx4 v[246:247], off
	v_lshl_add_u64 v[188:189], v[188:189], 0, s[6:7]
	s_mov_b32 m0, s0
	s_nop 0
	global_load_lds_dwordx4 v[188:189], off
	s_barrier
; DI unsigned cvt_pk_bf16(float lo, float hi) { f32x2_t v = {lo, hi}; bf16x2_t b = __builtin_convertvector(v, bf16x2_t); return __builtin_bit_cast(unsigned, b); }
; DI float bflo(unsigned u) { return __uint_as_float(u << 16); }
; DI float bfhi(unsigned u) { return __uint_as_float(u & 0xffff0000u); }
; #define STG_B(P, ptr) do { const bf16_t* _g = (ptr); \
;     __builtin_amdgcn_global_load_lds((const unsigned*)(_g + ob0), (__attribute__((address_space(3))) unsigned*)((P) + tb0), 16, 0, 0); \
;     __builtin_amdgcn_global_load_lds((const unsigned*)(_g + (size_t)64 * ldb + ob0), (__attribute__((address_space(3))) unsigned*)((P) + tb1), 16, 0, 0); } while (0)
; #define MMA(ai, bj, At_, Bt_) do { __builtin_amdgcn_s_setprio(1); \
;     _Pragma("unroll") for (int m = 0; m < 4; ++m) _Pragma("unroll") for (int n = 0; n < 2; ++n) _Pragma("unroll") for (int k = 0; k < 2; ++k) \
;       acc[ai][bj][m][n] = __builtin_amdgcn_mfma_f32_16x16x32_bf16(Bt_[n][k], At_[m][k], acc[ai][bj][m][n], 0, 0, 0); \
;     __builtin_amdgcn_s_setprio(0); } while (0)
; #define WAIT_V(n) asm volatile("s_waitcnt vmcnt(" #n ")" ::: "memory")
; #define WAIT_L(n) asm volatile("s_waitcnt lgkmcnt(" #n ")" ::: "memory")
; #define BAR __builtin_amdgcn_s_barrier()
; #define SCHED __builtin_amdgcn_sched_barrier(0)
; template <int lda, int ldb, int K, class Gen, class Epi>
; DI void gemm_stream(Gen gen, Epi epi) {
;     ...
;       BAR; WAIT_L(0); MMA(1, 0, At, B0); BAR; SCHED;
;       STG_B(SB(1, 1), b2 + (size_t)128 * ldb + 64);
;       WAIT_V(6); BAR; MMA(1, 1, At, B1); BAR;
; template <bool ADD>
; DI void gated_tile(acc_t& acc, bf16_t* Y, int ldy, const bf16_t* Gt, int ldg) {
;   epi_foreach(acc, [&](int r, int c, f32x4& v0, f32x4& v1) {
;     const u32x4 g = *(const u32x4*)(Gt + (size_t)r * ldg + c);
;     float o[8];
;     o[0] = bflo(g[0]) * v0[0]; o[1] = bfhi(g[0]) * v0[1]; o[2] = bflo(g[1]) * v0[2]; o[3] = bfhi(g[1]) * v0[3];
;     o[4] = bflo(g[2]) * v1[0]; o[5] = bfhi(g[2]) * v1[1]; o[6] = bflo(g[3]) * v1[2]; o[7] = bfhi(g[3]) * v1[3];
;     bf16_t* py = Y + (size_t)r * ldy + c;
;     if (ADD) {
;       const u32x4 y0 = *(const u32x4*)py;
; #pragma unroll
;       for (int j = 0; j < 4; ++j) { o[2 * j] += bflo(y0[j]); o[2 * j + 1] += bfhi(y0[j]); }
;     }
;     u32x4 pk;
; #pragma unroll
;     for (int j = 0; j < 4; ++j) pk[j] = cvt_pk_bf16(o[2 * j], o[2 * j + 1]);
;     *(u32x4*)py = pk;
;   });
	s_waitcnt lgkmcnt(0)
	s_setprio 1
	s_waitcnt lgkmcnt(0)
	v_mfma_f32_16x16x32_bf16 v[62:65], v[130:133], v[176:179], v[62:65]
	v_mfma_f32_16x16x32_bf16 v[58:61], v[168:171], v[176:179], v[58:61]
	v_mfma_f32_16x16x32_bf16 v[46:49], v[130:133], v[184:187], v[46:49]
	v_mfma_f32_16x16x32_bf16 v[42:45], v[168:171], v[184:187], v[42:45]
	v_mfma_f32_16x16x32_bf16 v[30:33], v[130:133], v[208:211], v[30:33]
	v_mfma_f32_16x16x32_bf16 v[26:29], v[168:171], v[208:211], v[26:29]
	v_mfma_f32_16x16x32_bf16 v[14:17], v[130:133], v[216:219], v[14:17]
	v_mfma_f32_16x16x32_bf16 v[10:13], v[168:171], v[216:219], v[10:13]
	v_mfma_f32_16x16x32_bf16 v[62:65], v[140:143], v[180:183], v[62:65]
	v_mfma_f32_16x16x32_bf16 v[58:61], v[172:175], v[180:183], v[58:61]
	v_mfma_f32_16x16x32_bf16 v[46:49], v[140:143], v[204:207], v[46:49]
	v_mfma_f32_16x16x32_bf16 v[42:45], v[172:175], v[204:207], v[42:45]
	v_mfma_f32_16x16x32_bf16 v[30:33], v[140:143], v[212:215], v[30:33]
	v_mfma_f32_16x16x32_bf16 v[26:29], v[172:175], v[212:215], v[26:29]
	v_mfma_f32_16x16x32_bf16 v[14:17], v[140:143], v[220:223], v[14:17]
	v_mfma_f32_16x16x32_bf16 v[10:13], v[172:175], v[220:223], v[10:13]
	s_setprio 0
	s_barrier
	v_readfirstlane_b32 s0, v158
	v_lshl_add_u64 v[130:131], v[244:245], 0, s[10:11]
	s_mov_b32 m0, s0
	v_readfirstlane_b32 s0, v159
	global_load_lds_dwordx4 v[130:131], off
	v_lshl_add_u64 v[130:131], v[244:245], 0, s[28:29]
	s_mov_b32 m0, s0
	s_nop 0
	global_load_lds_dwordx4 v[130:131], off
	s_waitcnt vmcnt(6)
	s_barrier
	s_setprio 1
	v_mfma_f32_16x16x32_bf16 v[54:57], v[224:227], v[176:179], v[54:57]
	v_mfma_f32_16x16x32_bf16 v[50:53], v[232:235], v[176:179], v[50:53]
	v_mfma_f32_16x16x32_bf16 v[38:41], v[224:227], v[184:187], v[38:41]
	v_mfma_f32_16x16x32_bf16 v[34:37], v[232:235], v[184:187], v[34:37]
	v_mfma_f32_16x16x32_bf16 v[22:25], v[224:227], v[208:211], v[22:25]
	v_mfma_f32_16x16x32_bf16 v[18:21], v[232:235], v[208:211], v[18:21]
	v_mfma_f32_16x16x32_bf16 v[6:9], v[224:227], v[216:219], v[6:9]
	v_mfma_f32_16x16x32_bf16 v[2:5], v[232:235], v[216:219], v[2:5]
	v_mfma_f32_16x16x32_bf16 v[54:57], v[228:231], v[180:183], v[54:57]
	v_mfma_f32_16x16x32_bf16 v[50:53], v[240:243], v[180:183], v[50:53]
	v_mfma_f32_16x16x32_bf16 v[38:41], v[228:231], v[204:207], v[38:41]
	v_mfma_f32_16x16x32_bf16 v[34:37], v[240:243], v[204:207], v[34:37]
	v_mfma_f32_16x16x32_bf16 v[22:25], v[228:231], v[212:215], v[22:25]
	v_mfma_f32_16x16x32_bf16 v[18:21], v[240:243], v[212:215], v[18:21]
	v_mfma_f32_16x16x32_bf16 v[6:9], v[228:231], v[220:223], v[6:9]
	v_mfma_f32_16x16x32_bf16 v[2:5], v[240:243], v[220:223], v[2:5]
	s_setprio 0
	s_add_u32 s47, s47, 0x100
	s_addc_u32 s51, s51, 0
	s_mov_b64 s[4:5], s[26:27]
	s_barrier
	s_cbranch_vccz .LBB0_1267
	s_andn2_b64 vcc, exec, s[44:45]
	s_mov_b64 s[4:5], -1
	s_cbranch_vccnz .LBB0_1270
	v_mov_b32_e32 v0, v149
	s_movk_i32 s0, 0xffc0
	v_and_b32_e32 v130, 15, v0
	v_ashrrev_i32_e32 v131, 2, v0
	v_and_or_b32 v140, v131, s0, v130
	v_ashrrev_i32_e32 v141, 31, v140
	v_readlane_b32 s18, v253, 34
	v_readlane_b32 s26, v253, 35
	v_readlane_b32 s4, v251, 33
	v_mad_i64_i32 v[130:131], s[0:1], s18, v140, 0
	v_readlane_b32 s27, v253, 36
	v_lshlrev_b64 v[168:169], 11, v[140:141]
	v_readlane_b32 s5, v251, 34
	v_lshl_add_u64 v[130:131], v[130:131], 1, s[26:27]
	v_and_b32_e32 v0, 0xf0, v0
	v_lshl_add_u64 v[168:169], s[4:5], 0, v[168:169]
	v_lshl_add_u64 v[142:143], v[130:131], 0, v[0:1]
	v_lshl_add_u64 v[172:173], v[168:169], 0, v[0:1]
	global_load_dwordx4 v[130:133], v[142:143], off offset:2048
	global_load_dwordx4 v[168:171], v[172:173], off
	s_lshl_b32 s100, s18, 5
	v_add_co_u32_e32 v178, vcc, s100, v142
	s_nop 1
	v_addc_co_u32_e32 v179, vcc, 0, v143, vcc
	v_add_co_u32_e32 v180, vcc, 0x8000, v172
	s_nop 1
	v_addc_co_u32_e32 v181, vcc, 0, v173, vcc
	global_load_dwordx4 v[204:207], v[142:143], off offset:2304
	global_load_dwordx4 v[208:211], v[172:173], off offset:256
	global_load_dwordx4 v[212:215], v[178:179], off offset:2048
	global_load_dwordx4 v[216:219], v[180:181], off
	global_load_dwordx4 v[220:223], v[178:179], off offset:2304
	global_load_dwordx4 v[224:227], v[180:181], off offset:256
	s_waitcnt vmcnt(0)
	v_lshlrev_b32_e32 v174, 16, v130
	v_and_b32_e32 v175, 0xffff0000, v130
	v_lshlrev_b32_e32 v176, 16, v168
	v_and_b32_e32 v177, 0xffff0000, v168
	v_lshlrev_b32_e32 v130, 16, v131
	v_and_b32_e32 v131, 0xffff0000, v131
	v_lshlrev_b32_e32 v168, 16, v169
	v_and_b32_e32 v169, 0xffff0000, v169
	v_pk_fma_f32 v[174:175], v[126:127], v[174:175], v[176:177]
	v_pk_fma_f32 v[168:169], v[128:129], v[130:131], v[168:169]
	v_lshlrev_b32_e32 v130, 16, v132
	v_and_b32_e32 v131, 0xffff0000, v132
	v_lshlrev_b32_e32 v176, 16, v170
	v_and_b32_e32 v177, 0xffff0000, v170
	v_pk_fma_f32 v[176:177], v[122:123], v[130:131], v[176:177]
	v_lshlrev_b32_e32 v130, 16, v133
	v_and_b32_e32 v131, 0xffff0000, v133
	v_lshlrev_b32_e32 v132, 16, v171
	v_and_b32_e32 v133, 0xffff0000, v171
	v_pk_fma_f32 v[170:171], v[124:125], v[130:131], v[132:133]
	v_cvt_pk_bf16_f32 v130, v174, v175
	v_cvt_pk_bf16_f32 v131, v168, v169
	v_cvt_pk_bf16_f32 v132, v176, v177
	v_cvt_pk_bf16_f32 v133, v170, v171
	global_store_dwordx4 v[172:173], v[130:133], off
	s_nop 1
	v_mov_b32_e32 v130, v204
	v_mov_b32_e32 v131, v205
	v_mov_b32_e32 v132, v206
	v_mov_b32_e32 v133, v207
	s_nop 0
	s_nop 1
	v_mov_b32_e32 v168, v208
	v_mov_b32_e32 v169, v209
	v_mov_b32_e32 v170, v210
	v_mov_b32_e32 v171, v211
	v_lshlrev_b32_e32 v142, 16, v130
	v_and_b32_e32 v143, 0xffff0000, v130
	v_lshlrev_b32_e32 v174, 16, v168
	v_and_b32_e32 v175, 0xffff0000, v168
	v_lshlrev_b32_e32 v130, 16, v131
	v_and_b32_e32 v131, 0xffff0000, v131
	v_lshlrev_b32_e32 v168, 16, v169
; DI unsigned cvt_pk_bf16(float lo, float hi) { f32x2_t v = {lo, hi}; bf16x2_t b = __builtin_convertvector(v, bf16x2_t); return __builtin_bit_cast(unsigned, b); }
; DI float bflo(unsigned u) { return __uint_as_float(u << 16); }
; DI float bfhi(unsigned u) { return __uint_as_float(u & 0xffff0000u); }
; template <bool ADD>
; DI void gated_tile(acc_t& acc, bf16_t* Y, int ldy, const bf16_t* Gt, int ldg) {
;   epi_foreach(acc, [&](int r, int c, f32x4& v0, f32x4& v1) {
;     const u32x4 g = *(const u32x4*)(Gt + (size_t)r * ldg + c);
;     float o[8];
;     o[0] = bflo(g[0]) * v0[0]; o[1] = bfhi(g[0]) * v0[1]; o[2] = bflo(g[1]) * v0[2]; o[3] = bfhi(g[1]) * v0[3];
;     o[4] = bflo(g[2]) * v1[0]; o[5] = bfhi(g[2]) * v1[1]; o[6] = bflo(g[3]) * v1[2]; o[7] = bfhi(g[3]) * v1[3];
;     bf16_t* py = Y + (size_t)r * ldy + c;
;     if (ADD) {
;       const u32x4 y0 = *(const u32x4*)py;
; #pragma unroll
;       for (int j = 0; j < 4; ++j) { o[2 * j] += bflo(y0[j]); o[2 * j + 1] += bfhi(y0[j]); }
;     }
;     u32x4 pk;
; #pragma unroll
;     for (int j = 0; j < 4; ++j) pk[j] = cvt_pk_bf16(o[2 * j], o[2 * j + 1]);
;     *(u32x4*)py = pk;
;   });
	v_and_b32_e32 v169, 0xffff0000, v169
	v_pk_fma_f32 v[142:143], v[118:119], v[142:143], v[174:175]
	v_pk_fma_f32 v[168:169], v[120:121], v[130:131], v[168:169]
	v_lshlrev_b32_e32 v130, 16, v132
	v_and_b32_e32 v131, 0xffff0000, v132
	v_lshlrev_b32_e32 v174, 16, v170
	v_and_b32_e32 v175, 0xffff0000, v170
	v_pk_fma_f32 v[174:175], v[114:115], v[130:131], v[174:175]
	v_lshlrev_b32_e32 v130, 16, v133
	v_and_b32_e32 v131, 0xffff0000, v133
	v_lshlrev_b32_e32 v132, 16, v171
	v_and_b32_e32 v133, 0xffff0000, v171
	v_pk_fma_f32 v[170:171], v[116:117], v[130:131], v[132:133]
	v_cvt_pk_bf16_f32 v130, v142, v143
	v_or_b32_e32 v142, 16, v140
	v_cvt_pk_bf16_f32 v131, v168, v169
	v_cvt_pk_bf16_f32 v132, v174, v175
	v_cvt_pk_bf16_f32 v133, v170, v171
	v_ashrrev_i32_e32 v143, 31, v142
	global_store_dwordx4 v[172:173], v[130:133], off offset:256
	s_nop 1
	v_mad_i64_i32 v[130:131], s[0:1], s18, v142, 0
	v_lshlrev_b64 v[142:143], 11, v[142:143]
	v_lshl_add_u64 v[130:131], v[130:131], 1, s[26:27]
	v_lshl_add_u64 v[142:143], s[4:5], 0, v[142:143]
	v_lshl_add_u64 v[172:173], v[130:131], 0, v[0:1]
	v_lshl_add_u64 v[142:143], v[142:143], 0, v[0:1]
	s_nop 1
	v_mov_b32_e32 v130, v212
	v_mov_b32_e32 v131, v213
	v_mov_b32_e32 v132, v214
	v_mov_b32_e32 v133, v215
	s_nop 1
	v_mov_b32_e32 v168, v216
	v_mov_b32_e32 v169, v217
	v_mov_b32_e32 v170, v218
	v_mov_b32_e32 v171, v219
	v_lshlrev_b32_e32 v174, 16, v130
	v_and_b32_e32 v175, 0xffff0000, v130
	v_lshlrev_b32_e32 v176, 16, v168
	v_and_b32_e32 v177, 0xffff0000, v168
	v_lshlrev_b32_e32 v130, 16, v131
	v_and_b32_e32 v131, 0xffff0000, v131
	v_lshlrev_b32_e32 v168, 16, v169
	v_and_b32_e32 v169, 0xffff0000, v169
	v_pk_fma_f32 v[174:175], v[110:111], v[174:175], v[176:177]
	v_pk_fma_f32 v[168:169], v[112:113], v[130:131], v[168:169]
	v_lshlrev_b32_e32 v130, 16, v132
	v_and_b32_e32 v131, 0xffff0000, v132
	v_lshlrev_b32_e32 v176, 16, v170
	v_and_b32_e32 v177, 0xffff0000, v170
	v_pk_fma_f32 v[176:177], v[106:107], v[130:131], v[176:177]
	v_lshlrev_b32_e32 v130, 16, v133
	v_and_b32_e32 v131, 0xffff0000, v133
	v_lshlrev_b32_e32 v132, 16, v171
	v_and_b32_e32 v133, 0xffff0000, v171
	v_pk_fma_f32 v[170:171], v[108:109], v[130:131], v[132:133]
	v_cvt_pk_bf16_f32 v130, v174, v175
	v_cvt_pk_bf16_f32 v131, v168, v169
	v_cvt_pk_bf16_f32 v132, v176, v177
	v_cvt_pk_bf16_f32 v133, v170, v171
	global_store_dwordx4 v[142:143], v[130:133], off
	s_nop 1
	v_mov_b32_e32 v130, v220
	v_mov_b32_e32 v131, v221
	v_mov_b32_e32 v132, v222
	v_mov_b32_e32 v133, v223
	s_nop 0
	s_nop 1
	v_mov_b32_e32 v168, v224
	v_mov_b32_e32 v169, v225
	v_mov_b32_e32 v170, v226
	v_mov_b32_e32 v171, v227
	v_lshlrev_b32_e32 v172, 16, v130
	v_and_b32_e32 v173, 0xffff0000, v130
	v_lshlrev_b32_e32 v174, 16, v168
	v_and_b32_e32 v175, 0xffff0000, v168
	v_lshlrev_b32_e32 v130, 16, v131
	v_and_b32_e32 v131, 0xffff0000, v131
	v_lshlrev_b32_e32 v168, 16, v169
	v_and_b32_e32 v169, 0xffff0000, v169
	v_pk_fma_f32 v[172:173], v[102:103], v[172:173], v[174:175]
	v_pk_fma_f32 v[168:169], v[104:105], v[130:131], v[168:169]
	v_lshlrev_b32_e32 v130, 16, v132
	v_and_b32_e32 v131, 0xffff0000, v132
	v_lshlrev_b32_e32 v174, 16, v170
	v_and_b32_e32 v175, 0xffff0000, v170
	v_pk_fma_f32 v[174:175], v[98:99], v[130:131], v[174:175]
	v_lshlrev_b32_e32 v130, 16, v133
	v_and_b32_e32 v131, 0xffff0000, v133
	v_lshlrev_b32_e32 v132, 16, v171
	v_and_b32_e32 v133, 0xffff0000, v171
	v_pk_fma_f32 v[170:171], v[100:101], v[130:131], v[132:133]
	v_cvt_pk_bf16_f32 v130, v172, v173
	v_cvt_pk_bf16_f32 v131, v168, v169
	v_cvt_pk_bf16_f32 v132, v174, v175
	v_cvt_pk_bf16_f32 v133, v170, v171
	global_store_dwordx4 v[142:143], v[130:133], off offset:256
	v_or_b32_e32 v142, 32, v140
	v_ashrrev_i32_e32 v143, 31, v142
	v_mad_i64_i32 v[130:131], s[0:1], s18, v142, 0
	v_lshlrev_b64 v[142:143], 11, v[142:143]
	v_lshl_add_u64 v[130:131], v[130:131], 1, s[26:27]
	v_lshl_add_u64 v[142:143], s[4:5], 0, v[142:143]
	v_lshl_add_u64 v[172:173], v[130:131], 0, v[0:1]
	v_lshl_add_u64 v[142:143], v[142:143], 0, v[0:1]
	global_load_dwordx4 v[130:133], v[172:173], off offset:2048
	global_load_dwordx4 v[168:171], v[142:143], off
	s_lshl_b32 s100, s18, 5
	v_add_co_u32_e32 v178, vcc, s100, v172
	s_nop 1
	v_addc_co_u32_e32 v179, vcc, 0, v173, vcc
	v_add_co_u32_e32 v180, vcc, 0x8000, v142
	s_nop 1
	v_addc_co_u32_e32 v181, vcc, 0, v143, vcc
	global_load_dwordx4 v[204:207], v[172:173], off offset:2304
	global_load_dwordx4 v[208:211], v[142:143], off offset:256
	global_load_dwordx4 v[212:215], v[178:179], off offset:2048
	global_load_dwordx4 v[216:219], v[180:181], off
	global_load_dwordx4 v[220:223], v[178:179], off offset:2304
	global_load_dwordx4 v[224:227], v[180:181], off offset:256
	s_waitcnt vmcnt(0)
; DI unsigned cvt_pk_bf16(float lo, float hi) { f32x2_t v = {lo, hi}; bf16x2_t b = __builtin_convertvector(v, bf16x2_t); return __builtin_bit_cast(unsigned, b); }
; DI float bflo(unsigned u) { return __uint_as_float(u << 16); }
; DI float bfhi(unsigned u) { return __uint_as_float(u & 0xffff0000u); }
; template <bool ADD>
; DI void gated_tile(acc_t& acc, bf16_t* Y, int ldy, const bf16_t* Gt, int ldg) {
;   epi_foreach(acc, [&](int r, int c, f32x4& v0, f32x4& v1) {
;     const u32x4 g = *(const u32x4*)(Gt + (size_t)r * ldg + c);
;     float o[8];
;     o[0] = bflo(g[0]) * v0[0]; o[1] = bfhi(g[0]) * v0[1]; o[2] = bflo(g[1]) * v0[2]; o[3] = bfhi(g[1]) * v0[3];
;     o[4] = bflo(g[2]) * v1[0]; o[5] = bfhi(g[2]) * v1[1]; o[6] = bflo(g[3]) * v1[2]; o[7] = bfhi(g[3]) * v1[3];
;     bf16_t* py = Y + (size_t)r * ldy + c;
;     if (ADD) {
;       const u32x4 y0 = *(const u32x4*)py;
; #pragma unroll
;       for (int j = 0; j < 4; ++j) { o[2 * j] += bflo(y0[j]); o[2 * j + 1] += bfhi(y0[j]); }
;     }
;     u32x4 pk;
; #pragma unroll
;     for (int j = 0; j < 4; ++j) pk[j] = cvt_pk_bf16(o[2 * j], o[2 * j + 1]);
;     *(u32x4*)py = pk;
	v_lshlrev_b32_e32 v174, 16, v130
	v_and_b32_e32 v175, 0xffff0000, v130
	v_lshlrev_b32_e32 v176, 16, v168
	v_and_b32_e32 v177, 0xffff0000, v168
	v_lshlrev_b32_e32 v130, 16, v131
	v_and_b32_e32 v131, 0xffff0000, v131
	v_lshlrev_b32_e32 v168, 16, v169
	v_and_b32_e32 v169, 0xffff0000, v169
	v_pk_fma_f32 v[174:175], v[94:95], v[174:175], v[176:177]
	v_pk_fma_f32 v[168:169], v[96:97], v[130:131], v[168:169]
	v_lshlrev_b32_e32 v130, 16, v132
	v_and_b32_e32 v131, 0xffff0000, v132
	v_lshlrev_b32_e32 v176, 16, v170
	v_and_b32_e32 v177, 0xffff0000, v170
	v_pk_fma_f32 v[176:177], v[90:91], v[130:131], v[176:177]
	v_lshlrev_b32_e32 v130, 16, v133
	v_and_b32_e32 v131, 0xffff0000, v133
	v_lshlrev_b32_e32 v132, 16, v171
	v_and_b32_e32 v133, 0xffff0000, v171
	v_pk_fma_f32 v[170:171], v[92:93], v[130:131], v[132:133]
	v_cvt_pk_bf16_f32 v130, v174, v175
	v_cvt_pk_bf16_f32 v131, v168, v169
	v_cvt_pk_bf16_f32 v132, v176, v177
	v_cvt_pk_bf16_f32 v133, v170, v171
	global_store_dwordx4 v[142:143], v[130:133], off
	s_nop 1
	v_mov_b32_e32 v130, v204
	v_mov_b32_e32 v131, v205
	v_mov_b32_e32 v132, v206
	v_mov_b32_e32 v133, v207
	s_nop 0
	s_nop 1
	v_mov_b32_e32 v168, v208
	v_mov_b32_e32 v169, v209
	v_mov_b32_e32 v170, v210
	v_mov_b32_e32 v171, v211
	v_lshlrev_b32_e32 v172, 16, v130
	v_and_b32_e32 v173, 0xffff0000, v130
	v_lshlrev_b32_e32 v174, 16, v168
	v_and_b32_e32 v175, 0xffff0000, v168
	v_lshlrev_b32_e32 v130, 16, v131
	v_and_b32_e32 v131, 0xffff0000, v131
	v_lshlrev_b32_e32 v168, 16, v169
	v_and_b32_e32 v169, 0xffff0000, v169
	v_pk_fma_f32 v[172:173], v[86:87], v[172:173], v[174:175]
	v_pk_fma_f32 v[168:169], v[88:89], v[130:131], v[168:169]
	v_lshlrev_b32_e32 v130, 16, v132
	v_and_b32_e32 v131, 0xffff0000, v132
	v_lshlrev_b32_e32 v174, 16, v170
	v_and_b32_e32 v175, 0xffff0000, v170
	v_pk_fma_f32 v[174:175], v[82:83], v[130:131], v[174:175]
	v_lshlrev_b32_e32 v130, 16, v133
	v_and_b32_e32 v131, 0xffff0000, v133
	v_lshlrev_b32_e32 v132, 16, v171
	v_and_b32_e32 v133, 0xffff0000, v171
	v_pk_fma_f32 v[170:171], v[84:85], v[130:131], v[132:133]
	v_cvt_pk_bf16_f32 v130, v172, v173
	v_cvt_pk_bf16_f32 v131, v168, v169
	v_cvt_pk_bf16_f32 v132, v174, v175
	v_cvt_pk_bf16_f32 v133, v170, v171
	global_store_dwordx4 v[142:143], v[130:133], off offset:256
	v_or_b32_e32 v142, 48, v140
	v_ashrrev_i32_e32 v143, 31, v142
	v_mad_i64_i32 v[130:131], s[0:1], s18, v142, 0
	v_lshlrev_b64 v[142:143], 11, v[142:143]
	v_lshl_add_u64 v[130:131], v[130:131], 1, s[26:27]
	v_lshl_add_u64 v[142:143], s[4:5], 0, v[142:143]
	v_lshl_add_u64 v[172:173], v[130:131], 0, v[0:1]
	v_lshl_add_u64 v[142:143], v[142:143], 0, v[0:1]
	s_nop 1
	v_mov_b32_e32 v130, v212
	v_mov_b32_e32 v131, v213
	v_mov_b32_e32 v132, v214
	v_mov_b32_e32 v133, v215
	s_nop 1
	v_mov_b32_e32 v168, v216
	v_mov_b32_e32 v169, v217
	v_mov_b32_e32 v170, v218
	v_mov_b32_e32 v171, v219
	v_lshlrev_b32_e32 v174, 16, v130
	v_and_b32_e32 v175, 0xffff0000, v130
	v_lshlrev_b32_e32 v176, 16, v168
	v_and_b32_e32 v177, 0xffff0000, v168
	v_lshlrev_b32_e32 v130, 16, v131
	v_and_b32_e32 v131, 0xffff0000, v131
	v_lshlrev_b32_e32 v168, 16, v169
	v_and_b32_e32 v169, 0xffff0000, v169
	v_pk_fma_f32 v[174:175], v[78:79], v[174:175], v[176:177]
	v_pk_fma_f32 v[168:169], v[80:81], v[130:131], v[168:169]
	v_lshlrev_b32_e32 v130, 16, v132
	v_and_b32_e32 v131, 0xffff0000, v132
	v_lshlrev_b32_e32 v176, 16, v170
	v_and_b32_e32 v177, 0xffff0000, v170
	v_pk_fma_f32 v[176:177], v[74:75], v[130:131], v[176:177]
	v_lshlrev_b32_e32 v130, 16, v133
	v_and_b32_e32 v131, 0xffff0000, v133
	v_lshlrev_b32_e32 v132, 16, v171
	v_and_b32_e32 v133, 0xffff0000, v171
	v_pk_fma_f32 v[170:171], v[76:77], v[130:131], v[132:133]
	v_cvt_pk_bf16_f32 v130, v174, v175
	v_cvt_pk_bf16_f32 v131, v168, v169
	v_cvt_pk_bf16_f32 v132, v176, v177
	v_cvt_pk_bf16_f32 v133, v170, v171
	global_store_dwordx4 v[142:143], v[130:133], off
	s_nop 1
	v_mov_b32_e32 v130, v220
	v_mov_b32_e32 v131, v221
	v_mov_b32_e32 v132, v222
	v_mov_b32_e32 v133, v223
	s_nop 0
	s_nop 1
	v_mov_b32_e32 v168, v224
	v_mov_b32_e32 v169, v225
	v_mov_b32_e32 v170, v226
	v_mov_b32_e32 v171, v227
	v_lshlrev_b32_e32 v172, 16, v130
	v_and_b32_e32 v173, 0xffff0000, v130
	v_lshlrev_b32_e32 v174, 16, v168
	v_and_b32_e32 v175, 0xffff0000, v168
	v_lshlrev_b32_e32 v130, 16, v131
	v_and_b32_e32 v131, 0xffff0000, v131
	v_lshlrev_b32_e32 v168, 16, v169
	v_and_b32_e32 v169, 0xffff0000, v169
	v_pk_fma_f32 v[172:173], v[70:71], v[172:173], v[174:175]
	v_pk_fma_f32 v[168:169], v[72:73], v[130:131], v[168:169]
	v_lshlrev_b32_e32 v130, 16, v132
	v_and_b32_e32 v131, 0xffff0000, v132
	v_lshlrev_b32_e32 v174, 16, v170
	v_and_b32_e32 v175, 0xffff0000, v170
	v_pk_fma_f32 v[174:175], v[66:67], v[130:131], v[174:175]
	v_lshlrev_b32_e32 v130, 16, v133
	v_and_b32_e32 v131, 0xffff0000, v133
	v_lshlrev_b32_e32 v132, 16, v171
	v_and_b32_e32 v133, 0xffff0000, v171
	v_pk_fma_f32 v[170:171], v[68:69], v[130:131], v[132:133]
	v_cvt_pk_bf16_f32 v130, v172, v173
	v_cvt_pk_bf16_f32 v131, v168, v169
	v_cvt_pk_bf16_f32 v132, v174, v175
	v_cvt_pk_bf16_f32 v133, v170, v171
	global_store_dwordx4 v[142:143], v[130:133], off offset:256
	v_add_u32_e32 v142, 0x80, v140
	v_ashrrev_i32_e32 v143, 31, v142
	v_mad_i64_i32 v[130:131], s[0:1], s18, v142, 0
	v_lshlrev_b64 v[142:143], 11, v[142:143]
	v_lshl_add_u64 v[130:131], v[130:131], 1, s[26:27]
	v_lshl_add_u64 v[142:143], s[4:5], 0, v[142:143]
	v_lshl_add_u64 v[172:173], v[130:131], 0, v[0:1]
	v_lshl_add_u64 v[142:143], v[142:143], 0, v[0:1]
	global_load_dwordx4 v[130:133], v[172:173], off offset:2048
	global_load_dwordx4 v[168:171], v[142:143], off
	s_lshl_b32 s100, s18, 5
	v_add_co_u32_e32 v178, vcc, s100, v172
	s_nop 1
	v_addc_co_u32_e32 v179, vcc, 0, v173, vcc
	v_add_co_u32_e32 v180, vcc, 0x8000, v142
	s_nop 1
	v_addc_co_u32_e32 v181, vcc, 0, v143, vcc
	global_load_dwordx4 v[204:207], v[172:173], off offset:2304
	global_load_dwordx4 v[208:211], v[142:143], off offset:256
	global_load_dwordx4 v[212:215], v[178:179], off offset:2048
	global_load_dwordx4 v[216:219], v[180:181], off
	global_load_dwordx4 v[220:223], v[178:179], off offset:2304
	global_load_dwordx4 v[224:227], v[180:181], off offset:256
	s_waitcnt vmcnt(0)
; DI unsigned cvt_pk_bf16(float lo, float hi) { f32x2_t v = {lo, hi}; bf16x2_t b = __builtin_convertvector(v, bf16x2_t); return __builtin_bit_cast(unsigned, b); }
; DI float bflo(unsigned u) { return __uint_as_float(u << 16); }
; DI float bfhi(unsigned u) { return __uint_as_float(u & 0xffff0000u); }
; template <bool ADD>
; DI void gated_tile(acc_t& acc, bf16_t* Y, int ldy, const bf16_t* Gt, int ldg) {
;   epi_foreach(acc, [&](int r, int c, f32x4& v0, f32x4& v1) {
;     const u32x4 g = *(const u32x4*)(Gt + (size_t)r * ldg + c);
;     float o[8];
;     o[0] = bflo(g[0]) * v0[0]; o[1] = bfhi(g[0]) * v0[1]; o[2] = bflo(g[1]) * v0[2]; o[3] = bfhi(g[1]) * v0[3];
;     o[4] = bflo(g[2]) * v1[0]; o[5] = bfhi(g[2]) * v1[1]; o[6] = bflo(g[3]) * v1[2]; o[7] = bfhi(g[3]) * v1[3];
;     bf16_t* py = Y + (size_t)r * ldy + c;
;     if (ADD) {
;       const u32x4 y0 = *(const u32x4*)py;
; #pragma unroll
;       for (int j = 0; j < 4; ++j) { o[2 * j] += bflo(y0[j]); o[2 * j + 1] += bfhi(y0[j]); }
;     }
;     u32x4 pk;
; #pragma unroll
;     for (int j = 0; j < 4; ++j) pk[j] = cvt_pk_bf16(o[2 * j], o[2 * j + 1]);
;     *(u32x4*)py = pk;
	v_lshlrev_b32_e32 v174, 16, v130
	v_and_b32_e32 v175, 0xffff0000, v130
	v_lshlrev_b32_e32 v176, 16, v168
	v_and_b32_e32 v177, 0xffff0000, v168
	v_lshlrev_b32_e32 v130, 16, v131
	v_and_b32_e32 v131, 0xffff0000, v131
	v_lshlrev_b32_e32 v168, 16, v169
	v_and_b32_e32 v169, 0xffff0000, v169
	v_pk_fma_f32 v[174:175], v[62:63], v[174:175], v[176:177]
	v_pk_fma_f32 v[168:169], v[64:65], v[130:131], v[168:169]
	v_lshlrev_b32_e32 v130, 16, v132
	v_and_b32_e32 v131, 0xffff0000, v132
	v_lshlrev_b32_e32 v176, 16, v170
	v_and_b32_e32 v177, 0xffff0000, v170
	v_pk_fma_f32 v[176:177], v[58:59], v[130:131], v[176:177]
	v_lshlrev_b32_e32 v130, 16, v133
	v_and_b32_e32 v131, 0xffff0000, v133
	v_lshlrev_b32_e32 v132, 16, v171
	v_and_b32_e32 v133, 0xffff0000, v171
	v_pk_fma_f32 v[170:171], v[60:61], v[130:131], v[132:133]
	v_cvt_pk_bf16_f32 v130, v174, v175
	v_cvt_pk_bf16_f32 v131, v168, v169
	v_cvt_pk_bf16_f32 v132, v176, v177
	v_cvt_pk_bf16_f32 v133, v170, v171
	global_store_dwordx4 v[142:143], v[130:133], off
	s_nop 1
	v_mov_b32_e32 v130, v204
	v_mov_b32_e32 v131, v205
	v_mov_b32_e32 v132, v206
	v_mov_b32_e32 v133, v207
	s_nop 0
	s_nop 1
	v_mov_b32_e32 v168, v208
	v_mov_b32_e32 v169, v209
	v_mov_b32_e32 v170, v210
	v_mov_b32_e32 v171, v211
	v_lshlrev_b32_e32 v172, 16, v130
	v_and_b32_e32 v173, 0xffff0000, v130
	v_lshlrev_b32_e32 v174, 16, v168
	v_and_b32_e32 v175, 0xffff0000, v168
	v_lshlrev_b32_e32 v130, 16, v131
	v_and_b32_e32 v131, 0xffff0000, v131
	v_lshlrev_b32_e32 v168, 16, v169
	v_and_b32_e32 v169, 0xffff0000, v169
	v_pk_fma_f32 v[172:173], v[54:55], v[172:173], v[174:175]
	v_pk_fma_f32 v[168:169], v[56:57], v[130:131], v[168:169]
	v_lshlrev_b32_e32 v130, 16, v132
	v_and_b32_e32 v131, 0xffff0000, v132
	v_lshlrev_b32_e32 v174, 16, v170
	v_and_b32_e32 v175, 0xffff0000, v170
	v_pk_fma_f32 v[174:175], v[50:51], v[130:131], v[174:175]
	v_lshlrev_b32_e32 v130, 16, v133
	v_and_b32_e32 v131, 0xffff0000, v133
	v_lshlrev_b32_e32 v132, 16, v171
	v_and_b32_e32 v133, 0xffff0000, v171
	v_pk_fma_f32 v[170:171], v[52:53], v[130:131], v[132:133]
	v_cvt_pk_bf16_f32 v130, v172, v173
	v_cvt_pk_bf16_f32 v131, v168, v169
	v_cvt_pk_bf16_f32 v132, v174, v175
	v_cvt_pk_bf16_f32 v133, v170, v171
	global_store_dwordx4 v[142:143], v[130:133], off offset:256
	v_add_u32_e32 v142, 0x90, v140
	v_ashrrev_i32_e32 v143, 31, v142
	v_mad_i64_i32 v[130:131], s[0:1], s18, v142, 0
	v_lshlrev_b64 v[142:143], 11, v[142:143]
	v_lshl_add_u64 v[130:131], v[130:131], 1, s[26:27]
	v_lshl_add_u64 v[142:143], s[4:5], 0, v[142:143]
	v_lshl_add_u64 v[172:173], v[130:131], 0, v[0:1]
	v_lshl_add_u64 v[142:143], v[142:143], 0, v[0:1]
	s_nop 1
	v_mov_b32_e32 v130, v212
	v_mov_b32_e32 v131, v213
	v_mov_b32_e32 v132, v214
	v_mov_b32_e32 v133, v215
	s_nop 1
	v_mov_b32_e32 v168, v216
	v_mov_b32_e32 v169, v217
	v_mov_b32_e32 v170, v218
	v_mov_b32_e32 v171, v219
	v_lshlrev_b32_e32 v174, 16, v130
	v_and_b32_e32 v175, 0xffff0000, v130
	v_lshlrev_b32_e32 v176, 16, v168
	v_and_b32_e32 v177, 0xffff0000, v168
	v_lshlrev_b32_e32 v130, 16, v131
	v_and_b32_e32 v131, 0xffff0000, v131
	v_lshlrev_b32_e32 v168, 16, v169
	v_and_b32_e32 v169, 0xffff0000, v169
	v_pk_fma_f32 v[174:175], v[46:47], v[174:175], v[176:177]
	v_pk_fma_f32 v[168:169], v[48:49], v[130:131], v[168:169]
	v_lshlrev_b32_e32 v130, 16, v132
	v_and_b32_e32 v131, 0xffff0000, v132
	v_lshlrev_b32_e32 v176, 16, v170
	v_and_b32_e32 v177, 0xffff0000, v170
	v_pk_fma_f32 v[176:177], v[42:43], v[130:131], v[176:177]
	v_lshlrev_b32_e32 v130, 16, v133
	v_and_b32_e32 v131, 0xffff0000, v133
	v_lshlrev_b32_e32 v132, 16, v171
	v_and_b32_e32 v133, 0xffff0000, v171
	v_pk_fma_f32 v[170:171], v[44:45], v[130:131], v[132:133]
	v_cvt_pk_bf16_f32 v130, v174, v175
	v_cvt_pk_bf16_f32 v131, v168, v169
	v_cvt_pk_bf16_f32 v132, v176, v177
	v_cvt_pk_bf16_f32 v133, v170, v171
	global_store_dwordx4 v[142:143], v[130:133], off
	s_nop 1
	v_mov_b32_e32 v130, v220
	v_mov_b32_e32 v131, v221
	v_mov_b32_e32 v132, v222
	v_mov_b32_e32 v133, v223
	s_nop 0
	s_nop 1
	v_mov_b32_e32 v168, v224
	v_mov_b32_e32 v169, v225
	v_mov_b32_e32 v170, v226
	v_mov_b32_e32 v171, v227
	v_lshlrev_b32_e32 v172, 16, v130
	v_and_b32_e32 v173, 0xffff0000, v130
	v_lshlrev_b32_e32 v174, 16, v168
	v_and_b32_e32 v175, 0xffff0000, v168
	v_lshlrev_b32_e32 v130, 16, v131
	v_and_b32_e32 v131, 0xffff0000, v131
	v_lshlrev_b32_e32 v168, 16, v169
	v_and_b32_e32 v169, 0xffff0000, v169
	v_pk_fma_f32 v[172:173], v[38:39], v[172:173], v[174:175]
	v_pk_fma_f32 v[168:169], v[40:41], v[130:131], v[168:169]
	v_lshlrev_b32_e32 v130, 16, v132
	v_and_b32_e32 v131, 0xffff0000, v132
	v_lshlrev_b32_e32 v174, 16, v170
	v_and_b32_e32 v175, 0xffff0000, v170
	v_pk_fma_f32 v[174:175], v[34:35], v[130:131], v[174:175]
	v_lshlrev_b32_e32 v130, 16, v133
	v_and_b32_e32 v131, 0xffff0000, v133
	v_lshlrev_b32_e32 v132, 16, v171
	v_and_b32_e32 v133, 0xffff0000, v171
	v_pk_fma_f32 v[170:171], v[36:37], v[130:131], v[132:133]
	v_cvt_pk_bf16_f32 v130, v172, v173
	v_cvt_pk_bf16_f32 v131, v168, v169
	v_cvt_pk_bf16_f32 v132, v174, v175
	v_cvt_pk_bf16_f32 v133, v170, v171
	global_store_dwordx4 v[142:143], v[130:133], off offset:256
	v_add_u32_e32 v142, 0xa0, v140
	v_ashrrev_i32_e32 v143, 31, v142
	v_mad_i64_i32 v[130:131], s[0:1], s18, v142, 0
	v_lshlrev_b64 v[142:143], 11, v[142:143]
	v_lshl_add_u64 v[130:131], v[130:131], 1, s[26:27]
	v_lshl_add_u64 v[142:143], s[4:5], 0, v[142:143]
	v_lshl_add_u64 v[172:173], v[130:131], 0, v[0:1]
	v_lshl_add_u64 v[142:143], v[142:143], 0, v[0:1]
	global_load_dwordx4 v[130:133], v[172:173], off offset:2048
	global_load_dwordx4 v[168:171], v[142:143], off
	s_lshl_b32 s100, s18, 5
	v_add_co_u32_e32 v178, vcc, s100, v172
	s_nop 1
	v_addc_co_u32_e32 v179, vcc, 0, v173, vcc
	v_add_co_u32_e32 v180, vcc, 0x8000, v142
	s_nop 1
	v_addc_co_u32_e32 v181, vcc, 0, v143, vcc
	global_load_dwordx4 v[204:207], v[172:173], off offset:2304
	global_load_dwordx4 v[208:211], v[142:143], off offset:256
	global_load_dwordx4 v[212:215], v[178:179], off offset:2048
	global_load_dwordx4 v[216:219], v[180:181], off
	global_load_dwordx4 v[220:223], v[178:179], off offset:2304
	global_load_dwordx4 v[224:227], v[180:181], off offset:256
	v_add_u32_e32 v140, 0xb0, v140
	v_ashrrev_i32_e32 v141, 31, v140
	s_waitcnt vmcnt(0)
; DI unsigned cvt_pk_bf16(float lo, float hi) { f32x2_t v = {lo, hi}; bf16x2_t b = __builtin_convertvector(v, bf16x2_t); return __builtin_bit_cast(unsigned, b); }
; DI float bflo(unsigned u) { return __uint_as_float(u << 16); }
; DI float bfhi(unsigned u) { return __uint_as_float(u & 0xffff0000u); }
; template <bool ADD>
; DI void gated_tile(acc_t& acc, bf16_t* Y, int ldy, const bf16_t* Gt, int ldg) {
;   epi_foreach(acc, [&](int r, int c, f32x4& v0, f32x4& v1) {
;     const u32x4 g = *(const u32x4*)(Gt + (size_t)r * ldg + c);
;     float o[8];
;     o[0] = bflo(g[0]) * v0[0]; o[1] = bfhi(g[0]) * v0[1]; o[2] = bflo(g[1]) * v0[2]; o[3] = bfhi(g[1]) * v0[3];
;     o[4] = bflo(g[2]) * v1[0]; o[5] = bfhi(g[2]) * v1[1]; o[6] = bflo(g[3]) * v1[2]; o[7] = bfhi(g[3]) * v1[3];
;     bf16_t* py = Y + (size_t)r * ldy + c;
;     if (ADD) {
;       const u32x4 y0 = *(const u32x4*)py;
; #pragma unroll
;       for (int j = 0; j < 4; ++j) { o[2 * j] += bflo(y0[j]); o[2 * j + 1] += bfhi(y0[j]); }
;     }
;     u32x4 pk;
; #pragma unroll
;     for (int j = 0; j < 4; ++j) pk[j] = cvt_pk_bf16(o[2 * j], o[2 * j + 1]);
;     *(u32x4*)py = pk;
	v_lshlrev_b32_e32 v174, 16, v130
	v_and_b32_e32 v175, 0xffff0000, v130
	v_lshlrev_b32_e32 v176, 16, v168
	v_and_b32_e32 v177, 0xffff0000, v168
	v_lshlrev_b32_e32 v130, 16, v131
	v_and_b32_e32 v131, 0xffff0000, v131
	v_lshlrev_b32_e32 v168, 16, v169
	v_and_b32_e32 v169, 0xffff0000, v169
	v_pk_fma_f32 v[174:175], v[30:31], v[174:175], v[176:177]
	v_pk_fma_f32 v[168:169], v[32:33], v[130:131], v[168:169]
	v_lshlrev_b32_e32 v130, 16, v132
	v_and_b32_e32 v131, 0xffff0000, v132
	v_lshlrev_b32_e32 v176, 16, v170
	v_and_b32_e32 v177, 0xffff0000, v170
	v_pk_fma_f32 v[176:177], v[26:27], v[130:131], v[176:177]
	v_lshlrev_b32_e32 v130, 16, v133
	v_and_b32_e32 v131, 0xffff0000, v133
	v_lshlrev_b32_e32 v132, 16, v171
	v_and_b32_e32 v133, 0xffff0000, v171
	v_pk_fma_f32 v[170:171], v[28:29], v[130:131], v[132:133]
	v_cvt_pk_bf16_f32 v130, v174, v175
	v_cvt_pk_bf16_f32 v131, v168, v169
	v_cvt_pk_bf16_f32 v132, v176, v177
	v_cvt_pk_bf16_f32 v133, v170, v171
	global_store_dwordx4 v[142:143], v[130:133], off
	s_nop 1
	v_mov_b32_e32 v130, v204
	v_mov_b32_e32 v131, v205
	v_mov_b32_e32 v132, v206
	v_mov_b32_e32 v133, v207
	s_nop 0
	s_nop 1
	v_mov_b32_e32 v168, v208
	v_mov_b32_e32 v169, v209
	v_mov_b32_e32 v170, v210
	v_mov_b32_e32 v171, v211
	v_lshlrev_b32_e32 v172, 16, v130
	v_and_b32_e32 v173, 0xffff0000, v130
	v_lshlrev_b32_e32 v174, 16, v168
	v_and_b32_e32 v175, 0xffff0000, v168
	v_lshlrev_b32_e32 v130, 16, v131
	v_and_b32_e32 v131, 0xffff0000, v131
	v_lshlrev_b32_e32 v168, 16, v169
	v_and_b32_e32 v169, 0xffff0000, v169
	v_pk_fma_f32 v[172:173], v[22:23], v[172:173], v[174:175]
	v_pk_fma_f32 v[168:169], v[24:25], v[130:131], v[168:169]
	v_lshlrev_b32_e32 v130, 16, v132
	v_and_b32_e32 v131, 0xffff0000, v132
	v_lshlrev_b32_e32 v174, 16, v170
	v_and_b32_e32 v175, 0xffff0000, v170
	v_pk_fma_f32 v[174:175], v[18:19], v[130:131], v[174:175]
	v_lshlrev_b32_e32 v130, 16, v133
	v_and_b32_e32 v131, 0xffff0000, v133
	v_lshlrev_b32_e32 v132, 16, v171
	v_and_b32_e32 v133, 0xffff0000, v171
	v_pk_fma_f32 v[170:171], v[20:21], v[130:131], v[132:133]
	v_cvt_pk_bf16_f32 v130, v172, v173
	v_cvt_pk_bf16_f32 v131, v168, v169
	v_cvt_pk_bf16_f32 v132, v174, v175
	v_cvt_pk_bf16_f32 v133, v170, v171
	global_store_dwordx4 v[142:143], v[130:133], off offset:256
	s_nop 1
	v_mad_i64_i32 v[130:131], s[0:1], s18, v140, 0
	v_lshlrev_b64 v[140:141], 11, v[140:141]
	v_lshl_add_u64 v[130:131], v[130:131], 1, s[26:27]
	v_lshl_add_u64 v[140:141], s[4:5], 0, v[140:141]
	v_lshl_add_u64 v[142:143], v[130:131], 0, v[0:1]
	v_lshl_add_u64 v[140:141], v[140:141], 0, v[0:1]
	s_nop 1
	v_mov_b32_e32 v130, v212
	v_mov_b32_e32 v131, v213
	v_mov_b32_e32 v132, v214
	v_mov_b32_e32 v133, v215
	s_nop 1
	v_mov_b32_e32 v168, v216
	v_mov_b32_e32 v169, v217
	v_mov_b32_e32 v170, v218
	v_mov_b32_e32 v171, v219
	s_mov_b64 s[4:5], 0
	v_lshlrev_b32_e32 v172, 16, v130
	v_and_b32_e32 v173, 0xffff0000, v130
	v_lshlrev_b32_e32 v174, 16, v168
	v_and_b32_e32 v175, 0xffff0000, v168
	v_lshlrev_b32_e32 v130, 16, v131
	v_and_b32_e32 v131, 0xffff0000, v131
	v_lshlrev_b32_e32 v168, 16, v169
	v_and_b32_e32 v169, 0xffff0000, v169
	v_pk_fma_f32 v[172:173], v[14:15], v[172:173], v[174:175]
	v_pk_fma_f32 v[168:169], v[16:17], v[130:131], v[168:169]
	v_lshlrev_b32_e32 v130, 16, v132
	v_and_b32_e32 v131, 0xffff0000, v132
	v_lshlrev_b32_e32 v174, 16, v170
	v_and_b32_e32 v175, 0xffff0000, v170
	v_pk_fma_f32 v[174:175], v[10:11], v[130:131], v[174:175]
	v_lshlrev_b32_e32 v130, 16, v133
	v_and_b32_e32 v131, 0xffff0000, v133
	v_lshlrev_b32_e32 v132, 16, v171
	v_and_b32_e32 v133, 0xffff0000, v171
	v_pk_fma_f32 v[170:171], v[12:13], v[130:131], v[132:133]
	v_cvt_pk_bf16_f32 v130, v172, v173
	v_cvt_pk_bf16_f32 v131, v168, v169
	v_cvt_pk_bf16_f32 v132, v174, v175
	v_cvt_pk_bf16_f32 v133, v170, v171
	global_store_dwordx4 v[140:141], v[130:133], off
	s_nop 1
	v_mov_b32_e32 v130, v220
	v_mov_b32_e32 v131, v221
	v_mov_b32_e32 v132, v222
	v_mov_b32_e32 v133, v223
	s_nop 0
	s_nop 1
	v_mov_b32_e32 v168, v224
	v_mov_b32_e32 v169, v225
	v_mov_b32_e32 v170, v226
	v_mov_b32_e32 v171, v227
	v_lshlrev_b32_e32 v142, 16, v130
	v_and_b32_e32 v143, 0xffff0000, v130
	v_lshlrev_b32_e32 v172, 16, v168
	v_and_b32_e32 v173, 0xffff0000, v168
	v_lshlrev_b32_e32 v130, 16, v131
	v_and_b32_e32 v131, 0xffff0000, v131
	v_lshlrev_b32_e32 v168, 16, v169
	v_and_b32_e32 v169, 0xffff0000, v169
	v_pk_fma_f32 v[142:143], v[6:7], v[142:143], v[172:173]
	v_pk_fma_f32 v[168:169], v[8:9], v[130:131], v[168:169]
	v_lshlrev_b32_e32 v130, 16, v132
	v_and_b32_e32 v131, 0xffff0000, v132
	v_lshlrev_b32_e32 v172, 16, v170
	v_and_b32_e32 v173, 0xffff0000, v170
	v_pk_fma_f32 v[172:173], v[2:3], v[130:131], v[172:173]
	v_lshlrev_b32_e32 v130, 16, v133
	v_and_b32_e32 v131, 0xffff0000, v133
	v_lshlrev_b32_e32 v132, 16, v171
	v_and_b32_e32 v133, 0xffff0000, v171
	v_pk_fma_f32 v[170:171], v[4:5], v[130:131], v[132:133]
	v_cvt_pk_bf16_f32 v130, v142, v143
	v_cvt_pk_bf16_f32 v131, v168, v169
	v_cvt_pk_bf16_f32 v132, v172, v173
	v_cvt_pk_bf16_f32 v133, v170, v171
	global_store_dwordx4 v[140:141], v[130:133], off offset:256
; DI unsigned cvt_pk_bf16(float lo, float hi) { f32x2_t v = {lo, hi}; bf16x2_t b = __builtin_convertvector(v, bf16x2_t); return __builtin_bit_cast(unsigned, b); }
; DI float bflo(unsigned u) { return __uint_as_float(u << 16); }
; DI float bfhi(unsigned u) { return __uint_as_float(u & 0xffff0000u); }
; template <bool ADD>
; DI void gated_tile(acc_t& acc, bf16_t* Y, int ldy, const bf16_t* Gt, int ldg) {
;   epi_foreach(acc, [&](int r, int c, f32x4& v0, f32x4& v1) {
;     const u32x4 g = *(const u32x4*)(Gt + (size_t)r * ldg + c);
;     float o[8];
;     o[0] = bflo(g[0]) * v0[0]; o[1] = bfhi(g[0]) * v0[1]; o[2] = bflo(g[1]) * v0[2]; o[3] = bfhi(g[1]) * v0[3];
;     o[4] = bflo(g[2]) * v1[0]; o[5] = bfhi(g[2]) * v1[1]; o[6] = bflo(g[3]) * v1[2]; o[7] = bfhi(g[3]) * v1[3];
;     bf16_t* py = Y + (size_t)r * ldy + c;
;     if (ADD) {
;       const u32x4 y0 = *(const u32x4*)py;
; #pragma unroll
;       for (int j = 0; j < 4; ++j) { o[2 * j] += bflo(y0[j]); o[2 * j + 1] += bfhi(y0[j]); }
;     }
;     u32x4 pk;
; #pragma unroll
;     for (int j = 0; j < 4; ++j) pk[j] = cvt_pk_bf16(o[2 * j], o[2 * j + 1]);
;     *(u32x4*)py = pk;
.LBB0_1270:
	v_readlane_b32 s18, v251, 31
	s_andn2_b64 vcc, exec, s[4:5]
	v_readlane_b32 s19, v251, 32
	s_cbranch_vccnz .LBB0_1265
	v_mov_b32_e32 v0, v149
	s_movk_i32 s0, 0xffc0
	v_and_b32_e32 v130, 15, v0
	v_ashrrev_i32_e32 v131, 2, v0
	v_and_or_b32 v130, v131, s0, v130
	v_readlane_b32 s26, v253, 34
	v_readlane_b32 s46, v253, 35
	v_readlane_b32 s47, v253, 36
	v_mad_i64_i32 v[132:133], s[0:1], s26, v130, 0
	s_nop 0
	v_lshl_add_u64 v[132:133], v[132:133], 1, s[46:47]
	v_and_b32_e32 v0, 0xf0, v0
	v_lshl_add_u64 v[132:133], v[132:133], 0, v[0:1]
	global_load_dwordx4 v[140:143], v[132:133], off
	s_lshl_b32 s100, s26, 5
	v_add_co_u32_e32 v178, vcc, s100, v132
	s_nop 1
	v_addc_co_u32_e32 v179, vcc, 0, v133, vcc
	global_load_dwordx4 v[204:207], v[132:133], off offset:256
	global_load_dwordx4 v[208:211], v[178:179], off
	global_load_dwordx4 v[212:215], v[178:179], off offset:256
	v_ashrrev_i32_e32 v131, 31, v130
	v_readlane_b32 s4, v251, 33
	v_readlane_b32 s5, v251, 34
	s_waitcnt vmcnt(0)
	v_lshlrev_b32_e32 v168, 16, v140
	v_and_b32_e32 v169, 0xffff0000, v140
	v_lshlrev_b32_e32 v140, 16, v141
	v_and_b32_e32 v141, 0xffff0000, v141
	v_pk_mul_f32 v[128:129], v[128:129], v[140:141]
	v_lshlrev_b32_e32 v140, 16, v142
	v_and_b32_e32 v141, 0xffff0000, v142
	v_pk_mul_f32 v[126:127], v[126:127], v[168:169]
	v_pk_mul_f32 v[140:141], v[122:123], v[140:141]
	v_lshlrev_b32_e32 v122, 16, v143
	v_and_b32_e32 v123, 0xffff0000, v143
	v_pk_mul_f32 v[142:143], v[124:125], v[122:123]
	v_cvt_pk_bf16_f32 v122, v126, v127
	v_lshlrev_b64 v[126:127], 11, v[130:131]
	v_lshl_add_u64 v[126:127], s[4:5], 0, v[126:127]
	v_cvt_pk_bf16_f32 v123, v128, v129
	v_cvt_pk_bf16_f32 v124, v140, v141
	v_cvt_pk_bf16_f32 v125, v142, v143
	v_lshl_add_u64 v[126:127], v[126:127], 0, v[0:1]
	global_store_dwordx4 v[126:127], v[122:125], off
	s_nop 1
	v_mov_b32_e32 v122, v204
	v_mov_b32_e32 v123, v205
	v_mov_b32_e32 v124, v206
	v_mov_b32_e32 v125, v207
	v_lshlrev_b32_e32 v128, 16, v122
	v_and_b32_e32 v129, 0xffff0000, v122
	v_lshlrev_b32_e32 v122, 16, v123
	v_and_b32_e32 v123, 0xffff0000, v123
	v_pk_mul_f32 v[120:121], v[120:121], v[122:123]
	v_lshlrev_b32_e32 v122, 16, v124
	v_and_b32_e32 v123, 0xffff0000, v124
	v_pk_mul_f32 v[122:123], v[114:115], v[122:123]
	v_lshlrev_b32_e32 v114, 16, v125
	v_and_b32_e32 v115, 0xffff0000, v125
	v_pk_mul_f32 v[118:119], v[118:119], v[128:129]
	v_pk_mul_f32 v[124:125], v[116:117], v[114:115]
	v_cvt_pk_bf16_f32 v114, v118, v119
	v_cvt_pk_bf16_f32 v115, v120, v121
	v_cvt_pk_bf16_f32 v116, v122, v123
	v_cvt_pk_bf16_f32 v117, v124, v125
	v_or_b32_e32 v118, 16, v130
	global_store_dwordx4 v[126:127], v[114:117], off offset:256
	v_ashrrev_i32_e32 v119, 31, v118
	s_nop 0
	v_mad_i64_i32 v[114:115], s[0:1], s26, v118, 0
	v_lshl_add_u64 v[114:115], v[114:115], 1, s[46:47]
	v_lshl_add_u64 v[120:121], v[114:115], 0, v[0:1]
	s_nop 1
	v_mov_b32_e32 v114, v208
	v_mov_b32_e32 v115, v209
	v_mov_b32_e32 v116, v210
	v_mov_b32_e32 v117, v211
	v_lshlrev_b32_e32 v122, 16, v114
	v_and_b32_e32 v123, 0xffff0000, v114
	v_lshlrev_b32_e32 v114, 16, v115
	v_and_b32_e32 v115, 0xffff0000, v115
	v_pk_mul_f32 v[112:113], v[112:113], v[114:115]
	v_lshlrev_b32_e32 v114, 16, v116
	v_and_b32_e32 v115, 0xffff0000, v116
	v_pk_mul_f32 v[110:111], v[110:111], v[122:123]
	v_pk_mul_f32 v[114:115], v[106:107], v[114:115]
	v_lshlrev_b32_e32 v106, 16, v117
	v_and_b32_e32 v107, 0xffff0000, v117
	v_pk_mul_f32 v[116:117], v[108:109], v[106:107]
	v_cvt_pk_bf16_f32 v106, v110, v111
	v_lshlrev_b64 v[110:111], 11, v[118:119]
	v_lshl_add_u64 v[110:111], s[4:5], 0, v[110:111]
	v_cvt_pk_bf16_f32 v107, v112, v113
	v_cvt_pk_bf16_f32 v108, v114, v115
	v_cvt_pk_bf16_f32 v109, v116, v117
	v_lshl_add_u64 v[110:111], v[110:111], 0, v[0:1]
	global_store_dwordx4 v[110:111], v[106:109], off
	s_nop 1
	v_mov_b32_e32 v106, v212
	v_mov_b32_e32 v107, v213
	v_mov_b32_e32 v108, v214
	v_mov_b32_e32 v109, v215
	v_lshlrev_b32_e32 v112, 16, v106
	v_and_b32_e32 v113, 0xffff0000, v106
	v_lshlrev_b32_e32 v106, 16, v107
	v_and_b32_e32 v107, 0xffff0000, v107
	v_pk_mul_f32 v[104:105], v[104:105], v[106:107]
	v_lshlrev_b32_e32 v106, 16, v108
	v_and_b32_e32 v107, 0xffff0000, v108
	v_pk_mul_f32 v[106:107], v[98:99], v[106:107]
	v_lshlrev_b32_e32 v98, 16, v109
	v_and_b32_e32 v99, 0xffff0000, v109
	v_pk_mul_f32 v[102:103], v[102:103], v[112:113]
	v_pk_mul_f32 v[108:109], v[100:101], v[98:99]
	v_cvt_pk_bf16_f32 v98, v102, v103
	v_cvt_pk_bf16_f32 v99, v104, v105
	v_cvt_pk_bf16_f32 v100, v106, v107
	v_cvt_pk_bf16_f32 v101, v108, v109
	v_or_b32_e32 v102, 32, v130
	global_store_dwordx4 v[110:111], v[98:101], off offset:256
	v_ashrrev_i32_e32 v103, 31, v102
	s_nop 0
	v_mad_i64_i32 v[98:99], s[0:1], s26, v102, 0
	v_lshl_add_u64 v[98:99], v[98:99], 1, s[46:47]
	v_lshl_add_u64 v[104:105], v[98:99], 0, v[0:1]
	global_load_dwordx4 v[98:101], v[104:105], off
	s_lshl_b32 s100, s26, 5
	v_add_co_u32_e32 v178, vcc, s100, v104
	s_nop 1
	v_addc_co_u32_e32 v179, vcc, 0, v105, vcc
	global_load_dwordx4 v[204:207], v[104:105], off offset:256
	global_load_dwordx4 v[208:211], v[178:179], off
	global_load_dwordx4 v[212:215], v[178:179], off offset:256
	s_waitcnt vmcnt(0)
; DI unsigned cvt_pk_bf16(float lo, float hi) { f32x2_t v = {lo, hi}; bf16x2_t b = __builtin_convertvector(v, bf16x2_t); return __builtin_bit_cast(unsigned, b); }
; DI float bflo(unsigned u) { return __uint_as_float(u << 16); }
; DI float bfhi(unsigned u) { return __uint_as_float(u & 0xffff0000u); }
; template <bool ADD>
; DI void gated_tile(acc_t& acc, bf16_t* Y, int ldy, const bf16_t* Gt, int ldg) {
;   epi_foreach(acc, [&](int r, int c, f32x4& v0, f32x4& v1) {
;     const u32x4 g = *(const u32x4*)(Gt + (size_t)r * ldg + c);
;     float o[8];
;     o[0] = bflo(g[0]) * v0[0]; o[1] = bfhi(g[0]) * v0[1]; o[2] = bflo(g[1]) * v0[2]; o[3] = bfhi(g[1]) * v0[3];
;     o[4] = bflo(g[2]) * v1[0]; o[5] = bfhi(g[2]) * v1[1]; o[6] = bflo(g[3]) * v1[2]; o[7] = bfhi(g[3]) * v1[3];
;     bf16_t* py = Y + (size_t)r * ldy + c;
;     if (ADD) {
;       const u32x4 y0 = *(const u32x4*)py;
; #pragma unroll
;       for (int j = 0; j < 4; ++j) { o[2 * j] += bflo(y0[j]); o[2 * j + 1] += bfhi(y0[j]); }
;     }
;     u32x4 pk;
; #pragma unroll
;     for (int j = 0; j < 4; ++j) pk[j] = cvt_pk_bf16(o[2 * j], o[2 * j + 1]);
;     *(u32x4*)py = pk;
	v_lshlrev_b32_e32 v106, 16, v98
	v_and_b32_e32 v107, 0xffff0000, v98
	v_lshlrev_b32_e32 v98, 16, v99
	v_and_b32_e32 v99, 0xffff0000, v99
	v_pk_mul_f32 v[96:97], v[96:97], v[98:99]
	v_lshlrev_b32_e32 v98, 16, v100
	v_and_b32_e32 v99, 0xffff0000, v100
	v_pk_mul_f32 v[94:95], v[94:95], v[106:107]
	v_pk_mul_f32 v[98:99], v[90:91], v[98:99]
	v_lshlrev_b32_e32 v90, 16, v101
	v_and_b32_e32 v91, 0xffff0000, v101
	v_pk_mul_f32 v[100:101], v[92:93], v[90:91]
	v_cvt_pk_bf16_f32 v90, v94, v95
	v_lshlrev_b64 v[94:95], 11, v[102:103]
	v_lshl_add_u64 v[94:95], s[4:5], 0, v[94:95]
	v_cvt_pk_bf16_f32 v91, v96, v97
	v_cvt_pk_bf16_f32 v92, v98, v99
	v_cvt_pk_bf16_f32 v93, v100, v101
	v_lshl_add_u64 v[94:95], v[94:95], 0, v[0:1]
	global_store_dwordx4 v[94:95], v[90:93], off
	s_nop 1
	v_mov_b32_e32 v90, v204
	v_mov_b32_e32 v91, v205
	v_mov_b32_e32 v92, v206
	v_mov_b32_e32 v93, v207
	v_lshlrev_b32_e32 v96, 16, v90
	v_and_b32_e32 v97, 0xffff0000, v90
	v_lshlrev_b32_e32 v90, 16, v91
	v_and_b32_e32 v91, 0xffff0000, v91
	v_pk_mul_f32 v[88:89], v[88:89], v[90:91]
	v_lshlrev_b32_e32 v90, 16, v92
	v_and_b32_e32 v91, 0xffff0000, v92
	v_pk_mul_f32 v[90:91], v[82:83], v[90:91]
	v_lshlrev_b32_e32 v82, 16, v93
	v_and_b32_e32 v83, 0xffff0000, v93
	v_pk_mul_f32 v[86:87], v[86:87], v[96:97]
	v_pk_mul_f32 v[92:93], v[84:85], v[82:83]
	v_cvt_pk_bf16_f32 v82, v86, v87
	v_cvt_pk_bf16_f32 v83, v88, v89
	v_cvt_pk_bf16_f32 v84, v90, v91
	v_cvt_pk_bf16_f32 v85, v92, v93
	v_or_b32_e32 v86, 48, v130
	global_store_dwordx4 v[94:95], v[82:85], off offset:256
	v_ashrrev_i32_e32 v87, 31, v86
	s_nop 0
	v_mad_i64_i32 v[82:83], s[0:1], s26, v86, 0
	v_lshl_add_u64 v[82:83], v[82:83], 1, s[46:47]
	v_lshl_add_u64 v[88:89], v[82:83], 0, v[0:1]
	s_nop 1
	v_mov_b32_e32 v82, v208
	v_mov_b32_e32 v83, v209
	v_mov_b32_e32 v84, v210
	v_mov_b32_e32 v85, v211
	v_lshlrev_b32_e32 v90, 16, v82
	v_and_b32_e32 v91, 0xffff0000, v82
	v_lshlrev_b32_e32 v82, 16, v83
	v_and_b32_e32 v83, 0xffff0000, v83
	v_pk_mul_f32 v[80:81], v[80:81], v[82:83]
	v_lshlrev_b32_e32 v82, 16, v84
	v_and_b32_e32 v83, 0xffff0000, v84
	v_pk_mul_f32 v[78:79], v[78:79], v[90:91]
	v_pk_mul_f32 v[82:83], v[74:75], v[82:83]
	v_lshlrev_b32_e32 v74, 16, v85
	v_and_b32_e32 v75, 0xffff0000, v85
	v_pk_mul_f32 v[84:85], v[76:77], v[74:75]
	v_cvt_pk_bf16_f32 v74, v78, v79
	v_lshlrev_b64 v[78:79], 11, v[86:87]
	v_lshl_add_u64 v[78:79], s[4:5], 0, v[78:79]
	v_cvt_pk_bf16_f32 v75, v80, v81
	v_cvt_pk_bf16_f32 v76, v82, v83
	v_cvt_pk_bf16_f32 v77, v84, v85
	v_lshl_add_u64 v[78:79], v[78:79], 0, v[0:1]
	global_store_dwordx4 v[78:79], v[74:77], off
	s_nop 1
	v_mov_b32_e32 v74, v212
	v_mov_b32_e32 v75, v213
	v_mov_b32_e32 v76, v214
	v_mov_b32_e32 v77, v215
	v_lshlrev_b32_e32 v80, 16, v74
	v_and_b32_e32 v81, 0xffff0000, v74
	v_lshlrev_b32_e32 v74, 16, v75
	v_and_b32_e32 v75, 0xffff0000, v75
	v_pk_mul_f32 v[72:73], v[72:73], v[74:75]
	v_lshlrev_b32_e32 v74, 16, v76
	v_and_b32_e32 v75, 0xffff0000, v76
	v_pk_mul_f32 v[74:75], v[66:67], v[74:75]
	v_lshlrev_b32_e32 v66, 16, v77
	v_and_b32_e32 v67, 0xffff0000, v77
	v_pk_mul_f32 v[70:71], v[70:71], v[80:81]
	v_pk_mul_f32 v[76:77], v[68:69], v[66:67]
	v_cvt_pk_bf16_f32 v66, v70, v71
	v_cvt_pk_bf16_f32 v67, v72, v73
	v_cvt_pk_bf16_f32 v68, v74, v75
	v_cvt_pk_bf16_f32 v69, v76, v77
	global_store_dwordx4 v[78:79], v[66:69], off offset:256
	v_add_u32_e32 v70, 0x80, v130
	s_nop 0
	v_mad_i64_i32 v[66:67], s[0:1], s26, v70, 0
	v_lshl_add_u64 v[66:67], v[66:67], 1, s[46:47]
	v_lshl_add_u64 v[72:73], v[66:67], 0, v[0:1]
	global_load_dwordx4 v[66:69], v[72:73], off
	s_lshl_b32 s100, s26, 5
	v_add_co_u32_e32 v178, vcc, s100, v72
	s_nop 1
	v_addc_co_u32_e32 v179, vcc, 0, v73, vcc
	global_load_dwordx4 v[204:207], v[72:73], off offset:256
	global_load_dwordx4 v[208:211], v[178:179], off
	global_load_dwordx4 v[212:215], v[178:179], off offset:256
	v_ashrrev_i32_e32 v71, 31, v70
	s_waitcnt vmcnt(0)
	v_lshlrev_b32_e32 v74, 16, v66
	v_and_b32_e32 v75, 0xffff0000, v66
	v_lshlrev_b32_e32 v66, 16, v67
	v_and_b32_e32 v67, 0xffff0000, v67
	v_pk_mul_f32 v[64:65], v[64:65], v[66:67]
	v_lshlrev_b32_e32 v66, 16, v68
	v_and_b32_e32 v67, 0xffff0000, v68
	v_pk_mul_f32 v[62:63], v[62:63], v[74:75]
	v_pk_mul_f32 v[66:67], v[58:59], v[66:67]
	v_lshlrev_b32_e32 v58, 16, v69
	v_and_b32_e32 v59, 0xffff0000, v69
	v_pk_mul_f32 v[68:69], v[60:61], v[58:59]
	v_cvt_pk_bf16_f32 v58, v62, v63
	v_lshlrev_b64 v[62:63], 11, v[70:71]
	v_lshl_add_u64 v[62:63], s[4:5], 0, v[62:63]
	v_cvt_pk_bf16_f32 v59, v64, v65
	v_cvt_pk_bf16_f32 v60, v66, v67
	v_cvt_pk_bf16_f32 v61, v68, v69
	v_lshl_add_u64 v[62:63], v[62:63], 0, v[0:1]
	global_store_dwordx4 v[62:63], v[58:61], off
	s_nop 1
	v_mov_b32_e32 v58, v204
	v_mov_b32_e32 v59, v205
	v_mov_b32_e32 v60, v206
	v_mov_b32_e32 v61, v207
	v_lshlrev_b32_e32 v64, 16, v58
	v_and_b32_e32 v65, 0xffff0000, v58
	v_lshlrev_b32_e32 v58, 16, v59
	v_and_b32_e32 v59, 0xffff0000, v59
	v_pk_mul_f32 v[56:57], v[56:57], v[58:59]
	v_lshlrev_b32_e32 v58, 16, v60
	v_and_b32_e32 v59, 0xffff0000, v60
	v_pk_mul_f32 v[58:59], v[50:51], v[58:59]
	v_lshlrev_b32_e32 v50, 16, v61
	v_and_b32_e32 v51, 0xffff0000, v61
	v_pk_mul_f32 v[54:55], v[54:55], v[64:65]
	v_pk_mul_f32 v[60:61], v[52:53], v[50:51]
	v_cvt_pk_bf16_f32 v50, v54, v55
	v_cvt_pk_bf16_f32 v51, v56, v57
	v_cvt_pk_bf16_f32 v52, v58, v59
	v_cvt_pk_bf16_f32 v53, v60, v61
	v_add_u32_e32 v54, 0x90, v130
	global_store_dwordx4 v[62:63], v[50:53], off offset:256
	v_ashrrev_i32_e32 v55, 31, v54
	s_nop 0
	v_mad_i64_i32 v[50:51], s[0:1], s26, v54, 0
	v_lshl_add_u64 v[50:51], v[50:51], 1, s[46:47]
; DI unsigned cvt_pk_bf16(float lo, float hi) { f32x2_t v = {lo, hi}; bf16x2_t b = __builtin_convertvector(v, bf16x2_t); return __builtin_bit_cast(unsigned, b); }
; DI float bflo(unsigned u) { return __uint_as_float(u << 16); }
; DI float bfhi(unsigned u) { return __uint_as_float(u & 0xffff0000u); }
; template <bool ADD>
; DI void gated_tile(acc_t& acc, bf16_t* Y, int ldy, const bf16_t* Gt, int ldg) {
;   epi_foreach(acc, [&](int r, int c, f32x4& v0, f32x4& v1) {
;     const u32x4 g = *(const u32x4*)(Gt + (size_t)r * ldg + c);
;     float o[8];
;     o[0] = bflo(g[0]) * v0[0]; o[1] = bfhi(g[0]) * v0[1]; o[2] = bflo(g[1]) * v0[2]; o[3] = bfhi(g[1]) * v0[3];
;     o[4] = bflo(g[2]) * v1[0]; o[5] = bfhi(g[2]) * v1[1]; o[6] = bflo(g[3]) * v1[2]; o[7] = bfhi(g[3]) * v1[3];
;     bf16_t* py = Y + (size_t)r * ldy + c;
;     if (ADD) {
;       const u32x4 y0 = *(const u32x4*)py;
; #pragma unroll
;       for (int j = 0; j < 4; ++j) { o[2 * j] += bflo(y0[j]); o[2 * j + 1] += bfhi(y0[j]); }
;     }
;     u32x4 pk;
; #pragma unroll
;     for (int j = 0; j < 4; ++j) pk[j] = cvt_pk_bf16(o[2 * j], o[2 * j + 1]);
;     *(u32x4*)py = pk;
	v_lshl_add_u64 v[56:57], v[50:51], 0, v[0:1]
	s_nop 1
	v_mov_b32_e32 v50, v208
	v_mov_b32_e32 v51, v209
	v_mov_b32_e32 v52, v210
	v_mov_b32_e32 v53, v211
	v_lshlrev_b32_e32 v58, 16, v50
	v_and_b32_e32 v59, 0xffff0000, v50
	v_lshlrev_b32_e32 v50, 16, v51
	v_and_b32_e32 v51, 0xffff0000, v51
	v_pk_mul_f32 v[48:49], v[48:49], v[50:51]
	v_lshlrev_b32_e32 v50, 16, v52
	v_and_b32_e32 v51, 0xffff0000, v52
	v_pk_mul_f32 v[46:47], v[46:47], v[58:59]
	v_pk_mul_f32 v[50:51], v[42:43], v[50:51]
	v_lshlrev_b32_e32 v42, 16, v53
	v_and_b32_e32 v43, 0xffff0000, v53
	v_pk_mul_f32 v[52:53], v[44:45], v[42:43]
	v_cvt_pk_bf16_f32 v42, v46, v47
	v_lshlrev_b64 v[46:47], 11, v[54:55]
	v_lshl_add_u64 v[46:47], s[4:5], 0, v[46:47]
	v_cvt_pk_bf16_f32 v43, v48, v49
	v_cvt_pk_bf16_f32 v44, v50, v51
	v_cvt_pk_bf16_f32 v45, v52, v53
	v_lshl_add_u64 v[46:47], v[46:47], 0, v[0:1]
	global_store_dwordx4 v[46:47], v[42:45], off
	s_nop 1
	v_mov_b32_e32 v42, v212
	v_mov_b32_e32 v43, v213
	v_mov_b32_e32 v44, v214
	v_mov_b32_e32 v45, v215
	v_lshlrev_b32_e32 v48, 16, v42
	v_and_b32_e32 v49, 0xffff0000, v42
	v_lshlrev_b32_e32 v42, 16, v43
	v_and_b32_e32 v43, 0xffff0000, v43
	v_pk_mul_f32 v[40:41], v[40:41], v[42:43]
	v_lshlrev_b32_e32 v42, 16, v44
	v_and_b32_e32 v43, 0xffff0000, v44
	v_pk_mul_f32 v[42:43], v[34:35], v[42:43]
	v_lshlrev_b32_e32 v34, 16, v45
	v_and_b32_e32 v35, 0xffff0000, v45
	v_pk_mul_f32 v[38:39], v[38:39], v[48:49]
	v_pk_mul_f32 v[44:45], v[36:37], v[34:35]
	v_cvt_pk_bf16_f32 v34, v38, v39
	v_cvt_pk_bf16_f32 v35, v40, v41
	v_cvt_pk_bf16_f32 v36, v42, v43
	v_cvt_pk_bf16_f32 v37, v44, v45
	v_add_u32_e32 v38, 0xa0, v130
	global_store_dwordx4 v[46:47], v[34:37], off offset:256
	v_ashrrev_i32_e32 v39, 31, v38
	s_nop 0
	v_mad_i64_i32 v[34:35], s[0:1], s26, v38, 0
	v_lshl_add_u64 v[34:35], v[34:35], 1, s[46:47]
	v_lshl_add_u64 v[40:41], v[34:35], 0, v[0:1]
	global_load_dwordx4 v[34:37], v[40:41], off
	s_lshl_b32 s100, s26, 5
	v_add_co_u32_e32 v178, vcc, s100, v40
	s_nop 1
	v_addc_co_u32_e32 v179, vcc, 0, v41, vcc
	global_load_dwordx4 v[204:207], v[40:41], off offset:256
	global_load_dwordx4 v[208:211], v[178:179], off
	global_load_dwordx4 v[212:215], v[178:179], off offset:256
	s_waitcnt vmcnt(0)
	v_lshlrev_b32_e32 v42, 16, v34
	v_and_b32_e32 v43, 0xffff0000, v34
	v_lshlrev_b32_e32 v34, 16, v35
	v_and_b32_e32 v35, 0xffff0000, v35
	v_pk_mul_f32 v[32:33], v[32:33], v[34:35]
	v_lshlrev_b32_e32 v34, 16, v36
	v_and_b32_e32 v35, 0xffff0000, v36
	v_pk_mul_f32 v[30:31], v[30:31], v[42:43]
	v_pk_mul_f32 v[34:35], v[26:27], v[34:35]
	v_lshlrev_b32_e32 v26, 16, v37
	v_and_b32_e32 v27, 0xffff0000, v37
	v_pk_mul_f32 v[36:37], v[28:29], v[26:27]
	v_cvt_pk_bf16_f32 v26, v30, v31
	v_lshlrev_b64 v[30:31], 11, v[38:39]
	v_lshl_add_u64 v[30:31], s[4:5], 0, v[30:31]
	v_cvt_pk_bf16_f32 v27, v32, v33
	v_cvt_pk_bf16_f32 v28, v34, v35
	v_cvt_pk_bf16_f32 v29, v36, v37
	v_lshl_add_u64 v[30:31], v[30:31], 0, v[0:1]
	global_store_dwordx4 v[30:31], v[26:29], off
	s_nop 1
	v_mov_b32_e32 v26, v204
	v_mov_b32_e32 v27, v205
	v_mov_b32_e32 v28, v206
	v_mov_b32_e32 v29, v207
	v_lshlrev_b32_e32 v32, 16, v26
	v_and_b32_e32 v33, 0xffff0000, v26
	v_lshlrev_b32_e32 v26, 16, v27
	v_and_b32_e32 v27, 0xffff0000, v27
	v_pk_mul_f32 v[24:25], v[24:25], v[26:27]
	v_lshlrev_b32_e32 v26, 16, v28
	v_and_b32_e32 v27, 0xffff0000, v28
	v_pk_mul_f32 v[26:27], v[18:19], v[26:27]
	v_lshlrev_b32_e32 v18, 16, v29
	v_and_b32_e32 v19, 0xffff0000, v29
	v_pk_mul_f32 v[22:23], v[22:23], v[32:33]
	v_pk_mul_f32 v[28:29], v[20:21], v[18:19]
	v_cvt_pk_bf16_f32 v18, v22, v23
	v_cvt_pk_bf16_f32 v19, v24, v25
	v_cvt_pk_bf16_f32 v20, v26, v27
	v_cvt_pk_bf16_f32 v21, v28, v29
	v_add_u32_e32 v22, 0xb0, v130
	global_store_dwordx4 v[30:31], v[18:21], off offset:256
	v_ashrrev_i32_e32 v23, 31, v22
	s_nop 0
	v_mad_i64_i32 v[18:19], s[0:1], s26, v22, 0
	v_lshl_add_u64 v[18:19], v[18:19], 1, s[46:47]
	v_lshl_add_u64 v[24:25], v[18:19], 0, v[0:1]
	s_nop 1
	v_mov_b32_e32 v18, v208
	v_mov_b32_e32 v19, v209
	v_mov_b32_e32 v20, v210
	v_mov_b32_e32 v21, v211
	v_lshlrev_b32_e32 v26, 16, v18
	v_and_b32_e32 v27, 0xffff0000, v18
	v_lshlrev_b32_e32 v18, 16, v19
	v_and_b32_e32 v19, 0xffff0000, v19
	v_pk_mul_f32 v[16:17], v[16:17], v[18:19]
	v_lshlrev_b32_e32 v18, 16, v20
	v_and_b32_e32 v19, 0xffff0000, v20
	v_pk_mul_f32 v[14:15], v[14:15], v[26:27]
	v_pk_mul_f32 v[18:19], v[10:11], v[18:19]
	v_lshlrev_b32_e32 v10, 16, v21
	v_and_b32_e32 v11, 0xffff0000, v21
	v_pk_mul_f32 v[20:21], v[12:13], v[10:11]
	v_cvt_pk_bf16_f32 v10, v14, v15
	v_lshlrev_b64 v[14:15], 11, v[22:23]
	v_lshl_add_u64 v[14:15], s[4:5], 0, v[14:15]
	v_cvt_pk_bf16_f32 v11, v16, v17
	v_cvt_pk_bf16_f32 v12, v18, v19
	v_cvt_pk_bf16_f32 v13, v20, v21
	v_lshl_add_u64 v[14:15], v[14:15], 0, v[0:1]
	global_store_dwordx4 v[14:15], v[10:13], off
	s_nop 1
	v_mov_b32_e32 v10, v212
	v_mov_b32_e32 v11, v213
	v_mov_b32_e32 v12, v214
	v_mov_b32_e32 v13, v215
	v_lshlrev_b32_e32 v16, 16, v10
	v_and_b32_e32 v17, 0xffff0000, v10
	v_lshlrev_b32_e32 v10, 16, v11
	v_and_b32_e32 v11, 0xffff0000, v11
	v_pk_mul_f32 v[8:9], v[8:9], v[10:11]
	v_lshlrev_b32_e32 v10, 16, v12
	v_and_b32_e32 v11, 0xffff0000, v12
	v_pk_mul_f32 v[10:11], v[2:3], v[10:11]
	v_lshlrev_b32_e32 v2, 16, v13
	v_and_b32_e32 v3, 0xffff0000, v13
	v_pk_mul_f32 v[6:7], v[6:7], v[16:17]
	v_pk_mul_f32 v[12:13], v[4:5], v[2:3]
	v_cvt_pk_bf16_f32 v2, v6, v7
	v_cvt_pk_bf16_f32 v3, v8, v9
	v_cvt_pk_bf16_f32 v4, v10, v11
	v_cvt_pk_bf16_f32 v5, v12, v13
	global_store_dwordx4 v[14:15], v[2:5], off offset:256
	s_branch .LBB0_1265

; #define STG_A(P, ptr) do { const bf16_t* _g = (ptr); \
;     __builtin_amdgcn_global_load_lds((const unsigned*)(_g + oa0), (__attribute__((address_space(3))) unsigned*)((P) + tb0), 16, 0, 0); \
;     __builtin_amdgcn_global_load_lds((const unsigned*)(_g + (size_t)64 * lda + oa0), (__attribute__((address_space(3))) unsigned*)((P) + tb1), 16, 0, 0); } while (0)
; #define STG_B(P, ptr) do { const bf16_t* _g = (ptr); \
;     __builtin_amdgcn_global_load_lds((const unsigned*)(_g + ob0), (__attribute__((address_space(3))) unsigned*)((P) + tb0), 16, 0, 0); \
;     __builtin_amdgcn_global_load_lds((const unsigned*)(_g + (size_t)64 * ldb + ob0), (__attribute__((address_space(3))) unsigned*)((P) + tb1), 16, 0, 0); } while (0)
; #define LDA(dst, b, h) _Pragma("unroll") for (int m = 0; m < 4; ++m) _Pragma("unroll") for (int k = 0; k < 2; ++k) \
;     dst[m][k] = *reinterpret_cast<const bf16x8*>(SA(b, h) + lds_byte(wr * 64 + m * 16 + fr, k * 32 + fq * 8))
; #define LDB(dst, b, h) _Pragma("unroll") for (int n = 0; n < 2; ++n) _Pragma("unroll") for (int k = 0; k < 2; ++k) \
;     dst[n][k] = *reinterpret_cast<const bf16x8*>(SB(b, h) + lds_byte(wc * 32 + n * 16 + fr, k * 32 + fq * 8))
; #define MMA(ai, bj, At_, Bt_) do { __builtin_amdgcn_s_setprio(1); \
;     _Pragma("unroll") for (int m = 0; m < 4; ++m) _Pragma("unroll") for (int n = 0; n < 2; ++n) _Pragma("unroll") for (int k = 0; k < 2; ++k) \
;       acc[ai][bj][m][n] = __builtin_amdgcn_mfma_f32_16x16x32_bf16(Bt_[n][k], At_[m][k], acc[ai][bj][m][n], 0, 0, 0); \
;     __builtin_amdgcn_s_setprio(0); } while (0)
; #define WAIT_L(n) asm volatile("s_waitcnt lgkmcnt(" #n ")" ::: "memory")
; template <int lda, int ldb, int K, class Gen, class Epi>
; DI void gemm_stream(Gen gen, Epi epi) {
;     ...
;     for (int t = 0; t < nt; t += 2) {
;       const bool wrap = (t + 2 >= nt);
;       const bf16_t* a1 = A + (t + 1) * 64;
;       const bf16_t* a2 = wrap ? An : A + (t + 2) * 64;
;       const bf16_t* b2 = wrap ? Bn : Bt + (t + 2) * 64;
;       LDB(B0, 0, 0); SCHED; LDA(At, 0, 0); STG_A(SA(1, 1), a1 + (size_t)128 * lda);
;       WAIT_L(8); BAR; WAIT_L(0); MMA(0, 0, At, B0); BAR; SCHED;
;       LDB(B1, 0, 1); STG_B(SB(0, 0), b2);
;       BAR; WAIT_L(0); MMA(0, 1, At, B1); BAR;
;       LDA(At, 0, 1); STG_A(SA(0, 0), a2);
;       BAR; WAIT_L(0); MMA(1, 0, At, B0); BAR; SCHED;
;       STG_B(SB(0, 1), b2 + (size_t)128 * ldb);
.LBB0_1282:
	s_add_i32 s47, s47, 2
	ds_read_b128 v[130:133], v166
	ds_read_b128 v[134:137], v166 offset:1024
	ds_read_b128 v[144:147], v166 offset:2048
	ds_read_b128 v[174:177], v166 offset:3072
	s_add_u32 s26, s4, 0x100
	s_addc_u32 s27, s5, 0
	s_cmp_gt_u32 s47, 5
	s_cselect_b64 s[0:1], -1, 0
	s_and_b64 vcc, s[0:1], exec
	s_cselect_b32 s0, s33, s27
	s_cselect_b32 s1, s44, s26
	v_mov_b32_e32 v152, s1
	v_mov_b32_e32 v153, s0
	v_add_u32_e32 v0, 0xc000, v155
	v_lshl_add_u64 v[224:225], s[4:5], 0, v[142:143]
	v_readfirstlane_b32 s0, v0
	v_add_u32_e32 v0, 0xe000, v155
	v_lshl_add_u64 v[226:227], v[224:225], 0, s[10:11]
	s_mov_b32 m0, s0
	v_readfirstlane_b32 s0, v0
	ds_read_b128 v[178:181], v167
	ds_read_b128 v[182:185], v167 offset:1024
	ds_read_b128 v[186:189], v168
	ds_read_b128 v[204:207], v168 offset:1024
	ds_read_b128 v[208:211], v169
	ds_read_b128 v[212:215], v169 offset:1024
	ds_read_b128 v[216:219], v170
	ds_read_b128 v[220:223], v170 offset:1024
	global_load_lds_dwordx4 v[226:227], off
	v_lshl_add_u64 v[224:225], v[224:225], 0, s[28:29]
	s_mov_b32 m0, s0
	s_nop 0
	global_load_lds_dwordx4 v[224:225], off
	s_waitcnt lgkmcnt(8)
	s_barrier
	s_waitcnt lgkmcnt(0)
	s_setprio 1
	s_waitcnt lgkmcnt(0)
	v_mfma_f32_16x16x32_bf16 v[126:129], v[130:133], v[178:181], v[126:129]
	v_mfma_f32_16x16x32_bf16 v[122:125], v[144:147], v[178:181], v[122:125]
	v_mfma_f32_16x16x32_bf16 v[110:113], v[130:133], v[186:189], v[110:113]
	v_mfma_f32_16x16x32_bf16 v[106:109], v[144:147], v[186:189], v[106:109]
	v_mfma_f32_16x16x32_bf16 v[94:97], v[130:133], v[208:211], v[94:97]
	v_mfma_f32_16x16x32_bf16 v[90:93], v[144:147], v[208:211], v[90:93]
	v_mfma_f32_16x16x32_bf16 v[78:81], v[130:133], v[216:219], v[78:81]
	v_mfma_f32_16x16x32_bf16 v[74:77], v[144:147], v[216:219], v[74:77]
	v_mfma_f32_16x16x32_bf16 v[126:129], v[134:137], v[182:185], v[126:129]
	v_mfma_f32_16x16x32_bf16 v[122:125], v[174:177], v[182:185], v[122:125]
	v_mfma_f32_16x16x32_bf16 v[110:113], v[134:137], v[204:207], v[110:113]
	v_mfma_f32_16x16x32_bf16 v[106:109], v[174:177], v[204:207], v[106:109]
	v_mfma_f32_16x16x32_bf16 v[94:97], v[134:137], v[212:215], v[94:97]
	v_mfma_f32_16x16x32_bf16 v[90:93], v[174:177], v[212:215], v[90:93]
	v_mfma_f32_16x16x32_bf16 v[78:81], v[134:137], v[220:223], v[78:81]
	v_mfma_f32_16x16x32_bf16 v[74:77], v[174:177], v[220:223], v[74:77]
	s_setprio 0
	s_barrier
	s_cselect_b32 s0, s19, s46
	s_cselect_b32 s1, s30, s45
	v_mov_b32_e32 v244, s1
	v_mov_b32_e32 v245, s0
	v_readfirstlane_b32 s0, v154
	v_add_u32_e32 v0, 0x2000, v154
	v_lshl_add_u64 v[244:245], v[140:141], 1, v[244:245]
	s_mov_b32 m0, s0
	v_readfirstlane_b32 s0, v0
	ds_read_b128 v[224:227], v171
	ds_read_b128 v[228:231], v171 offset:1024
	ds_read_b128 v[232:235], v171 offset:2048
	ds_read_b128 v[240:243], v171 offset:3072
	global_load_lds_dwordx4 v[244:245], off
	v_lshl_add_u64 v[246:247], v[244:245], 0, s[14:15]
	s_mov_b32 m0, s0
	s_nop 0
	global_load_lds_dwordx4 v[246:247], off
	s_barrier
	s_waitcnt lgkmcnt(0)
	s_setprio 1
	s_waitcnt lgkmcnt(0)
	v_mfma_f32_16x16x32_bf16 v[118:121], v[224:227], v[178:181], v[118:121]
	v_mfma_f32_16x16x32_bf16 v[114:117], v[232:235], v[178:181], v[114:117]
	v_mfma_f32_16x16x32_bf16 v[102:105], v[224:227], v[186:189], v[102:105]
	v_mfma_f32_16x16x32_bf16 v[98:101], v[232:235], v[186:189], v[98:101]
	v_mfma_f32_16x16x32_bf16 v[86:89], v[224:227], v[208:211], v[86:89]
	v_mfma_f32_16x16x32_bf16 v[82:85], v[232:235], v[208:211], v[82:85]
	v_mfma_f32_16x16x32_bf16 v[70:73], v[224:227], v[216:219], v[70:73]
	v_mfma_f32_16x16x32_bf16 v[66:69], v[232:235], v[216:219], v[66:69]
	v_mfma_f32_16x16x32_bf16 v[118:121], v[228:231], v[182:185], v[118:121]
	v_mfma_f32_16x16x32_bf16 v[114:117], v[240:243], v[182:185], v[114:117]
	v_mfma_f32_16x16x32_bf16 v[102:105], v[228:231], v[204:207], v[102:105]
	v_mfma_f32_16x16x32_bf16 v[98:101], v[240:243], v[204:207], v[98:101]
	v_mfma_f32_16x16x32_bf16 v[86:89], v[228:231], v[212:215], v[86:89]
	v_mfma_f32_16x16x32_bf16 v[82:85], v[240:243], v[212:215], v[82:85]
	v_mfma_f32_16x16x32_bf16 v[70:73], v[228:231], v[220:223], v[70:73]
	v_mfma_f32_16x16x32_bf16 v[66:69], v[240:243], v[220:223], v[66:69]
	s_setprio 0
	v_readfirstlane_b32 s0, v155
	v_lshl_add_u64 v[152:153], v[138:139], 1, v[152:153]
	s_mov_b32 m0, s0
	v_readfirstlane_b32 s0, v156
	s_barrier
	ds_read_b128 v[178:181], v167 offset:16384
	ds_read_b128 v[182:185], v167 offset:17408
	ds_read_b128 v[186:189], v168 offset:16384
	ds_read_b128 v[204:207], v168 offset:17408
	ds_read_b128 v[208:211], v169 offset:16384
	ds_read_b128 v[212:215], v169 offset:17408
	ds_read_b128 v[216:219], v170 offset:16384
	ds_read_b128 v[220:223], v170 offset:17408
	global_load_lds_dwordx4 v[152:153], off
	v_lshl_add_u64 v[246:247], v[152:153], 0, s[14:15]
	s_mov_b32 m0, s0
	s_nop 0
	global_load_lds_dwordx4 v[246:247], off
	s_barrier
	s_waitcnt lgkmcnt(0)
	s_setprio 1
	s_waitcnt lgkmcnt(0)
	v_mfma_f32_16x16x32_bf16 v[62:65], v[130:133], v[178:181], v[62:65]
	v_mfma_f32_16x16x32_bf16 v[58:61], v[144:147], v[178:181], v[58:61]
	v_mfma_f32_16x16x32_bf16 v[46:49], v[130:133], v[186:189], v[46:49]
	v_mfma_f32_16x16x32_bf16 v[42:45], v[144:147], v[186:189], v[42:45]
	v_mfma_f32_16x16x32_bf16 v[30:33], v[130:133], v[208:211], v[30:33]
	v_mfma_f32_16x16x32_bf16 v[26:29], v[144:147], v[208:211], v[26:29]
	v_mfma_f32_16x16x32_bf16 v[14:17], v[130:133], v[216:219], v[14:17]
	v_mfma_f32_16x16x32_bf16 v[10:13], v[144:147], v[216:219], v[10:13]
	v_mfma_f32_16x16x32_bf16 v[62:65], v[134:137], v[182:185], v[62:65]
	v_mfma_f32_16x16x32_bf16 v[58:61], v[174:177], v[182:185], v[58:61]
	v_mfma_f32_16x16x32_bf16 v[46:49], v[134:137], v[204:207], v[46:49]
	v_mfma_f32_16x16x32_bf16 v[42:45], v[174:177], v[204:207], v[42:45]
	v_mfma_f32_16x16x32_bf16 v[30:33], v[134:137], v[212:215], v[30:33]
	v_mfma_f32_16x16x32_bf16 v[26:29], v[174:177], v[212:215], v[26:29]
	v_mfma_f32_16x16x32_bf16 v[14:17], v[134:137], v[220:223], v[14:17]
	v_mfma_f32_16x16x32_bf16 v[10:13], v[174:177], v[220:223], v[10:13]
	s_setprio 0
	s_barrier
; #define STG_A(P, ptr) do { const bf16_t* _g = (ptr); \
;     __builtin_amdgcn_global_load_lds((const unsigned*)(_g + oa0), (__attribute__((address_space(3))) unsigned*)((P) + tb0), 16, 0, 0); \
;     __builtin_amdgcn_global_load_lds((const unsigned*)(_g + (size_t)64 * lda + oa0), (__attribute__((address_space(3))) unsigned*)((P) + tb1), 16, 0, 0); } while (0)
; #define STG_B(P, ptr) do { const bf16_t* _g = (ptr); \
;     __builtin_amdgcn_global_load_lds((const unsigned*)(_g + ob0), (__attribute__((address_space(3))) unsigned*)((P) + tb0), 16, 0, 0); \
;     __builtin_amdgcn_global_load_lds((const unsigned*)(_g + (size_t)64 * ldb + ob0), (__attribute__((address_space(3))) unsigned*)((P) + tb1), 16, 0, 0); } while (0)
; #define LDA(dst, b, h) _Pragma("unroll") for (int m = 0; m < 4; ++m) _Pragma("unroll") for (int k = 0; k < 2; ++k) \
;     dst[m][k] = *reinterpret_cast<const bf16x8*>(SA(b, h) + lds_byte(wr * 64 + m * 16 + fr, k * 32 + fq * 8))
; #define LDB(dst, b, h) _Pragma("unroll") for (int n = 0; n < 2; ++n) _Pragma("unroll") for (int k = 0; k < 2; ++k) \
;     dst[n][k] = *reinterpret_cast<const bf16x8*>(SB(b, h) + lds_byte(wc * 32 + n * 16 + fr, k * 32 + fq * 8))
; #define MMA(ai, bj, At_, Bt_) do { __builtin_amdgcn_s_setprio(1); \
;     _Pragma("unroll") for (int m = 0; m < 4; ++m) _Pragma("unroll") for (int n = 0; n < 2; ++n) _Pragma("unroll") for (int k = 0; k < 2; ++k) \
;       acc[ai][bj][m][n] = __builtin_amdgcn_mfma_f32_16x16x32_bf16(Bt_[n][k], At_[m][k], acc[ai][bj][m][n], 0, 0, 0); \
;     __builtin_amdgcn_s_setprio(0); } while (0)
; #define WAIT_V(n) asm volatile("s_waitcnt vmcnt(" #n ")" ::: "memory")
; #define WAIT_L(n) asm volatile("s_waitcnt lgkmcnt(" #n ")" ::: "memory")
; #define BAR __builtin_amdgcn_s_barrier()
; #define SCHED __builtin_amdgcn_sched_barrier(0)
; template <int lda, int ldb, int K, class Gen, class Epi>
; DI void gemm_stream(Gen gen, Epi epi) {
;     ...
;       STG_B(SB(0, 1), b2 + (size_t)128 * ldb);
;       WAIT_V(6); BAR; MMA(1, 1, At, B1); BAR;
;       LDB(B0, 1, 0); SCHED; LDA(At, 1, 0); STG_A(SA(0, 1), a2 + (size_t)128 * lda);
;       WAIT_L(8); BAR; WAIT_L(0); MMA(0, 0, At, B0); BAR; SCHED;
;       LDB(B1, 1, 1); STG_B(SB(1, 0), b2 + 64);
;       BAR; WAIT_L(0); MMA(0, 1, At, B1); BAR;
;       LDA(At, 1, 1); STG_A(SA(1, 0), a2 + 64);
;       BAR; WAIT_L(0); MMA(1, 0, At, B0); BAR; SCHED;
	v_readfirstlane_b32 s0, v157
	v_add_u32_e32 v0, 0x2000, v157
	v_lshl_add_u64 v[130:131], v[244:245], 0, s[24:25]
	s_mov_b32 m0, s0
	v_readfirstlane_b32 s0, v0
	global_load_lds_dwordx4 v[130:131], off
	v_lshl_add_u64 v[130:131], v[244:245], 0, s[16:17]
	s_mov_b32 m0, s0
	s_nop 0
	global_load_lds_dwordx4 v[130:131], off
	s_waitcnt vmcnt(6)
	s_barrier
	s_setprio 1
	v_mfma_f32_16x16x32_bf16 v[54:57], v[224:227], v[178:181], v[54:57]
	v_mfma_f32_16x16x32_bf16 v[50:53], v[232:235], v[178:181], v[50:53]
	v_mfma_f32_16x16x32_bf16 v[38:41], v[224:227], v[186:189], v[38:41]
	v_mfma_f32_16x16x32_bf16 v[34:37], v[232:235], v[186:189], v[34:37]
	v_mfma_f32_16x16x32_bf16 v[22:25], v[224:227], v[208:211], v[22:25]
	v_mfma_f32_16x16x32_bf16 v[18:21], v[232:235], v[208:211], v[18:21]
	v_mfma_f32_16x16x32_bf16 v[6:9], v[224:227], v[216:219], v[6:9]
	v_mfma_f32_16x16x32_bf16 v[2:5], v[232:235], v[216:219], v[2:5]
	v_mfma_f32_16x16x32_bf16 v[54:57], v[228:231], v[182:185], v[54:57]
	v_mfma_f32_16x16x32_bf16 v[50:53], v[240:243], v[182:185], v[50:53]
	v_mfma_f32_16x16x32_bf16 v[38:41], v[228:231], v[204:207], v[38:41]
	v_mfma_f32_16x16x32_bf16 v[34:37], v[240:243], v[204:207], v[34:37]
	v_mfma_f32_16x16x32_bf16 v[22:25], v[228:231], v[212:215], v[22:25]
	v_mfma_f32_16x16x32_bf16 v[18:21], v[240:243], v[212:215], v[18:21]
	v_mfma_f32_16x16x32_bf16 v[6:9], v[228:231], v[220:223], v[6:9]
	v_mfma_f32_16x16x32_bf16 v[2:5], v[240:243], v[220:223], v[2:5]
	s_setprio 0
	s_barrier
	ds_read_b128 v[130:133], v172
	ds_read_b128 v[134:137], v172 offset:1024
	ds_read_b128 v[144:147], v172 offset:2048
	ds_read_b128 v[174:177], v172 offset:3072
	v_readfirstlane_b32 s0, v158
	v_lshl_add_u64 v[224:225], v[152:153], 0, s[24:25]
	s_mov_b32 m0, s0
	v_readfirstlane_b32 s0, v159
	ds_read_b128 v[178:181], v167 offset:32768
	ds_read_b128 v[182:185], v167 offset:33792
	ds_read_b128 v[186:189], v168 offset:32768
	ds_read_b128 v[204:207], v168 offset:33792
	ds_read_b128 v[208:211], v169 offset:32768
	ds_read_b128 v[212:215], v169 offset:33792
	ds_read_b128 v[216:219], v170 offset:32768
	ds_read_b128 v[220:223], v170 offset:33792
	global_load_lds_dwordx4 v[224:225], off
	v_lshl_add_u64 v[224:225], v[152:153], 0, s[16:17]
	s_mov_b32 m0, s0
	s_nop 0
	global_load_lds_dwordx4 v[224:225], off
	s_waitcnt lgkmcnt(8)
	s_barrier
	s_waitcnt lgkmcnt(0)
	s_setprio 1
	s_waitcnt lgkmcnt(0)
	v_mfma_f32_16x16x32_bf16 v[126:129], v[130:133], v[178:181], v[126:129]
	v_mfma_f32_16x16x32_bf16 v[122:125], v[144:147], v[178:181], v[122:125]
	v_mfma_f32_16x16x32_bf16 v[110:113], v[130:133], v[186:189], v[110:113]
	v_mfma_f32_16x16x32_bf16 v[106:109], v[144:147], v[186:189], v[106:109]
	v_mfma_f32_16x16x32_bf16 v[94:97], v[130:133], v[208:211], v[94:97]
	v_mfma_f32_16x16x32_bf16 v[90:93], v[144:147], v[208:211], v[90:93]
	v_mfma_f32_16x16x32_bf16 v[78:81], v[130:133], v[216:219], v[78:81]
	v_mfma_f32_16x16x32_bf16 v[74:77], v[144:147], v[216:219], v[74:77]
	v_mfma_f32_16x16x32_bf16 v[126:129], v[134:137], v[182:185], v[126:129]
	v_mfma_f32_16x16x32_bf16 v[122:125], v[174:177], v[182:185], v[122:125]
	v_mfma_f32_16x16x32_bf16 v[110:113], v[134:137], v[204:207], v[110:113]
	v_mfma_f32_16x16x32_bf16 v[106:109], v[174:177], v[204:207], v[106:109]
	v_mfma_f32_16x16x32_bf16 v[94:97], v[134:137], v[212:215], v[94:97]
	v_mfma_f32_16x16x32_bf16 v[90:93], v[174:177], v[212:215], v[90:93]
	v_mfma_f32_16x16x32_bf16 v[78:81], v[134:137], v[220:223], v[78:81]
	v_mfma_f32_16x16x32_bf16 v[74:77], v[174:177], v[220:223], v[74:77]
	s_setprio 0
	s_barrier
	v_readfirstlane_b32 s0, v160
	v_lshl_add_u64 v[246:247], v[244:245], 0, s[34:35]
	s_mov_b32 m0, s0
	v_readfirstlane_b32 s0, v161
	ds_read_b128 v[224:227], v173
	ds_read_b128 v[228:231], v173 offset:1024
	ds_read_b128 v[232:235], v173 offset:2048
	ds_read_b128 v[240:243], v173 offset:3072
	global_load_lds_dwordx4 v[246:247], off
	v_lshl_add_u64 v[246:247], v[244:245], 0, s[6:7]
	s_mov_b32 m0, s0
	s_nop 0
	global_load_lds_dwordx4 v[246:247], off
	s_barrier
	s_waitcnt lgkmcnt(0)
	s_setprio 1
	s_waitcnt lgkmcnt(0)
	v_mfma_f32_16x16x32_bf16 v[118:121], v[224:227], v[178:181], v[118:121]
	v_mfma_f32_16x16x32_bf16 v[114:117], v[232:235], v[178:181], v[114:117]
	v_mfma_f32_16x16x32_bf16 v[102:105], v[224:227], v[186:189], v[102:105]
	v_mfma_f32_16x16x32_bf16 v[98:101], v[232:235], v[186:189], v[98:101]
	v_mfma_f32_16x16x32_bf16 v[86:89], v[224:227], v[208:211], v[86:89]
	v_mfma_f32_16x16x32_bf16 v[82:85], v[232:235], v[208:211], v[82:85]
	v_mfma_f32_16x16x32_bf16 v[70:73], v[224:227], v[216:219], v[70:73]
	v_mfma_f32_16x16x32_bf16 v[66:69], v[232:235], v[216:219], v[66:69]
	v_mfma_f32_16x16x32_bf16 v[118:121], v[228:231], v[182:185], v[118:121]
	v_mfma_f32_16x16x32_bf16 v[114:117], v[240:243], v[182:185], v[114:117]
	v_mfma_f32_16x16x32_bf16 v[102:105], v[228:231], v[204:207], v[102:105]
	v_mfma_f32_16x16x32_bf16 v[98:101], v[240:243], v[204:207], v[98:101]
	v_mfma_f32_16x16x32_bf16 v[86:89], v[228:231], v[212:215], v[86:89]
	v_mfma_f32_16x16x32_bf16 v[82:85], v[240:243], v[212:215], v[82:85]
	v_mfma_f32_16x16x32_bf16 v[70:73], v[228:231], v[220:223], v[70:73]
	v_mfma_f32_16x16x32_bf16 v[66:69], v[240:243], v[220:223], v[66:69]
	s_setprio 0
	v_readfirstlane_b32 s0, v162
	v_lshl_add_u64 v[246:247], v[152:153], 0, s[34:35]
	s_mov_b32 m0, s0
	v_readfirstlane_b32 s0, v163
	s_barrier
	ds_read_b128 v[178:181], v167 offset:49152
	ds_read_b128 v[182:185], v167 offset:50176
	ds_read_b128 v[186:189], v168 offset:49152
	ds_read_b128 v[204:207], v168 offset:50176
	ds_read_b128 v[208:211], v169 offset:49152
	ds_read_b128 v[212:215], v169 offset:50176
	ds_read_b128 v[216:219], v170 offset:49152
	ds_read_b128 v[220:223], v170 offset:50176
	global_load_lds_dwordx4 v[246:247], off
	v_lshl_add_u64 v[152:153], v[152:153], 0, s[6:7]
	s_mov_b32 m0, s0
	s_nop 0
	global_load_lds_dwordx4 v[152:153], off
	s_barrier
; DI unsigned cvt_pk_bf16(float lo, float hi) { f32x2_t v = {lo, hi}; bf16x2_t b = __builtin_convertvector(v, bf16x2_t); return __builtin_bit_cast(unsigned, b); }
; DI float bflo(unsigned u) { return __uint_as_float(u << 16); }
; DI float bfhi(unsigned u) { return __uint_as_float(u & 0xffff0000u); }
; #define STG_B(P, ptr) do { const bf16_t* _g = (ptr); \
;     __builtin_amdgcn_global_load_lds((const unsigned*)(_g + ob0), (__attribute__((address_space(3))) unsigned*)((P) + tb0), 16, 0, 0); \
;     __builtin_amdgcn_global_load_lds((const unsigned*)(_g + (size_t)64 * ldb + ob0), (__attribute__((address_space(3))) unsigned*)((P) + tb1), 16, 0, 0); } while (0)
; #define MMA(ai, bj, At_, Bt_) do { __builtin_amdgcn_s_setprio(1); \
;     _Pragma("unroll") for (int m = 0; m < 4; ++m) _Pragma("unroll") for (int n = 0; n < 2; ++n) _Pragma("unroll") for (int k = 0; k < 2; ++k) \
;       acc[ai][bj][m][n] = __builtin_amdgcn_mfma_f32_16x16x32_bf16(Bt_[n][k], At_[m][k], acc[ai][bj][m][n], 0, 0, 0); \
;     __builtin_amdgcn_s_setprio(0); } while (0)
; #define WAIT_V(n) asm volatile("s_waitcnt vmcnt(" #n ")" ::: "memory")
; #define WAIT_L(n) asm volatile("s_waitcnt lgkmcnt(" #n ")" ::: "memory")
; #define BAR __builtin_amdgcn_s_barrier()
; template <int lda, int ldb, int K, class Gen, class Epi>
; DI void gemm_stream(Gen gen, Epi epi) {
;     ...
;       BAR; WAIT_L(0); MMA(1, 0, At, B0); BAR; SCHED;
;       STG_B(SB(1, 1), b2 + (size_t)128 * ldb + 64);
;       WAIT_V(6); BAR; MMA(1, 1, At, B1); BAR;
;     }
;     epi(i, acc);
; template <bool ADD>
; DI void gated_tile(acc_t& acc, bf16_t* Y, int ldy, const bf16_t* Gt, int ldg) {
;   epi_foreach(acc, [&](int r, int c, f32x4& v0, f32x4& v1) {
;     const u32x4 g = *(const u32x4*)(Gt + (size_t)r * ldg + c);
;     float o[8];
;     o[0] = bflo(g[0]) * v0[0]; o[1] = bfhi(g[0]) * v0[1]; o[2] = bflo(g[1]) * v0[2]; o[3] = bfhi(g[1]) * v0[3];
;     o[4] = bflo(g[2]) * v1[0]; o[5] = bfhi(g[2]) * v1[1]; o[6] = bflo(g[3]) * v1[2]; o[7] = bfhi(g[3]) * v1[3];
;     bf16_t* py = Y + (size_t)r * ldy + c;
;     if (ADD) {
;       const u32x4 y0 = *(const u32x4*)py;
; #pragma unroll
;       for (int j = 0; j < 4; ++j) { o[2 * j] += bflo(y0[j]); o[2 * j + 1] += bfhi(y0[j]); }
;     }
;     u32x4 pk;
; #pragma unroll
;     for (int j = 0; j < 4; ++j) pk[j] = cvt_pk_bf16(o[2 * j], o[2 * j + 1]);
;     *(u32x4*)py = pk;
	s_waitcnt lgkmcnt(0)
	s_setprio 1
	s_waitcnt lgkmcnt(0)
	v_mfma_f32_16x16x32_bf16 v[62:65], v[130:133], v[178:181], v[62:65]
	v_mfma_f32_16x16x32_bf16 v[58:61], v[144:147], v[178:181], v[58:61]
	v_mfma_f32_16x16x32_bf16 v[46:49], v[130:133], v[186:189], v[46:49]
	v_mfma_f32_16x16x32_bf16 v[42:45], v[144:147], v[186:189], v[42:45]
	v_mfma_f32_16x16x32_bf16 v[30:33], v[130:133], v[208:211], v[30:33]
	v_mfma_f32_16x16x32_bf16 v[26:29], v[144:147], v[208:211], v[26:29]
	v_mfma_f32_16x16x32_bf16 v[14:17], v[130:133], v[216:219], v[14:17]
	v_mfma_f32_16x16x32_bf16 v[10:13], v[144:147], v[216:219], v[10:13]
	v_mfma_f32_16x16x32_bf16 v[62:65], v[134:137], v[182:185], v[62:65]
	v_mfma_f32_16x16x32_bf16 v[58:61], v[174:177], v[182:185], v[58:61]
	v_mfma_f32_16x16x32_bf16 v[46:49], v[134:137], v[204:207], v[46:49]
	v_mfma_f32_16x16x32_bf16 v[42:45], v[174:177], v[204:207], v[42:45]
	v_mfma_f32_16x16x32_bf16 v[30:33], v[134:137], v[212:215], v[30:33]
	v_mfma_f32_16x16x32_bf16 v[26:29], v[174:177], v[212:215], v[26:29]
	v_mfma_f32_16x16x32_bf16 v[14:17], v[134:137], v[220:223], v[14:17]
	v_mfma_f32_16x16x32_bf16 v[10:13], v[174:177], v[220:223], v[10:13]
	s_setprio 0
	s_barrier
	v_readfirstlane_b32 s0, v164
	v_lshl_add_u64 v[130:131], v[244:245], 0, s[10:11]
	s_mov_b32 m0, s0
	v_readfirstlane_b32 s0, v165
	global_load_lds_dwordx4 v[130:131], off
	v_lshl_add_u64 v[130:131], v[244:245], 0, s[28:29]
	s_mov_b32 m0, s0
	s_nop 0
	global_load_lds_dwordx4 v[130:131], off
	s_waitcnt vmcnt(6)
	s_barrier
	s_setprio 1
	v_mfma_f32_16x16x32_bf16 v[54:57], v[224:227], v[178:181], v[54:57]
	v_mfma_f32_16x16x32_bf16 v[50:53], v[232:235], v[178:181], v[50:53]
	v_mfma_f32_16x16x32_bf16 v[38:41], v[224:227], v[186:189], v[38:41]
	v_mfma_f32_16x16x32_bf16 v[34:37], v[232:235], v[186:189], v[34:37]
	v_mfma_f32_16x16x32_bf16 v[22:25], v[224:227], v[208:211], v[22:25]
	v_mfma_f32_16x16x32_bf16 v[18:21], v[232:235], v[208:211], v[18:21]
	v_mfma_f32_16x16x32_bf16 v[6:9], v[224:227], v[216:219], v[6:9]
	v_mfma_f32_16x16x32_bf16 v[2:5], v[232:235], v[216:219], v[2:5]
	v_mfma_f32_16x16x32_bf16 v[54:57], v[228:231], v[182:185], v[54:57]
	v_mfma_f32_16x16x32_bf16 v[50:53], v[240:243], v[182:185], v[50:53]
	v_mfma_f32_16x16x32_bf16 v[38:41], v[228:231], v[204:207], v[38:41]
	v_mfma_f32_16x16x32_bf16 v[34:37], v[240:243], v[204:207], v[34:37]
	v_mfma_f32_16x16x32_bf16 v[22:25], v[228:231], v[212:215], v[22:25]
	v_mfma_f32_16x16x32_bf16 v[18:21], v[240:243], v[212:215], v[18:21]
	v_mfma_f32_16x16x32_bf16 v[6:9], v[228:231], v[220:223], v[6:9]
	v_mfma_f32_16x16x32_bf16 v[2:5], v[240:243], v[220:223], v[2:5]
	s_setprio 0
	s_add_u32 s45, s45, 0x100
	s_addc_u32 s46, s46, 0
	s_mov_b64 s[4:5], s[26:27]
	s_barrier
	s_cbranch_vccz .LBB0_1282
	s_andn2_b64 vcc, exec, s[42:43]
	s_mov_b64 s[4:5], -1
	s_cbranch_vccnz .LBB0_1285
	v_mov_b32_e32 v0, v149
	s_movk_i32 s0, 0xffc0
	v_and_b32_e32 v130, 15, v0
	v_ashrrev_i32_e32 v131, 2, v0
	v_and_or_b32 v144, v131, s0, v130
	v_ashrrev_i32_e32 v145, 31, v144
	v_readlane_b32 s4, v251, 57
	v_readlane_b32 s0, v251, 55
	v_lshlrev_b64 v[130:131], 12, v[144:145]
	v_readlane_b32 s5, v251, 58
	v_lshlrev_b64 v[134:135], 11, v[144:145]
	v_readlane_b32 s1, v251, 56
	v_lshl_add_u64 v[130:131], s[4:5], 0, v[130:131]
	v_and_b32_e32 v0, 0xf0, v0
	v_lshl_add_u64 v[134:135], s[0:1], 0, v[134:135]
	v_lshl_add_u64 v[146:147], v[130:131], 0, v[0:1]
	v_lshl_add_u64 v[152:153], v[134:135], 0, v[0:1]
	global_load_dwordx4 v[130:133], v[146:147], off offset:2048
	global_load_dwordx4 v[134:137], v[152:153], off
	v_add_co_u32_e32 v178, vcc, 0x10000, v146
	s_nop 1
	v_addc_co_u32_e32 v179, vcc, 0, v147, vcc
	v_add_co_u32_e32 v180, vcc, 0x8000, v152
	s_nop 1
	v_addc_co_u32_e32 v181, vcc, 0, v153, vcc
	global_load_dwordx4 v[204:207], v[146:147], off offset:2304
	global_load_dwordx4 v[208:211], v[152:153], off offset:256
	global_load_dwordx4 v[212:215], v[178:179], off offset:2048
	global_load_dwordx4 v[216:219], v[180:181], off
	global_load_dwordx4 v[220:223], v[178:179], off offset:2304
	global_load_dwordx4 v[224:227], v[180:181], off offset:256
	s_waitcnt vmcnt(0)
	v_lshlrev_b32_e32 v174, 16, v130
	v_and_b32_e32 v175, 0xffff0000, v130
	v_lshlrev_b32_e32 v176, 16, v134
	v_and_b32_e32 v177, 0xffff0000, v134
	v_lshlrev_b32_e32 v130, 16, v131
	v_and_b32_e32 v131, 0xffff0000, v131
	v_lshlrev_b32_e32 v134, 16, v135
	v_and_b32_e32 v135, 0xffff0000, v135
	v_pk_fma_f32 v[174:175], v[126:127], v[174:175], v[176:177]
	v_pk_fma_f32 v[134:135], v[128:129], v[130:131], v[134:135]
	v_lshlrev_b32_e32 v130, 16, v132
	v_and_b32_e32 v131, 0xffff0000, v132
	v_lshlrev_b32_e32 v176, 16, v136
	v_and_b32_e32 v177, 0xffff0000, v136
	v_pk_fma_f32 v[176:177], v[122:123], v[130:131], v[176:177]
	v_lshlrev_b32_e32 v130, 16, v133
	v_and_b32_e32 v131, 0xffff0000, v133
	v_lshlrev_b32_e32 v132, 16, v137
	v_and_b32_e32 v133, 0xffff0000, v137
	v_pk_fma_f32 v[136:137], v[124:125], v[130:131], v[132:133]
	v_cvt_pk_bf16_f32 v130, v174, v175
	v_cvt_pk_bf16_f32 v131, v134, v135
	v_cvt_pk_bf16_f32 v132, v176, v177
	v_cvt_pk_bf16_f32 v133, v136, v137
	global_store_dwordx4 v[152:153], v[130:133], off
	s_nop 1
	v_mov_b32_e32 v130, v204
	v_mov_b32_e32 v131, v205
	v_mov_b32_e32 v132, v206
	v_mov_b32_e32 v133, v207
	s_nop 0
	s_nop 1
	v_mov_b32_e32 v134, v208
	v_mov_b32_e32 v135, v209
	v_mov_b32_e32 v136, v210
	v_mov_b32_e32 v137, v211
	v_lshlrev_b32_e32 v146, 16, v130
	v_and_b32_e32 v147, 0xffff0000, v130
	v_lshlrev_b32_e32 v174, 16, v134
	v_and_b32_e32 v175, 0xffff0000, v134
	v_lshlrev_b32_e32 v130, 16, v131
	v_and_b32_e32 v131, 0xffff0000, v131
	v_lshlrev_b32_e32 v134, 16, v135
	v_and_b32_e32 v135, 0xffff0000, v135
; DI unsigned cvt_pk_bf16(float lo, float hi) { f32x2_t v = {lo, hi}; bf16x2_t b = __builtin_convertvector(v, bf16x2_t); return __builtin_bit_cast(unsigned, b); }
; DI float bflo(unsigned u) { return __uint_as_float(u << 16); }
; DI float bfhi(unsigned u) { return __uint_as_float(u & 0xffff0000u); }
; template <bool ADD>
; DI void gated_tile(acc_t& acc, bf16_t* Y, int ldy, const bf16_t* Gt, int ldg) {
;   epi_foreach(acc, [&](int r, int c, f32x4& v0, f32x4& v1) {
;     const u32x4 g = *(const u32x4*)(Gt + (size_t)r * ldg + c);
;     float o[8];
;     o[0] = bflo(g[0]) * v0[0]; o[1] = bfhi(g[0]) * v0[1]; o[2] = bflo(g[1]) * v0[2]; o[3] = bfhi(g[1]) * v0[3];
;     o[4] = bflo(g[2]) * v1[0]; o[5] = bfhi(g[2]) * v1[1]; o[6] = bflo(g[3]) * v1[2]; o[7] = bfhi(g[3]) * v1[3];
;     bf16_t* py = Y + (size_t)r * ldy + c;
;     if (ADD) {
;       const u32x4 y0 = *(const u32x4*)py;
; #pragma unroll
;       for (int j = 0; j < 4; ++j) { o[2 * j] += bflo(y0[j]); o[2 * j + 1] += bfhi(y0[j]); }
;     }
;     u32x4 pk;
; #pragma unroll
;     for (int j = 0; j < 4; ++j) pk[j] = cvt_pk_bf16(o[2 * j], o[2 * j + 1]);
;     *(u32x4*)py = pk;
	v_pk_fma_f32 v[146:147], v[118:119], v[146:147], v[174:175]
	v_pk_fma_f32 v[134:135], v[120:121], v[130:131], v[134:135]
	v_lshlrev_b32_e32 v130, 16, v132
	v_and_b32_e32 v131, 0xffff0000, v132
	v_lshlrev_b32_e32 v174, 16, v136
	v_and_b32_e32 v175, 0xffff0000, v136
	v_pk_fma_f32 v[174:175], v[114:115], v[130:131], v[174:175]
	v_lshlrev_b32_e32 v130, 16, v133
	v_and_b32_e32 v131, 0xffff0000, v133
	v_lshlrev_b32_e32 v132, 16, v137
	v_and_b32_e32 v133, 0xffff0000, v137
	v_pk_fma_f32 v[136:137], v[116:117], v[130:131], v[132:133]
	v_cvt_pk_bf16_f32 v131, v134, v135
	v_or_b32_e32 v134, 16, v144
	v_cvt_pk_bf16_f32 v130, v146, v147
	v_cvt_pk_bf16_f32 v132, v174, v175
	v_cvt_pk_bf16_f32 v133, v136, v137
	v_ashrrev_i32_e32 v135, 31, v134
	global_store_dwordx4 v[152:153], v[130:133], off offset:256
	s_nop 1
	v_lshlrev_b64 v[130:131], 12, v[134:135]
	v_lshlrev_b64 v[134:135], 11, v[134:135]
	v_lshl_add_u64 v[130:131], s[4:5], 0, v[130:131]
	v_lshl_add_u64 v[134:135], s[0:1], 0, v[134:135]
	v_lshl_add_u64 v[146:147], v[130:131], 0, v[0:1]
	v_lshl_add_u64 v[152:153], v[134:135], 0, v[0:1]
	s_nop 1
	v_mov_b32_e32 v130, v212
	v_mov_b32_e32 v131, v213
	v_mov_b32_e32 v132, v214
	v_mov_b32_e32 v133, v215
	s_nop 1
	v_mov_b32_e32 v134, v216
	v_mov_b32_e32 v135, v217
	v_mov_b32_e32 v136, v218
	v_mov_b32_e32 v137, v219
	v_lshlrev_b32_e32 v174, 16, v130
	v_and_b32_e32 v175, 0xffff0000, v130
	v_lshlrev_b32_e32 v176, 16, v134
	v_and_b32_e32 v177, 0xffff0000, v134
	v_lshlrev_b32_e32 v130, 16, v131
	v_and_b32_e32 v131, 0xffff0000, v131
	v_lshlrev_b32_e32 v134, 16, v135
	v_and_b32_e32 v135, 0xffff0000, v135
	v_pk_fma_f32 v[174:175], v[110:111], v[174:175], v[176:177]
	v_pk_fma_f32 v[134:135], v[112:113], v[130:131], v[134:135]
	v_lshlrev_b32_e32 v130, 16, v132
	v_and_b32_e32 v131, 0xffff0000, v132
	v_lshlrev_b32_e32 v176, 16, v136
	v_and_b32_e32 v177, 0xffff0000, v136
	v_pk_fma_f32 v[176:177], v[106:107], v[130:131], v[176:177]
	v_lshlrev_b32_e32 v130, 16, v133
	v_and_b32_e32 v131, 0xffff0000, v133
	v_lshlrev_b32_e32 v132, 16, v137
	v_and_b32_e32 v133, 0xffff0000, v137
	v_pk_fma_f32 v[136:137], v[108:109], v[130:131], v[132:133]
	v_cvt_pk_bf16_f32 v130, v174, v175
	v_cvt_pk_bf16_f32 v131, v134, v135
	v_cvt_pk_bf16_f32 v132, v176, v177
	v_cvt_pk_bf16_f32 v133, v136, v137
	global_store_dwordx4 v[152:153], v[130:133], off
	s_nop 1
	v_mov_b32_e32 v130, v220
	v_mov_b32_e32 v131, v221
	v_mov_b32_e32 v132, v222
	v_mov_b32_e32 v133, v223
	s_nop 0
	s_nop 1
	v_mov_b32_e32 v134, v224
	v_mov_b32_e32 v135, v225
	v_mov_b32_e32 v136, v226
	v_mov_b32_e32 v137, v227
	v_lshlrev_b32_e32 v146, 16, v130
	v_and_b32_e32 v147, 0xffff0000, v130
	v_lshlrev_b32_e32 v174, 16, v134
	v_and_b32_e32 v175, 0xffff0000, v134
	v_lshlrev_b32_e32 v130, 16, v131
	v_and_b32_e32 v131, 0xffff0000, v131
	v_lshlrev_b32_e32 v134, 16, v135
	v_and_b32_e32 v135, 0xffff0000, v135
	v_pk_fma_f32 v[146:147], v[102:103], v[146:147], v[174:175]
	v_pk_fma_f32 v[134:135], v[104:105], v[130:131], v[134:135]
	v_lshlrev_b32_e32 v130, 16, v132
	v_and_b32_e32 v131, 0xffff0000, v132
	v_lshlrev_b32_e32 v174, 16, v136
	v_and_b32_e32 v175, 0xffff0000, v136
	v_pk_fma_f32 v[174:175], v[98:99], v[130:131], v[174:175]
	v_lshlrev_b32_e32 v130, 16, v133
	v_and_b32_e32 v131, 0xffff0000, v133
	v_lshlrev_b32_e32 v132, 16, v137
	v_and_b32_e32 v133, 0xffff0000, v137
	v_pk_fma_f32 v[136:137], v[100:101], v[130:131], v[132:133]
	v_cvt_pk_bf16_f32 v131, v134, v135
	v_or_b32_e32 v134, 32, v144
	v_cvt_pk_bf16_f32 v130, v146, v147
	v_cvt_pk_bf16_f32 v132, v174, v175
	v_cvt_pk_bf16_f32 v133, v136, v137
	v_ashrrev_i32_e32 v135, 31, v134
	global_store_dwordx4 v[152:153], v[130:133], off offset:256
	s_nop 1
	v_lshlrev_b64 v[130:131], 12, v[134:135]
	v_lshlrev_b64 v[134:135], 11, v[134:135]
	v_lshl_add_u64 v[130:131], s[4:5], 0, v[130:131]
	v_lshl_add_u64 v[134:135], s[0:1], 0, v[134:135]
	v_lshl_add_u64 v[146:147], v[130:131], 0, v[0:1]
	v_lshl_add_u64 v[152:153], v[134:135], 0, v[0:1]
	global_load_dwordx4 v[130:133], v[146:147], off offset:2048
	global_load_dwordx4 v[134:137], v[152:153], off
	v_add_co_u32_e32 v178, vcc, 0x10000, v146
	s_nop 1
	v_addc_co_u32_e32 v179, vcc, 0, v147, vcc
	v_add_co_u32_e32 v180, vcc, 0x8000, v152
	s_nop 1
	v_addc_co_u32_e32 v181, vcc, 0, v153, vcc
	global_load_dwordx4 v[204:207], v[146:147], off offset:2304
	global_load_dwordx4 v[208:211], v[152:153], off offset:256
	global_load_dwordx4 v[212:215], v[178:179], off offset:2048
	global_load_dwordx4 v[216:219], v[180:181], off
	global_load_dwordx4 v[220:223], v[178:179], off offset:2304
	global_load_dwordx4 v[224:227], v[180:181], off offset:256
	s_waitcnt vmcnt(0)
; DI unsigned cvt_pk_bf16(float lo, float hi) { f32x2_t v = {lo, hi}; bf16x2_t b = __builtin_convertvector(v, bf16x2_t); return __builtin_bit_cast(unsigned, b); }
; DI float bflo(unsigned u) { return __uint_as_float(u << 16); }
; DI float bfhi(unsigned u) { return __uint_as_float(u & 0xffff0000u); }
; template <bool ADD>
; DI void gated_tile(acc_t& acc, bf16_t* Y, int ldy, const bf16_t* Gt, int ldg) {
;   epi_foreach(acc, [&](int r, int c, f32x4& v0, f32x4& v1) {
;     const u32x4 g = *(const u32x4*)(Gt + (size_t)r * ldg + c);
;     float o[8];
;     o[0] = bflo(g[0]) * v0[0]; o[1] = bfhi(g[0]) * v0[1]; o[2] = bflo(g[1]) * v0[2]; o[3] = bfhi(g[1]) * v0[3];
;     o[4] = bflo(g[2]) * v1[0]; o[5] = bfhi(g[2]) * v1[1]; o[6] = bflo(g[3]) * v1[2]; o[7] = bfhi(g[3]) * v1[3];
;     bf16_t* py = Y + (size_t)r * ldy + c;
;     if (ADD) {
;       const u32x4 y0 = *(const u32x4*)py;
; #pragma unroll
;       for (int j = 0; j < 4; ++j) { o[2 * j] += bflo(y0[j]); o[2 * j + 1] += bfhi(y0[j]); }
;     }
;     u32x4 pk;
; #pragma unroll
;     for (int j = 0; j < 4; ++j) pk[j] = cvt_pk_bf16(o[2 * j], o[2 * j + 1]);
;     *(u32x4*)py = pk;
	v_lshlrev_b32_e32 v174, 16, v130
	v_and_b32_e32 v175, 0xffff0000, v130
	v_lshlrev_b32_e32 v176, 16, v134
	v_and_b32_e32 v177, 0xffff0000, v134
	v_lshlrev_b32_e32 v130, 16, v131
	v_and_b32_e32 v131, 0xffff0000, v131
	v_lshlrev_b32_e32 v134, 16, v135
	v_and_b32_e32 v135, 0xffff0000, v135
	v_pk_fma_f32 v[174:175], v[94:95], v[174:175], v[176:177]
	v_pk_fma_f32 v[134:135], v[96:97], v[130:131], v[134:135]
	v_lshlrev_b32_e32 v130, 16, v132
	v_and_b32_e32 v131, 0xffff0000, v132
	v_lshlrev_b32_e32 v176, 16, v136
	v_and_b32_e32 v177, 0xffff0000, v136
	v_pk_fma_f32 v[176:177], v[90:91], v[130:131], v[176:177]
	v_lshlrev_b32_e32 v130, 16, v133
	v_and_b32_e32 v131, 0xffff0000, v133
	v_lshlrev_b32_e32 v132, 16, v137
	v_and_b32_e32 v133, 0xffff0000, v137
	v_pk_fma_f32 v[136:137], v[92:93], v[130:131], v[132:133]
	v_cvt_pk_bf16_f32 v130, v174, v175
	v_cvt_pk_bf16_f32 v131, v134, v135
	v_cvt_pk_bf16_f32 v132, v176, v177
	v_cvt_pk_bf16_f32 v133, v136, v137
	global_store_dwordx4 v[152:153], v[130:133], off
	s_nop 1
	v_mov_b32_e32 v130, v204
	v_mov_b32_e32 v131, v205
	v_mov_b32_e32 v132, v206
	v_mov_b32_e32 v133, v207
	s_nop 0
	s_nop 1
	v_mov_b32_e32 v134, v208
	v_mov_b32_e32 v135, v209
	v_mov_b32_e32 v136, v210
	v_mov_b32_e32 v137, v211
	v_lshlrev_b32_e32 v146, 16, v130
	v_and_b32_e32 v147, 0xffff0000, v130
	v_lshlrev_b32_e32 v174, 16, v134
	v_and_b32_e32 v175, 0xffff0000, v134
	v_lshlrev_b32_e32 v130, 16, v131
	v_and_b32_e32 v131, 0xffff0000, v131
	v_lshlrev_b32_e32 v134, 16, v135
	v_and_b32_e32 v135, 0xffff0000, v135
	v_pk_fma_f32 v[146:147], v[86:87], v[146:147], v[174:175]
	v_pk_fma_f32 v[134:135], v[88:89], v[130:131], v[134:135]
	v_lshlrev_b32_e32 v130, 16, v132
	v_and_b32_e32 v131, 0xffff0000, v132
	v_lshlrev_b32_e32 v174, 16, v136
	v_and_b32_e32 v175, 0xffff0000, v136
	v_pk_fma_f32 v[174:175], v[82:83], v[130:131], v[174:175]
	v_lshlrev_b32_e32 v130, 16, v133
	v_and_b32_e32 v131, 0xffff0000, v133
	v_lshlrev_b32_e32 v132, 16, v137
	v_and_b32_e32 v133, 0xffff0000, v137
	v_pk_fma_f32 v[136:137], v[84:85], v[130:131], v[132:133]
	v_cvt_pk_bf16_f32 v131, v134, v135
	v_or_b32_e32 v134, 48, v144
	v_cvt_pk_bf16_f32 v130, v146, v147
	v_cvt_pk_bf16_f32 v132, v174, v175
	v_cvt_pk_bf16_f32 v133, v136, v137
	v_ashrrev_i32_e32 v135, 31, v134
	global_store_dwordx4 v[152:153], v[130:133], off offset:256
	s_nop 1
	v_lshlrev_b64 v[130:131], 12, v[134:135]
	v_lshlrev_b64 v[134:135], 11, v[134:135]
	v_lshl_add_u64 v[130:131], s[4:5], 0, v[130:131]
	v_lshl_add_u64 v[134:135], s[0:1], 0, v[134:135]
	v_lshl_add_u64 v[152:153], v[130:131], 0, v[0:1]
	v_lshl_add_u64 v[146:147], v[134:135], 0, v[0:1]
	s_nop 1
	v_mov_b32_e32 v130, v212
	v_mov_b32_e32 v131, v213
	v_mov_b32_e32 v132, v214
	v_mov_b32_e32 v133, v215
	s_nop 1
	v_mov_b32_e32 v134, v216
	v_mov_b32_e32 v135, v217
	v_mov_b32_e32 v136, v218
	v_mov_b32_e32 v137, v219
	v_lshlrev_b32_e32 v174, 16, v130
	v_and_b32_e32 v175, 0xffff0000, v130
	v_lshlrev_b32_e32 v176, 16, v134
	v_and_b32_e32 v177, 0xffff0000, v134
	v_lshlrev_b32_e32 v130, 16, v131
	v_and_b32_e32 v131, 0xffff0000, v131
	v_lshlrev_b32_e32 v134, 16, v135
	v_and_b32_e32 v135, 0xffff0000, v135
	v_pk_fma_f32 v[174:175], v[78:79], v[174:175], v[176:177]
	v_pk_fma_f32 v[134:135], v[80:81], v[130:131], v[134:135]
	v_lshlrev_b32_e32 v130, 16, v132
	v_and_b32_e32 v131, 0xffff0000, v132
	v_lshlrev_b32_e32 v176, 16, v136
	v_and_b32_e32 v177, 0xffff0000, v136
	v_pk_fma_f32 v[176:177], v[74:75], v[130:131], v[176:177]
	v_lshlrev_b32_e32 v130, 16, v133
	v_and_b32_e32 v131, 0xffff0000, v133
	v_lshlrev_b32_e32 v132, 16, v137
	v_and_b32_e32 v133, 0xffff0000, v137
	v_pk_fma_f32 v[136:137], v[76:77], v[130:131], v[132:133]
	v_cvt_pk_bf16_f32 v130, v174, v175
	v_cvt_pk_bf16_f32 v131, v134, v135
	v_cvt_pk_bf16_f32 v132, v176, v177
	v_cvt_pk_bf16_f32 v133, v136, v137
	global_store_dwordx4 v[146:147], v[130:133], off
	s_nop 1
	v_mov_b32_e32 v130, v220
	v_mov_b32_e32 v131, v221
	v_mov_b32_e32 v132, v222
	v_mov_b32_e32 v133, v223
	s_nop 0
	s_nop 1
	v_mov_b32_e32 v134, v224
	v_mov_b32_e32 v135, v225
	v_mov_b32_e32 v136, v226
	v_mov_b32_e32 v137, v227
	v_lshlrev_b32_e32 v152, 16, v130
	v_and_b32_e32 v153, 0xffff0000, v130
	v_lshlrev_b32_e32 v174, 16, v134
	v_and_b32_e32 v175, 0xffff0000, v134
	v_lshlrev_b32_e32 v130, 16, v131
	v_and_b32_e32 v131, 0xffff0000, v131
	v_lshlrev_b32_e32 v134, 16, v135
	v_and_b32_e32 v135, 0xffff0000, v135
	v_pk_fma_f32 v[152:153], v[70:71], v[152:153], v[174:175]
	v_pk_fma_f32 v[134:135], v[72:73], v[130:131], v[134:135]
	v_lshlrev_b32_e32 v130, 16, v132
	v_and_b32_e32 v131, 0xffff0000, v132
	v_lshlrev_b32_e32 v174, 16, v136
	v_and_b32_e32 v175, 0xffff0000, v136
	v_pk_fma_f32 v[174:175], v[66:67], v[130:131], v[174:175]
	v_lshlrev_b32_e32 v130, 16, v133
	v_and_b32_e32 v131, 0xffff0000, v133
	v_lshlrev_b32_e32 v132, 16, v137
	v_and_b32_e32 v133, 0xffff0000, v137
	v_pk_fma_f32 v[136:137], v[68:69], v[130:131], v[132:133]
	v_cvt_pk_bf16_f32 v130, v152, v153
	v_cvt_pk_bf16_f32 v131, v134, v135
	v_cvt_pk_bf16_f32 v132, v174, v175
	v_cvt_pk_bf16_f32 v133, v136, v137
	global_store_dwordx4 v[146:147], v[130:133], off offset:256
	v_add_u32_e32 v134, 0x80, v144
	v_ashrrev_i32_e32 v135, 31, v134
	v_lshlrev_b64 v[130:131], 12, v[134:135]
	v_lshlrev_b64 v[134:135], 11, v[134:135]
	v_lshl_add_u64 v[130:131], s[4:5], 0, v[130:131]
	v_lshl_add_u64 v[134:135], s[0:1], 0, v[134:135]
	v_lshl_add_u64 v[146:147], v[130:131], 0, v[0:1]
	v_lshl_add_u64 v[152:153], v[134:135], 0, v[0:1]
	global_load_dwordx4 v[130:133], v[146:147], off offset:2048
	global_load_dwordx4 v[134:137], v[152:153], off
	v_add_co_u32_e32 v178, vcc, 0x10000, v146
	s_nop 1
	v_addc_co_u32_e32 v179, vcc, 0, v147, vcc
	v_add_co_u32_e32 v180, vcc, 0x8000, v152
	s_nop 1
	v_addc_co_u32_e32 v181, vcc, 0, v153, vcc
	global_load_dwordx4 v[204:207], v[146:147], off offset:2304
	global_load_dwordx4 v[208:211], v[152:153], off offset:256
	global_load_dwordx4 v[212:215], v[178:179], off offset:2048
	global_load_dwordx4 v[216:219], v[180:181], off
	global_load_dwordx4 v[220:223], v[178:179], off offset:2304
	global_load_dwordx4 v[224:227], v[180:181], off offset:256
	s_waitcnt vmcnt(0)
; DI unsigned cvt_pk_bf16(float lo, float hi) { f32x2_t v = {lo, hi}; bf16x2_t b = __builtin_convertvector(v, bf16x2_t); return __builtin_bit_cast(unsigned, b); }
; DI float bflo(unsigned u) { return __uint_as_float(u << 16); }
; DI float bfhi(unsigned u) { return __uint_as_float(u & 0xffff0000u); }
; template <bool ADD>
; DI void gated_tile(acc_t& acc, bf16_t* Y, int ldy, const bf16_t* Gt, int ldg) {
;   epi_foreach(acc, [&](int r, int c, f32x4& v0, f32x4& v1) {
;     const u32x4 g = *(const u32x4*)(Gt + (size_t)r * ldg + c);
;     float o[8];
;     o[0] = bflo(g[0]) * v0[0]; o[1] = bfhi(g[0]) * v0[1]; o[2] = bflo(g[1]) * v0[2]; o[3] = bfhi(g[1]) * v0[3];
;     o[4] = bflo(g[2]) * v1[0]; o[5] = bfhi(g[2]) * v1[1]; o[6] = bflo(g[3]) * v1[2]; o[7] = bfhi(g[3]) * v1[3];
;     bf16_t* py = Y + (size_t)r * ldy + c;
;     if (ADD) {
;       const u32x4 y0 = *(const u32x4*)py;
; #pragma unroll
;       for (int j = 0; j < 4; ++j) { o[2 * j] += bflo(y0[j]); o[2 * j + 1] += bfhi(y0[j]); }
;     }
;     u32x4 pk;
; #pragma unroll
;     for (int j = 0; j < 4; ++j) pk[j] = cvt_pk_bf16(o[2 * j], o[2 * j + 1]);
;     *(u32x4*)py = pk;
	v_lshlrev_b32_e32 v174, 16, v130
	v_and_b32_e32 v175, 0xffff0000, v130
	v_lshlrev_b32_e32 v176, 16, v134
	v_and_b32_e32 v177, 0xffff0000, v134
	v_lshlrev_b32_e32 v130, 16, v131
	v_and_b32_e32 v131, 0xffff0000, v131
	v_lshlrev_b32_e32 v134, 16, v135
	v_and_b32_e32 v135, 0xffff0000, v135
	v_pk_fma_f32 v[174:175], v[62:63], v[174:175], v[176:177]
	v_pk_fma_f32 v[134:135], v[64:65], v[130:131], v[134:135]
	v_lshlrev_b32_e32 v130, 16, v132
	v_and_b32_e32 v131, 0xffff0000, v132
	v_lshlrev_b32_e32 v176, 16, v136
	v_and_b32_e32 v177, 0xffff0000, v136
	v_pk_fma_f32 v[176:177], v[58:59], v[130:131], v[176:177]
	v_lshlrev_b32_e32 v130, 16, v133
	v_and_b32_e32 v131, 0xffff0000, v133
	v_lshlrev_b32_e32 v132, 16, v137
	v_and_b32_e32 v133, 0xffff0000, v137
	v_pk_fma_f32 v[136:137], v[60:61], v[130:131], v[132:133]
	v_cvt_pk_bf16_f32 v130, v174, v175
	v_cvt_pk_bf16_f32 v131, v134, v135
	v_cvt_pk_bf16_f32 v132, v176, v177
	v_cvt_pk_bf16_f32 v133, v136, v137
	global_store_dwordx4 v[152:153], v[130:133], off
	s_nop 1
	v_mov_b32_e32 v130, v204
	v_mov_b32_e32 v131, v205
	v_mov_b32_e32 v132, v206
	v_mov_b32_e32 v133, v207
	s_nop 0
	s_nop 1
	v_mov_b32_e32 v134, v208
	v_mov_b32_e32 v135, v209
	v_mov_b32_e32 v136, v210
	v_mov_b32_e32 v137, v211
	v_lshlrev_b32_e32 v146, 16, v130
	v_and_b32_e32 v147, 0xffff0000, v130
	v_lshlrev_b32_e32 v174, 16, v134
	v_and_b32_e32 v175, 0xffff0000, v134
	v_lshlrev_b32_e32 v130, 16, v131
	v_and_b32_e32 v131, 0xffff0000, v131
	v_lshlrev_b32_e32 v134, 16, v135
	v_and_b32_e32 v135, 0xffff0000, v135
	v_pk_fma_f32 v[146:147], v[54:55], v[146:147], v[174:175]
	v_pk_fma_f32 v[134:135], v[56:57], v[130:131], v[134:135]
	v_lshlrev_b32_e32 v130, 16, v132
	v_and_b32_e32 v131, 0xffff0000, v132
	v_lshlrev_b32_e32 v174, 16, v136
	v_and_b32_e32 v175, 0xffff0000, v136
	v_pk_fma_f32 v[174:175], v[50:51], v[130:131], v[174:175]
	v_lshlrev_b32_e32 v130, 16, v133
	v_and_b32_e32 v131, 0xffff0000, v133
	v_lshlrev_b32_e32 v132, 16, v137
	v_and_b32_e32 v133, 0xffff0000, v137
	v_pk_fma_f32 v[136:137], v[52:53], v[130:131], v[132:133]
	v_cvt_pk_bf16_f32 v131, v134, v135
	v_add_u32_e32 v134, 0x90, v144
	v_cvt_pk_bf16_f32 v130, v146, v147
	v_cvt_pk_bf16_f32 v132, v174, v175
	v_cvt_pk_bf16_f32 v133, v136, v137
	v_ashrrev_i32_e32 v135, 31, v134
	global_store_dwordx4 v[152:153], v[130:133], off offset:256
	s_nop 1
	v_lshlrev_b64 v[130:131], 12, v[134:135]
	v_lshlrev_b64 v[134:135], 11, v[134:135]
	v_lshl_add_u64 v[130:131], s[4:5], 0, v[130:131]
	v_lshl_add_u64 v[134:135], s[0:1], 0, v[134:135]
	v_lshl_add_u64 v[146:147], v[130:131], 0, v[0:1]
	v_lshl_add_u64 v[152:153], v[134:135], 0, v[0:1]
	s_nop 1
	v_mov_b32_e32 v130, v212
	v_mov_b32_e32 v131, v213
	v_mov_b32_e32 v132, v214
	v_mov_b32_e32 v133, v215
	s_nop 1
	v_mov_b32_e32 v134, v216
	v_mov_b32_e32 v135, v217
	v_mov_b32_e32 v136, v218
	v_mov_b32_e32 v137, v219
	v_lshlrev_b32_e32 v174, 16, v130
	v_and_b32_e32 v175, 0xffff0000, v130
	v_lshlrev_b32_e32 v176, 16, v134
	v_and_b32_e32 v177, 0xffff0000, v134
	v_lshlrev_b32_e32 v130, 16, v131
	v_and_b32_e32 v131, 0xffff0000, v131
	v_lshlrev_b32_e32 v134, 16, v135
	v_and_b32_e32 v135, 0xffff0000, v135
	v_pk_fma_f32 v[174:175], v[46:47], v[174:175], v[176:177]
	v_pk_fma_f32 v[134:135], v[48:49], v[130:131], v[134:135]
	v_lshlrev_b32_e32 v130, 16, v132
	v_and_b32_e32 v131, 0xffff0000, v132
	v_lshlrev_b32_e32 v176, 16, v136
	v_and_b32_e32 v177, 0xffff0000, v136
	v_pk_fma_f32 v[176:177], v[42:43], v[130:131], v[176:177]
	v_lshlrev_b32_e32 v130, 16, v133
	v_and_b32_e32 v131, 0xffff0000, v133
	v_lshlrev_b32_e32 v132, 16, v137
	v_and_b32_e32 v133, 0xffff0000, v137
	v_pk_fma_f32 v[136:137], v[44:45], v[130:131], v[132:133]
	v_cvt_pk_bf16_f32 v130, v174, v175
	v_cvt_pk_bf16_f32 v131, v134, v135
	v_cvt_pk_bf16_f32 v132, v176, v177
	v_cvt_pk_bf16_f32 v133, v136, v137
	global_store_dwordx4 v[152:153], v[130:133], off
	s_nop 1
	v_mov_b32_e32 v130, v220
	v_mov_b32_e32 v131, v221
	v_mov_b32_e32 v132, v222
	v_mov_b32_e32 v133, v223
	s_nop 0
	s_nop 1
	v_mov_b32_e32 v134, v224
	v_mov_b32_e32 v135, v225
	v_mov_b32_e32 v136, v226
	v_mov_b32_e32 v137, v227
	v_lshlrev_b32_e32 v146, 16, v130
	v_and_b32_e32 v147, 0xffff0000, v130
	v_lshlrev_b32_e32 v174, 16, v134
	v_and_b32_e32 v175, 0xffff0000, v134
	v_lshlrev_b32_e32 v130, 16, v131
	v_and_b32_e32 v131, 0xffff0000, v131
	v_lshlrev_b32_e32 v134, 16, v135
	v_and_b32_e32 v135, 0xffff0000, v135
	v_pk_fma_f32 v[146:147], v[38:39], v[146:147], v[174:175]
	v_pk_fma_f32 v[134:135], v[40:41], v[130:131], v[134:135]
	v_lshlrev_b32_e32 v130, 16, v132
	v_and_b32_e32 v131, 0xffff0000, v132
	v_lshlrev_b32_e32 v174, 16, v136
	v_and_b32_e32 v175, 0xffff0000, v136
	v_pk_fma_f32 v[174:175], v[34:35], v[130:131], v[174:175]
	v_lshlrev_b32_e32 v130, 16, v133
	v_and_b32_e32 v131, 0xffff0000, v133
	v_lshlrev_b32_e32 v132, 16, v137
	v_and_b32_e32 v133, 0xffff0000, v137
	v_pk_fma_f32 v[136:137], v[36:37], v[130:131], v[132:133]
	v_cvt_pk_bf16_f32 v131, v134, v135
	v_add_u32_e32 v134, 0xa0, v144
	v_cvt_pk_bf16_f32 v130, v146, v147
	v_cvt_pk_bf16_f32 v132, v174, v175
	v_cvt_pk_bf16_f32 v133, v136, v137
	v_ashrrev_i32_e32 v135, 31, v134
	global_store_dwordx4 v[152:153], v[130:133], off offset:256
	s_nop 1
	v_lshlrev_b64 v[130:131], 12, v[134:135]
	v_lshlrev_b64 v[134:135], 11, v[134:135]
	v_lshl_add_u64 v[130:131], s[4:5], 0, v[130:131]
	v_lshl_add_u64 v[134:135], s[0:1], 0, v[134:135]
	v_lshl_add_u64 v[146:147], v[130:131], 0, v[0:1]
	v_lshl_add_u64 v[152:153], v[134:135], 0, v[0:1]
	global_load_dwordx4 v[130:133], v[146:147], off offset:2048
	global_load_dwordx4 v[134:137], v[152:153], off
	v_add_co_u32_e32 v178, vcc, 0x10000, v146
	s_nop 1
	v_addc_co_u32_e32 v179, vcc, 0, v147, vcc
	v_add_co_u32_e32 v180, vcc, 0x8000, v152
	s_nop 1
	v_addc_co_u32_e32 v181, vcc, 0, v153, vcc
	global_load_dwordx4 v[204:207], v[146:147], off offset:2304
	global_load_dwordx4 v[208:211], v[152:153], off offset:256
	global_load_dwordx4 v[212:215], v[178:179], off offset:2048
	global_load_dwordx4 v[216:219], v[180:181], off
	global_load_dwordx4 v[220:223], v[178:179], off offset:2304
	global_load_dwordx4 v[224:227], v[180:181], off offset:256
	s_waitcnt vmcnt(0)
; DI unsigned cvt_pk_bf16(float lo, float hi) { f32x2_t v = {lo, hi}; bf16x2_t b = __builtin_convertvector(v, bf16x2_t); return __builtin_bit_cast(unsigned, b); }
; DI float bflo(unsigned u) { return __uint_as_float(u << 16); }
; DI float bfhi(unsigned u) { return __uint_as_float(u & 0xffff0000u); }
; template <bool ADD>
; DI void gated_tile(acc_t& acc, bf16_t* Y, int ldy, const bf16_t* Gt, int ldg) {
;   epi_foreach(acc, [&](int r, int c, f32x4& v0, f32x4& v1) {
;     const u32x4 g = *(const u32x4*)(Gt + (size_t)r * ldg + c);
;     float o[8];
;     o[0] = bflo(g[0]) * v0[0]; o[1] = bfhi(g[0]) * v0[1]; o[2] = bflo(g[1]) * v0[2]; o[3] = bfhi(g[1]) * v0[3];
;     o[4] = bflo(g[2]) * v1[0]; o[5] = bfhi(g[2]) * v1[1]; o[6] = bflo(g[3]) * v1[2]; o[7] = bfhi(g[3]) * v1[3];
;     bf16_t* py = Y + (size_t)r * ldy + c;
;     if (ADD) {
;       const u32x4 y0 = *(const u32x4*)py;
; #pragma unroll
;       for (int j = 0; j < 4; ++j) { o[2 * j] += bflo(y0[j]); o[2 * j + 1] += bfhi(y0[j]); }
;     }
;     u32x4 pk;
; #pragma unroll
;     for (int j = 0; j < 4; ++j) pk[j] = cvt_pk_bf16(o[2 * j], o[2 * j + 1]);
;     *(u32x4*)py = pk;
	v_lshlrev_b32_e32 v174, 16, v130
	v_and_b32_e32 v175, 0xffff0000, v130
	v_lshlrev_b32_e32 v176, 16, v134
	v_and_b32_e32 v177, 0xffff0000, v134
	v_lshlrev_b32_e32 v130, 16, v131
	v_and_b32_e32 v131, 0xffff0000, v131
	v_lshlrev_b32_e32 v134, 16, v135
	v_and_b32_e32 v135, 0xffff0000, v135
	v_pk_fma_f32 v[174:175], v[30:31], v[174:175], v[176:177]
	v_pk_fma_f32 v[134:135], v[32:33], v[130:131], v[134:135]
	v_lshlrev_b32_e32 v130, 16, v132
	v_and_b32_e32 v131, 0xffff0000, v132
	v_lshlrev_b32_e32 v176, 16, v136
	v_and_b32_e32 v177, 0xffff0000, v136
	v_pk_fma_f32 v[176:177], v[26:27], v[130:131], v[176:177]
	v_lshlrev_b32_e32 v130, 16, v133
	v_and_b32_e32 v131, 0xffff0000, v133
	v_lshlrev_b32_e32 v132, 16, v137
	v_and_b32_e32 v133, 0xffff0000, v137
	v_pk_fma_f32 v[136:137], v[28:29], v[130:131], v[132:133]
	v_cvt_pk_bf16_f32 v130, v174, v175
	v_cvt_pk_bf16_f32 v131, v134, v135
	v_cvt_pk_bf16_f32 v132, v176, v177
	v_cvt_pk_bf16_f32 v133, v136, v137
	global_store_dwordx4 v[152:153], v[130:133], off
	s_nop 1
	v_mov_b32_e32 v130, v204
	v_mov_b32_e32 v131, v205
	v_mov_b32_e32 v132, v206
	v_mov_b32_e32 v133, v207
	s_nop 0
	s_nop 1
	v_mov_b32_e32 v134, v208
	v_mov_b32_e32 v135, v209
	v_mov_b32_e32 v136, v210
	v_mov_b32_e32 v137, v211
	v_lshlrev_b32_e32 v146, 16, v130
	v_and_b32_e32 v147, 0xffff0000, v130
	v_lshlrev_b32_e32 v174, 16, v134
	v_and_b32_e32 v175, 0xffff0000, v134
	v_lshlrev_b32_e32 v130, 16, v131
	v_and_b32_e32 v131, 0xffff0000, v131
	v_lshlrev_b32_e32 v134, 16, v135
	v_and_b32_e32 v135, 0xffff0000, v135
	v_pk_fma_f32 v[146:147], v[22:23], v[146:147], v[174:175]
	v_pk_fma_f32 v[134:135], v[24:25], v[130:131], v[134:135]
	v_lshlrev_b32_e32 v130, 16, v132
	v_and_b32_e32 v131, 0xffff0000, v132
	v_lshlrev_b32_e32 v174, 16, v136
	v_and_b32_e32 v175, 0xffff0000, v136
	v_pk_fma_f32 v[174:175], v[18:19], v[130:131], v[174:175]
	v_lshlrev_b32_e32 v130, 16, v133
	v_and_b32_e32 v131, 0xffff0000, v133
	v_lshlrev_b32_e32 v132, 16, v137
	v_and_b32_e32 v133, 0xffff0000, v137
	v_pk_fma_f32 v[136:137], v[20:21], v[130:131], v[132:133]
	v_cvt_pk_bf16_f32 v131, v134, v135
	v_add_u32_e32 v134, 0xb0, v144
	v_cvt_pk_bf16_f32 v130, v146, v147
	v_cvt_pk_bf16_f32 v132, v174, v175
	v_cvt_pk_bf16_f32 v133, v136, v137
	v_ashrrev_i32_e32 v135, 31, v134
	global_store_dwordx4 v[152:153], v[130:133], off offset:256
	s_nop 1
	v_lshlrev_b64 v[130:131], 12, v[134:135]
	v_lshlrev_b64 v[134:135], 11, v[134:135]
	v_lshl_add_u64 v[130:131], s[4:5], 0, v[130:131]
	v_lshl_add_u64 v[134:135], s[0:1], 0, v[134:135]
	v_lshl_add_u64 v[146:147], v[130:131], 0, v[0:1]
	v_lshl_add_u64 v[144:145], v[134:135], 0, v[0:1]
	s_nop 1
	v_mov_b32_e32 v130, v212
	v_mov_b32_e32 v131, v213
	v_mov_b32_e32 v132, v214
	v_mov_b32_e32 v133, v215
	s_nop 1
	v_mov_b32_e32 v134, v216
	v_mov_b32_e32 v135, v217
	v_mov_b32_e32 v136, v218
	v_mov_b32_e32 v137, v219
	s_mov_b64 s[4:5], 0
	v_lshlrev_b32_e32 v152, 16, v130
	v_and_b32_e32 v153, 0xffff0000, v130
	v_lshlrev_b32_e32 v174, 16, v134
	v_and_b32_e32 v175, 0xffff0000, v134
	v_lshlrev_b32_e32 v130, 16, v131
	v_and_b32_e32 v131, 0xffff0000, v131
	v_lshlrev_b32_e32 v134, 16, v135
	v_and_b32_e32 v135, 0xffff0000, v135
	v_pk_fma_f32 v[152:153], v[14:15], v[152:153], v[174:175]
	v_pk_fma_f32 v[134:135], v[16:17], v[130:131], v[134:135]
	v_lshlrev_b32_e32 v130, 16, v132
	v_and_b32_e32 v131, 0xffff0000, v132
	v_lshlrev_b32_e32 v174, 16, v136
	v_and_b32_e32 v175, 0xffff0000, v136
	v_pk_fma_f32 v[174:175], v[10:11], v[130:131], v[174:175]
	v_lshlrev_b32_e32 v130, 16, v133
	v_and_b32_e32 v131, 0xffff0000, v133
	v_lshlrev_b32_e32 v132, 16, v137
	v_and_b32_e32 v133, 0xffff0000, v137
	v_pk_fma_f32 v[136:137], v[12:13], v[130:131], v[132:133]
	v_cvt_pk_bf16_f32 v130, v152, v153
	v_cvt_pk_bf16_f32 v131, v134, v135
	v_cvt_pk_bf16_f32 v132, v174, v175
	v_cvt_pk_bf16_f32 v133, v136, v137
	global_store_dwordx4 v[144:145], v[130:133], off
	s_nop 1
	v_mov_b32_e32 v130, v220
	v_mov_b32_e32 v131, v221
	v_mov_b32_e32 v132, v222
	v_mov_b32_e32 v133, v223
	s_nop 0
	s_nop 1
	v_mov_b32_e32 v134, v224
	v_mov_b32_e32 v135, v225
	v_mov_b32_e32 v136, v226
	v_mov_b32_e32 v137, v227
	v_lshlrev_b32_e32 v146, 16, v130
	v_and_b32_e32 v147, 0xffff0000, v130
	v_lshlrev_b32_e32 v152, 16, v134
	v_and_b32_e32 v153, 0xffff0000, v134
	v_lshlrev_b32_e32 v130, 16, v131
	v_and_b32_e32 v131, 0xffff0000, v131
	v_lshlrev_b32_e32 v134, 16, v135
	v_and_b32_e32 v135, 0xffff0000, v135
	v_pk_fma_f32 v[146:147], v[6:7], v[146:147], v[152:153]
	v_pk_fma_f32 v[134:135], v[8:9], v[130:131], v[134:135]
	v_lshlrev_b32_e32 v130, 16, v132
	v_and_b32_e32 v131, 0xffff0000, v132
	v_lshlrev_b32_e32 v152, 16, v136
	v_and_b32_e32 v153, 0xffff0000, v136
	v_pk_fma_f32 v[152:153], v[2:3], v[130:131], v[152:153]
	v_lshlrev_b32_e32 v130, 16, v133
	v_and_b32_e32 v131, 0xffff0000, v133
	v_lshlrev_b32_e32 v132, 16, v137
	v_and_b32_e32 v133, 0xffff0000, v137
	v_pk_fma_f32 v[136:137], v[4:5], v[130:131], v[132:133]
	v_cvt_pk_bf16_f32 v130, v146, v147
	v_cvt_pk_bf16_f32 v131, v134, v135
	v_cvt_pk_bf16_f32 v132, v152, v153
	v_cvt_pk_bf16_f32 v133, v136, v137
	global_store_dwordx4 v[144:145], v[130:133], off offset:256
; DI unsigned cvt_pk_bf16(float lo, float hi) { f32x2_t v = {lo, hi}; bf16x2_t b = __builtin_convertvector(v, bf16x2_t); return __builtin_bit_cast(unsigned, b); }
; DI float bflo(unsigned u) { return __uint_as_float(u << 16); }
; DI float bfhi(unsigned u) { return __uint_as_float(u & 0xffff0000u); }
; template <bool ADD>
; DI void gated_tile(acc_t& acc, bf16_t* Y, int ldy, const bf16_t* Gt, int ldg) {
;   epi_foreach(acc, [&](int r, int c, f32x4& v0, f32x4& v1) {
;     const u32x4 g = *(const u32x4*)(Gt + (size_t)r * ldg + c);
;     float o[8];
;     o[0] = bflo(g[0]) * v0[0]; o[1] = bfhi(g[0]) * v0[1]; o[2] = bflo(g[1]) * v0[2]; o[3] = bfhi(g[1]) * v0[3];
;     o[4] = bflo(g[2]) * v1[0]; o[5] = bfhi(g[2]) * v1[1]; o[6] = bflo(g[3]) * v1[2]; o[7] = bfhi(g[3]) * v1[3];
;     bf16_t* py = Y + (size_t)r * ldy + c;
;     if (ADD) {
;       const u32x4 y0 = *(const u32x4*)py;
; #pragma unroll
;       for (int j = 0; j < 4; ++j) { o[2 * j] += bflo(y0[j]); o[2 * j + 1] += bfhi(y0[j]); }
;     }
;     u32x4 pk;
; #pragma unroll
;     for (int j = 0; j < 4; ++j) pk[j] = cvt_pk_bf16(o[2 * j], o[2 * j + 1]);
;     *(u32x4*)py = pk;
.LBB0_1285:
	v_readlane_b32 s0, v251, 51
	s_andn2_b64 vcc, exec, s[4:5]
	v_readlane_b32 s1, v251, 52
	s_cbranch_vccnz .LBB0_1280
	v_mov_b32_e32 v0, v149
	s_movk_i32 s4, 0xffc0
	v_and_b32_e32 v130, 15, v0
	v_ashrrev_i32_e32 v131, 2, v0
	v_and_or_b32 v130, v131, s4, v130
	v_ashrrev_i32_e32 v131, 31, v130
	v_readlane_b32 s26, v251, 57
	v_lshlrev_b64 v[132:133], 12, v[130:131]
	v_readlane_b32 s27, v251, 58
	v_and_b32_e32 v0, 0xf0, v0
	v_readlane_b32 s4, v251, 55
	v_lshl_add_u64 v[132:133], s[26:27], 0, v[132:133]
	v_lshl_add_u64 v[136:137], v[132:133], 0, v[0:1]
	global_load_dwordx4 v[132:135], v[136:137], off
	v_add_co_u32_e32 v178, vcc, 0x10000, v136
	s_nop 1
	v_addc_co_u32_e32 v179, vcc, 0, v137, vcc
	global_load_dwordx4 v[204:207], v[136:137], off offset:256
	global_load_dwordx4 v[208:211], v[178:179], off
	global_load_dwordx4 v[212:215], v[178:179], off offset:256
	v_readlane_b32 s5, v251, 56
	s_waitcnt vmcnt(0)
	v_lshlrev_b32_e32 v144, 16, v132
	v_and_b32_e32 v145, 0xffff0000, v132
	v_lshlrev_b32_e32 v132, 16, v133
	v_and_b32_e32 v133, 0xffff0000, v133
	v_pk_mul_f32 v[128:129], v[128:129], v[132:133]
	v_lshlrev_b32_e32 v132, 16, v134
	v_and_b32_e32 v133, 0xffff0000, v134
	v_pk_mul_f32 v[126:127], v[126:127], v[144:145]
	v_pk_mul_f32 v[132:133], v[122:123], v[132:133]
	v_lshlrev_b32_e32 v122, 16, v135
	v_and_b32_e32 v123, 0xffff0000, v135
	v_pk_mul_f32 v[134:135], v[124:125], v[122:123]
	v_cvt_pk_bf16_f32 v122, v126, v127
	v_lshlrev_b64 v[126:127], 11, v[130:131]
	v_lshl_add_u64 v[126:127], s[4:5], 0, v[126:127]
	v_cvt_pk_bf16_f32 v123, v128, v129
	v_cvt_pk_bf16_f32 v124, v132, v133
	v_cvt_pk_bf16_f32 v125, v134, v135
	v_lshl_add_u64 v[126:127], v[126:127], 0, v[0:1]
	global_store_dwordx4 v[126:127], v[122:125], off
	s_nop 1
	v_mov_b32_e32 v122, v204
	v_mov_b32_e32 v123, v205
	v_mov_b32_e32 v124, v206
	v_mov_b32_e32 v125, v207
	v_lshlrev_b32_e32 v128, 16, v122
	v_and_b32_e32 v129, 0xffff0000, v122
	v_lshlrev_b32_e32 v122, 16, v123
	v_and_b32_e32 v123, 0xffff0000, v123
	v_pk_mul_f32 v[120:121], v[120:121], v[122:123]
	v_lshlrev_b32_e32 v122, 16, v124
	v_and_b32_e32 v123, 0xffff0000, v124
	v_pk_mul_f32 v[122:123], v[114:115], v[122:123]
	v_lshlrev_b32_e32 v114, 16, v125
	v_and_b32_e32 v115, 0xffff0000, v125
	v_pk_mul_f32 v[118:119], v[118:119], v[128:129]
	v_pk_mul_f32 v[124:125], v[116:117], v[114:115]
	v_cvt_pk_bf16_f32 v115, v120, v121
	v_or_b32_e32 v120, 16, v130
	v_cvt_pk_bf16_f32 v114, v118, v119
	v_cvt_pk_bf16_f32 v116, v122, v123
	v_cvt_pk_bf16_f32 v117, v124, v125
	v_ashrrev_i32_e32 v121, 31, v120
	global_store_dwordx4 v[126:127], v[114:117], off offset:256
	s_nop 1
	v_lshlrev_b64 v[114:115], 12, v[120:121]
	v_lshl_add_u64 v[114:115], s[26:27], 0, v[114:115]
	v_lshl_add_u64 v[114:115], v[114:115], 0, v[0:1]
	s_nop 1
	v_mov_b32_e32 v116, v208
	v_mov_b32_e32 v117, v209
	v_mov_b32_e32 v118, v210
	v_mov_b32_e32 v119, v211
	v_lshlrev_b32_e32 v122, 16, v116
	v_and_b32_e32 v123, 0xffff0000, v116
	v_lshlrev_b32_e32 v116, 16, v117
	v_and_b32_e32 v117, 0xffff0000, v117
	v_pk_mul_f32 v[112:113], v[112:113], v[116:117]
	v_lshlrev_b32_e32 v116, 16, v118
	v_and_b32_e32 v117, 0xffff0000, v118
	v_pk_mul_f32 v[110:111], v[110:111], v[122:123]
	v_pk_mul_f32 v[116:117], v[106:107], v[116:117]
	v_lshlrev_b32_e32 v106, 16, v119
	v_and_b32_e32 v107, 0xffff0000, v119
	v_pk_mul_f32 v[118:119], v[108:109], v[106:107]
	v_cvt_pk_bf16_f32 v106, v110, v111
	v_lshlrev_b64 v[110:111], 11, v[120:121]
	v_lshl_add_u64 v[110:111], s[4:5], 0, v[110:111]
	v_cvt_pk_bf16_f32 v107, v112, v113
	v_cvt_pk_bf16_f32 v108, v116, v117
	v_cvt_pk_bf16_f32 v109, v118, v119
	v_lshl_add_u64 v[110:111], v[110:111], 0, v[0:1]
	global_store_dwordx4 v[110:111], v[106:109], off
	s_nop 1
	v_mov_b32_e32 v106, v212
	v_mov_b32_e32 v107, v213
	v_mov_b32_e32 v108, v214
	v_mov_b32_e32 v109, v215
	v_lshlrev_b32_e32 v112, 16, v106
	v_and_b32_e32 v113, 0xffff0000, v106
	v_lshlrev_b32_e32 v106, 16, v107
	v_and_b32_e32 v107, 0xffff0000, v107
	v_pk_mul_f32 v[104:105], v[104:105], v[106:107]
	v_lshlrev_b32_e32 v106, 16, v108
	v_and_b32_e32 v107, 0xffff0000, v108
	v_pk_mul_f32 v[106:107], v[98:99], v[106:107]
	v_lshlrev_b32_e32 v98, 16, v109
	v_and_b32_e32 v99, 0xffff0000, v109
	v_pk_mul_f32 v[102:103], v[102:103], v[112:113]
	v_pk_mul_f32 v[108:109], v[100:101], v[98:99]
	v_cvt_pk_bf16_f32 v99, v104, v105
	v_or_b32_e32 v104, 32, v130
	v_cvt_pk_bf16_f32 v98, v102, v103
	v_cvt_pk_bf16_f32 v100, v106, v107
	v_cvt_pk_bf16_f32 v101, v108, v109
	v_ashrrev_i32_e32 v105, 31, v104
	global_store_dwordx4 v[110:111], v[98:101], off offset:256
	s_nop 1
	v_lshlrev_b64 v[98:99], 12, v[104:105]
	v_lshl_add_u64 v[98:99], s[26:27], 0, v[98:99]
	v_lshl_add_u64 v[98:99], v[98:99], 0, v[0:1]
	global_load_dwordx4 v[100:103], v[98:99], off
	v_add_co_u32_e32 v178, vcc, 0x10000, v98
	s_nop 1
	v_addc_co_u32_e32 v179, vcc, 0, v99, vcc
	global_load_dwordx4 v[204:207], v[98:99], off offset:256
	global_load_dwordx4 v[208:211], v[178:179], off
	global_load_dwordx4 v[212:215], v[178:179], off offset:256
	s_waitcnt vmcnt(0)
; DI unsigned cvt_pk_bf16(float lo, float hi) { f32x2_t v = {lo, hi}; bf16x2_t b = __builtin_convertvector(v, bf16x2_t); return __builtin_bit_cast(unsigned, b); }
; DI float bflo(unsigned u) { return __uint_as_float(u << 16); }
; DI float bfhi(unsigned u) { return __uint_as_float(u & 0xffff0000u); }
; template <bool ADD>
; DI void gated_tile(acc_t& acc, bf16_t* Y, int ldy, const bf16_t* Gt, int ldg) {
;   epi_foreach(acc, [&](int r, int c, f32x4& v0, f32x4& v1) {
;     const u32x4 g = *(const u32x4*)(Gt + (size_t)r * ldg + c);
;     float o[8];
;     o[0] = bflo(g[0]) * v0[0]; o[1] = bfhi(g[0]) * v0[1]; o[2] = bflo(g[1]) * v0[2]; o[3] = bfhi(g[1]) * v0[3];
;     o[4] = bflo(g[2]) * v1[0]; o[5] = bfhi(g[2]) * v1[1]; o[6] = bflo(g[3]) * v1[2]; o[7] = bfhi(g[3]) * v1[3];
;     bf16_t* py = Y + (size_t)r * ldy + c;
;     if (ADD) {
;       const u32x4 y0 = *(const u32x4*)py;
; #pragma unroll
;       for (int j = 0; j < 4; ++j) { o[2 * j] += bflo(y0[j]); o[2 * j + 1] += bfhi(y0[j]); }
;     }
;     u32x4 pk;
; #pragma unroll
;     for (int j = 0; j < 4; ++j) pk[j] = cvt_pk_bf16(o[2 * j], o[2 * j + 1]);
;     *(u32x4*)py = pk;
	v_lshlrev_b32_e32 v106, 16, v100
	v_and_b32_e32 v107, 0xffff0000, v100
	v_lshlrev_b32_e32 v100, 16, v101
	v_and_b32_e32 v101, 0xffff0000, v101
	v_pk_mul_f32 v[96:97], v[96:97], v[100:101]
	v_lshlrev_b32_e32 v100, 16, v102
	v_and_b32_e32 v101, 0xffff0000, v102
	v_pk_mul_f32 v[94:95], v[94:95], v[106:107]
	v_pk_mul_f32 v[100:101], v[90:91], v[100:101]
	v_lshlrev_b32_e32 v90, 16, v103
	v_and_b32_e32 v91, 0xffff0000, v103
	v_pk_mul_f32 v[102:103], v[92:93], v[90:91]
	v_cvt_pk_bf16_f32 v90, v94, v95
	v_lshlrev_b64 v[94:95], 11, v[104:105]
	v_lshl_add_u64 v[94:95], s[4:5], 0, v[94:95]
	v_cvt_pk_bf16_f32 v91, v96, v97
	v_cvt_pk_bf16_f32 v92, v100, v101
	v_cvt_pk_bf16_f32 v93, v102, v103
	v_lshl_add_u64 v[94:95], v[94:95], 0, v[0:1]
	global_store_dwordx4 v[94:95], v[90:93], off
	s_nop 1
	v_mov_b32_e32 v90, v204
	v_mov_b32_e32 v91, v205
	v_mov_b32_e32 v92, v206
	v_mov_b32_e32 v93, v207
	v_lshlrev_b32_e32 v96, 16, v90
	v_and_b32_e32 v97, 0xffff0000, v90
	v_lshlrev_b32_e32 v90, 16, v91
	v_and_b32_e32 v91, 0xffff0000, v91
	v_pk_mul_f32 v[88:89], v[88:89], v[90:91]
	v_lshlrev_b32_e32 v90, 16, v92
	v_and_b32_e32 v91, 0xffff0000, v92
	v_pk_mul_f32 v[90:91], v[82:83], v[90:91]
	v_lshlrev_b32_e32 v82, 16, v93
	v_and_b32_e32 v83, 0xffff0000, v93
	v_pk_mul_f32 v[86:87], v[86:87], v[96:97]
	v_pk_mul_f32 v[92:93], v[84:85], v[82:83]
	v_cvt_pk_bf16_f32 v83, v88, v89
	v_or_b32_e32 v88, 48, v130
	v_cvt_pk_bf16_f32 v82, v86, v87
	v_cvt_pk_bf16_f32 v84, v90, v91
	v_cvt_pk_bf16_f32 v85, v92, v93
	v_ashrrev_i32_e32 v89, 31, v88
	global_store_dwordx4 v[94:95], v[82:85], off offset:256
	s_nop 1
	v_lshlrev_b64 v[82:83], 12, v[88:89]
	v_lshl_add_u64 v[82:83], s[26:27], 0, v[82:83]
	v_lshl_add_u64 v[82:83], v[82:83], 0, v[0:1]
	s_nop 1
	v_mov_b32_e32 v84, v208
	v_mov_b32_e32 v85, v209
	v_mov_b32_e32 v86, v210
	v_mov_b32_e32 v87, v211
	v_lshlrev_b32_e32 v90, 16, v84
	v_and_b32_e32 v91, 0xffff0000, v84
	v_lshlrev_b32_e32 v84, 16, v85
	v_and_b32_e32 v85, 0xffff0000, v85
	v_pk_mul_f32 v[80:81], v[80:81], v[84:85]
	v_lshlrev_b32_e32 v84, 16, v86
	v_and_b32_e32 v85, 0xffff0000, v86
	v_pk_mul_f32 v[78:79], v[78:79], v[90:91]
	v_pk_mul_f32 v[74:75], v[74:75], v[84:85]
	v_lshlrev_b32_e32 v84, 16, v87
	v_and_b32_e32 v85, 0xffff0000, v87
	v_pk_mul_f32 v[84:85], v[76:77], v[84:85]
	v_cvt_pk_bf16_f32 v76, v78, v79
	v_cvt_pk_bf16_f32 v78, v74, v75
	v_lshlrev_b64 v[74:75], 11, v[88:89]
	v_lshl_add_u64 v[74:75], s[4:5], 0, v[74:75]
	v_cvt_pk_bf16_f32 v77, v80, v81
	v_cvt_pk_bf16_f32 v79, v84, v85
	v_lshl_add_u64 v[74:75], v[74:75], 0, v[0:1]
	global_store_dwordx4 v[74:75], v[76:79], off
	s_nop 1
	v_mov_b32_e32 v76, v212
	v_mov_b32_e32 v77, v213
	v_mov_b32_e32 v78, v214
	v_mov_b32_e32 v79, v215
	v_lshlrev_b32_e32 v80, 16, v76
	v_and_b32_e32 v81, 0xffff0000, v76
	v_lshlrev_b32_e32 v76, 16, v77
	v_and_b32_e32 v77, 0xffff0000, v77
	v_pk_mul_f32 v[72:73], v[72:73], v[76:77]
	v_lshlrev_b32_e32 v76, 16, v78
	v_and_b32_e32 v77, 0xffff0000, v78
	v_pk_mul_f32 v[76:77], v[66:67], v[76:77]
	v_lshlrev_b32_e32 v66, 16, v79
	v_and_b32_e32 v67, 0xffff0000, v79
	v_pk_mul_f32 v[70:71], v[70:71], v[80:81]
	v_pk_mul_f32 v[78:79], v[68:69], v[66:67]
	v_cvt_pk_bf16_f32 v66, v70, v71
	v_cvt_pk_bf16_f32 v67, v72, v73
	v_cvt_pk_bf16_f32 v68, v76, v77
	v_cvt_pk_bf16_f32 v69, v78, v79
	global_store_dwordx4 v[74:75], v[66:69], off offset:256
	v_add_u32_e32 v70, 0x80, v130
	v_ashrrev_i32_e32 v71, 31, v70
	v_lshlrev_b64 v[66:67], 12, v[70:71]
	v_lshl_add_u64 v[66:67], s[26:27], 0, v[66:67]
	v_lshl_add_u64 v[72:73], v[66:67], 0, v[0:1]
	global_load_dwordx4 v[66:69], v[72:73], off
	v_add_co_u32_e32 v178, vcc, 0x10000, v72
	s_nop 1
	v_addc_co_u32_e32 v179, vcc, 0, v73, vcc
	global_load_dwordx4 v[204:207], v[72:73], off offset:256
	global_load_dwordx4 v[208:211], v[178:179], off
	global_load_dwordx4 v[212:215], v[178:179], off offset:256
	s_waitcnt vmcnt(0)
	v_lshlrev_b32_e32 v74, 16, v66
	v_and_b32_e32 v75, 0xffff0000, v66
	v_lshlrev_b32_e32 v66, 16, v67
	v_and_b32_e32 v67, 0xffff0000, v67
	v_pk_mul_f32 v[64:65], v[64:65], v[66:67]
	v_lshlrev_b32_e32 v66, 16, v68
	v_and_b32_e32 v67, 0xffff0000, v68
	v_pk_mul_f32 v[62:63], v[62:63], v[74:75]
	v_pk_mul_f32 v[66:67], v[58:59], v[66:67]
	v_lshlrev_b32_e32 v58, 16, v69
	v_and_b32_e32 v59, 0xffff0000, v69
	v_pk_mul_f32 v[68:69], v[60:61], v[58:59]
	v_cvt_pk_bf16_f32 v58, v62, v63
	v_lshlrev_b64 v[62:63], 11, v[70:71]
	v_lshl_add_u64 v[62:63], s[4:5], 0, v[62:63]
	v_cvt_pk_bf16_f32 v59, v64, v65
	v_cvt_pk_bf16_f32 v60, v66, v67
	v_cvt_pk_bf16_f32 v61, v68, v69
	v_lshl_add_u64 v[62:63], v[62:63], 0, v[0:1]
	global_store_dwordx4 v[62:63], v[58:61], off
	s_nop 1
	v_mov_b32_e32 v58, v204
	v_mov_b32_e32 v59, v205
	v_mov_b32_e32 v60, v206
	v_mov_b32_e32 v61, v207
	v_lshlrev_b32_e32 v64, 16, v58
	v_and_b32_e32 v65, 0xffff0000, v58
	v_lshlrev_b32_e32 v58, 16, v59
	v_and_b32_e32 v59, 0xffff0000, v59
	v_pk_mul_f32 v[56:57], v[56:57], v[58:59]
	v_lshlrev_b32_e32 v58, 16, v60
	v_and_b32_e32 v59, 0xffff0000, v60
	v_pk_mul_f32 v[58:59], v[50:51], v[58:59]
	v_lshlrev_b32_e32 v50, 16, v61
	v_and_b32_e32 v51, 0xffff0000, v61
	v_pk_mul_f32 v[54:55], v[54:55], v[64:65]
	v_pk_mul_f32 v[60:61], v[52:53], v[50:51]
	v_cvt_pk_bf16_f32 v51, v56, v57
	v_add_u32_e32 v56, 0x90, v130
	v_cvt_pk_bf16_f32 v50, v54, v55
	v_cvt_pk_bf16_f32 v52, v58, v59
	v_cvt_pk_bf16_f32 v53, v60, v61
	v_ashrrev_i32_e32 v57, 31, v56
	global_store_dwordx4 v[62:63], v[50:53], off offset:256
	s_nop 1
	v_lshlrev_b64 v[50:51], 12, v[56:57]
	v_lshl_add_u64 v[50:51], s[26:27], 0, v[50:51]
; DI unsigned cvt_pk_bf16(float lo, float hi) { f32x2_t v = {lo, hi}; bf16x2_t b = __builtin_convertvector(v, bf16x2_t); return __builtin_bit_cast(unsigned, b); }
; DI float bflo(unsigned u) { return __uint_as_float(u << 16); }
; DI float bfhi(unsigned u) { return __uint_as_float(u & 0xffff0000u); }
; template <bool ADD>
; DI void gated_tile(acc_t& acc, bf16_t* Y, int ldy, const bf16_t* Gt, int ldg) {
;   epi_foreach(acc, [&](int r, int c, f32x4& v0, f32x4& v1) {
;     const u32x4 g = *(const u32x4*)(Gt + (size_t)r * ldg + c);
;     float o[8];
;     o[0] = bflo(g[0]) * v0[0]; o[1] = bfhi(g[0]) * v0[1]; o[2] = bflo(g[1]) * v0[2]; o[3] = bfhi(g[1]) * v0[3];
;     o[4] = bflo(g[2]) * v1[0]; o[5] = bfhi(g[2]) * v1[1]; o[6] = bflo(g[3]) * v1[2]; o[7] = bfhi(g[3]) * v1[3];
;     bf16_t* py = Y + (size_t)r * ldy + c;
;     if (ADD) {
;       const u32x4 y0 = *(const u32x4*)py;
; #pragma unroll
;       for (int j = 0; j < 4; ++j) { o[2 * j] += bflo(y0[j]); o[2 * j + 1] += bfhi(y0[j]); }
;     }
;     u32x4 pk;
; #pragma unroll
;     for (int j = 0; j < 4; ++j) pk[j] = cvt_pk_bf16(o[2 * j], o[2 * j + 1]);
;     *(u32x4*)py = pk;
	v_lshl_add_u64 v[50:51], v[50:51], 0, v[0:1]
	s_nop 1
	v_mov_b32_e32 v52, v208
	v_mov_b32_e32 v53, v209
	v_mov_b32_e32 v54, v210
	v_mov_b32_e32 v55, v211
	v_lshlrev_b32_e32 v58, 16, v52
	v_and_b32_e32 v59, 0xffff0000, v52
	v_lshlrev_b32_e32 v52, 16, v53
	v_and_b32_e32 v53, 0xffff0000, v53
	v_pk_mul_f32 v[48:49], v[48:49], v[52:53]
	v_lshlrev_b32_e32 v52, 16, v54
	v_and_b32_e32 v53, 0xffff0000, v54
	v_pk_mul_f32 v[46:47], v[46:47], v[58:59]
	v_pk_mul_f32 v[52:53], v[42:43], v[52:53]
	v_lshlrev_b32_e32 v42, 16, v55
	v_and_b32_e32 v43, 0xffff0000, v55
	v_pk_mul_f32 v[54:55], v[44:45], v[42:43]
	v_cvt_pk_bf16_f32 v42, v46, v47
	v_lshlrev_b64 v[46:47], 11, v[56:57]
	v_lshl_add_u64 v[46:47], s[4:5], 0, v[46:47]
	v_cvt_pk_bf16_f32 v43, v48, v49
	v_cvt_pk_bf16_f32 v44, v52, v53
	v_cvt_pk_bf16_f32 v45, v54, v55
	v_lshl_add_u64 v[46:47], v[46:47], 0, v[0:1]
	global_store_dwordx4 v[46:47], v[42:45], off
	s_nop 1
	v_mov_b32_e32 v42, v212
	v_mov_b32_e32 v43, v213
	v_mov_b32_e32 v44, v214
	v_mov_b32_e32 v45, v215
	v_lshlrev_b32_e32 v48, 16, v42
	v_and_b32_e32 v49, 0xffff0000, v42
	v_lshlrev_b32_e32 v42, 16, v43
	v_and_b32_e32 v43, 0xffff0000, v43
	v_pk_mul_f32 v[40:41], v[40:41], v[42:43]
	v_lshlrev_b32_e32 v42, 16, v44
	v_and_b32_e32 v43, 0xffff0000, v44
	v_pk_mul_f32 v[42:43], v[34:35], v[42:43]
	v_lshlrev_b32_e32 v34, 16, v45
	v_and_b32_e32 v35, 0xffff0000, v45
	v_pk_mul_f32 v[38:39], v[38:39], v[48:49]
	v_pk_mul_f32 v[44:45], v[36:37], v[34:35]
	v_cvt_pk_bf16_f32 v35, v40, v41
	v_add_u32_e32 v40, 0xa0, v130
	v_cvt_pk_bf16_f32 v34, v38, v39
	v_cvt_pk_bf16_f32 v36, v42, v43
	v_cvt_pk_bf16_f32 v37, v44, v45
	v_ashrrev_i32_e32 v41, 31, v40
	global_store_dwordx4 v[46:47], v[34:37], off offset:256
	s_nop 1
	v_lshlrev_b64 v[34:35], 12, v[40:41]
	v_lshl_add_u64 v[34:35], s[26:27], 0, v[34:35]
	v_lshl_add_u64 v[34:35], v[34:35], 0, v[0:1]
	global_load_dwordx4 v[36:39], v[34:35], off
	v_add_co_u32_e32 v178, vcc, 0x10000, v34
	s_nop 1
	v_addc_co_u32_e32 v179, vcc, 0, v35, vcc
	global_load_dwordx4 v[204:207], v[34:35], off offset:256
	global_load_dwordx4 v[208:211], v[178:179], off
	global_load_dwordx4 v[212:215], v[178:179], off offset:256
	s_waitcnt vmcnt(0)
	v_lshlrev_b32_e32 v42, 16, v36
	v_and_b32_e32 v43, 0xffff0000, v36
	v_lshlrev_b32_e32 v36, 16, v37
	v_and_b32_e32 v37, 0xffff0000, v37
	v_pk_mul_f32 v[32:33], v[32:33], v[36:37]
	v_lshlrev_b32_e32 v36, 16, v38
	v_and_b32_e32 v37, 0xffff0000, v38
	v_pk_mul_f32 v[30:31], v[30:31], v[42:43]
	v_pk_mul_f32 v[36:37], v[26:27], v[36:37]
	v_lshlrev_b32_e32 v26, 16, v39
	v_and_b32_e32 v27, 0xffff0000, v39
	v_pk_mul_f32 v[38:39], v[28:29], v[26:27]
	v_cvt_pk_bf16_f32 v26, v30, v31
	v_lshlrev_b64 v[30:31], 11, v[40:41]
	v_lshl_add_u64 v[30:31], s[4:5], 0, v[30:31]
	v_cvt_pk_bf16_f32 v27, v32, v33
	v_cvt_pk_bf16_f32 v28, v36, v37
	v_cvt_pk_bf16_f32 v29, v38, v39
	v_lshl_add_u64 v[30:31], v[30:31], 0, v[0:1]
	global_store_dwordx4 v[30:31], v[26:29], off
	s_nop 1
	v_mov_b32_e32 v26, v204
	v_mov_b32_e32 v27, v205
	v_mov_b32_e32 v28, v206
	v_mov_b32_e32 v29, v207
	v_lshlrev_b32_e32 v32, 16, v26
	v_and_b32_e32 v33, 0xffff0000, v26
	v_lshlrev_b32_e32 v26, 16, v27
	v_and_b32_e32 v27, 0xffff0000, v27
	v_pk_mul_f32 v[24:25], v[24:25], v[26:27]
	v_lshlrev_b32_e32 v26, 16, v28
	v_and_b32_e32 v27, 0xffff0000, v28
	v_pk_mul_f32 v[26:27], v[18:19], v[26:27]
	v_lshlrev_b32_e32 v18, 16, v29
	v_and_b32_e32 v19, 0xffff0000, v29
	v_pk_mul_f32 v[22:23], v[22:23], v[32:33]
	v_pk_mul_f32 v[28:29], v[20:21], v[18:19]
	v_cvt_pk_bf16_f32 v19, v24, v25
	v_add_u32_e32 v24, 0xb0, v130
	v_cvt_pk_bf16_f32 v18, v22, v23
	v_cvt_pk_bf16_f32 v20, v26, v27
	v_cvt_pk_bf16_f32 v21, v28, v29
	v_ashrrev_i32_e32 v25, 31, v24
	global_store_dwordx4 v[30:31], v[18:21], off offset:256
	s_nop 1
	v_lshlrev_b64 v[18:19], 12, v[24:25]
	v_lshl_add_u64 v[18:19], s[26:27], 0, v[18:19]
	v_lshl_add_u64 v[18:19], v[18:19], 0, v[0:1]
	s_nop 1
	v_mov_b32_e32 v20, v208
	v_mov_b32_e32 v21, v209
	v_mov_b32_e32 v22, v210
	v_mov_b32_e32 v23, v211
	v_lshlrev_b32_e32 v26, 16, v20
	v_and_b32_e32 v27, 0xffff0000, v20
	v_lshlrev_b32_e32 v20, 16, v21
	v_and_b32_e32 v21, 0xffff0000, v21
	v_pk_mul_f32 v[16:17], v[16:17], v[20:21]
	v_lshlrev_b32_e32 v20, 16, v22
	v_and_b32_e32 v21, 0xffff0000, v22
	v_pk_mul_f32 v[14:15], v[14:15], v[26:27]
	v_pk_mul_f32 v[10:11], v[10:11], v[20:21]
	v_lshlrev_b32_e32 v20, 16, v23
	v_and_b32_e32 v21, 0xffff0000, v23
	v_pk_mul_f32 v[20:21], v[12:13], v[20:21]
	v_cvt_pk_bf16_f32 v12, v14, v15
	v_cvt_pk_bf16_f32 v14, v10, v11
	v_lshlrev_b64 v[10:11], 11, v[24:25]
	v_lshl_add_u64 v[10:11], s[4:5], 0, v[10:11]
	v_cvt_pk_bf16_f32 v13, v16, v17
	v_cvt_pk_bf16_f32 v15, v20, v21
	v_lshl_add_u64 v[10:11], v[10:11], 0, v[0:1]
	global_store_dwordx4 v[10:11], v[12:15], off
	s_nop 1
	v_mov_b32_e32 v12, v212
	v_mov_b32_e32 v13, v213
	v_mov_b32_e32 v14, v214
	v_mov_b32_e32 v15, v215
	v_lshlrev_b32_e32 v16, 16, v12
	v_and_b32_e32 v17, 0xffff0000, v12
	v_lshlrev_b32_e32 v12, 16, v13
	v_and_b32_e32 v13, 0xffff0000, v13
	v_pk_mul_f32 v[8:9], v[8:9], v[12:13]
	v_lshlrev_b32_e32 v12, 16, v14
	v_and_b32_e32 v13, 0xffff0000, v14
	v_pk_mul_f32 v[12:13], v[2:3], v[12:13]
	v_lshlrev_b32_e32 v2, 16, v15
	v_and_b32_e32 v3, 0xffff0000, v15
	v_pk_mul_f32 v[6:7], v[6:7], v[16:17]
	v_pk_mul_f32 v[14:15], v[4:5], v[2:3]
	v_cvt_pk_bf16_f32 v2, v6, v7
	v_cvt_pk_bf16_f32 v3, v8, v9
	v_cvt_pk_bf16_f32 v4, v12, v13
	v_cvt_pk_bf16_f32 v5, v14, v15
	global_store_dwordx4 v[10:11], v[2:5], off offset:256
	s_branch .LBB0_1280

; __global__ void __launch_bounds__(512, 2) fwd_megakernel(Params p) {
	.amdhsa_kernel _Z14fwd_megakernel6Params
		.amdhsa_group_segment_fixed_size 0
		.amdhsa_private_segment_fixed_size 0
		.amdhsa_kernarg_size 456
		.amdhsa_user_sgpr_count 2
		.amdhsa_user_sgpr_dispatch_ptr 0
		.amdhsa_user_sgpr_queue_ptr 0
		.amdhsa_user_sgpr_kernarg_segment_ptr 1
		.amdhsa_user_sgpr_dispatch_id 0
		.amdhsa_user_sgpr_kernarg_preload_length 0
		.amdhsa_user_sgpr_kernarg_preload_offset 0
		.amdhsa_user_sgpr_private_segment_size 0
		.amdhsa_uses_dynamic_stack 0
		.amdhsa_enable_private_segment 0
		.amdhsa_system_sgpr_workgroup_id_x 1
		.amdhsa_system_sgpr_workgroup_id_y 0
		.amdhsa_system_sgpr_workgroup_id_z 0
		.amdhsa_system_sgpr_workgroup_info 0
		.amdhsa_system_vgpr_workitem_id 2
		.amdhsa_next_free_vgpr 255
		.amdhsa_next_free_sgpr 102
		.amdhsa_accum_offset 256
		.amdhsa_reserve_vcc 1
		.amdhsa_float_round_mode_32 0
		.amdhsa_float_round_mode_16_64 0
		.amdhsa_float_denorm_mode_32 3
		.amdhsa_float_denorm_mode_16_64 3
		.amdhsa_dx10_clamp 1
		.amdhsa_ieee_mode 1
		.amdhsa_fp16_overflow 0
		.amdhsa_tg_split 0
		.amdhsa_exception_fp_ieee_invalid_op 0
		.amdhsa_exception_fp_denorm_src 0
		.amdhsa_exception_fp_ieee_div_zero 0
		.amdhsa_exception_fp_ieee_overflow 0
		.amdhsa_exception_fp_ieee_underflow 0
		.amdhsa_exception_fp_ieee_inexact 0
		.amdhsa_exception_int_div_zero 0
	.end_amdhsa_kernel

; __global__ void __launch_bounds__(512, 2) fwd_megakernel(Params p) {
amdhsa.kernels:
  - .agpr_count:     0
    .args:
      - .offset:         0
        .size:           200
        .value_kind:     by_value
      - .offset:         200
        .size:           4
        .value_kind:     hidden_block_count_x
      - .offset:         204
        .size:           4
        .value_kind:     hidden_block_count_y
      - .offset:         208
        .size:           4
        .value_kind:     hidden_block_count_z
      - .offset:         212
        .size:           2
        .value_kind:     hidden_group_size_x
      - .offset:         214
        .size:           2
        .value_kind:     hidden_group_size_y
      - .offset:         216
        .size:           2
        .value_kind:     hidden_group_size_z
      - .offset:         218
        .size:           2
        .value_kind:     hidden_remainder_x
      - .offset:         220
        .size:           2
        .value_kind:     hidden_remainder_y
      - .offset:         222
        .size:           2
        .value_kind:     hidden_remainder_z
      - .offset:         240
        .size:           8
        .value_kind:     hidden_global_offset_x
      - .offset:         248
        .size:           8
        .value_kind:     hidden_global_offset_y
      - .offset:         256
        .size:           8
        .value_kind:     hidden_global_offset_z
      - .offset:         264
        .size:           2
        .value_kind:     hidden_grid_dims
      - .offset:         288
        .size:           8
        .value_kind:     hidden_multigrid_sync_arg
      - .offset:         320
        .size:           4
        .value_kind:     hidden_dynamic_lds_size
    .group_segment_fixed_size: 0
    .kernarg_segment_align: 8
    .kernarg_segment_size: 456
    .language:       OpenCL C
    .language_version:
      - 2
      - 0
    .max_flat_workgroup_size: 512
    .name:           _Z14fwd_megakernel6Params
    .private_segment_fixed_size: 0
    .sgpr_count:     108
    .sgpr_spill_count: 447
    .symbol:         _Z14fwd_megakernel6Params.kd
    .uniform_work_group_size: 1
    .uses_dynamic_stack: false
    .vgpr_count:     255
    .vgpr_spill_count: 0
    .wavefront_size: 64
